# GATES epilogue rewritten by hand: packed f32 mul/add/fma + SDWA byte-insert packing (on top of Z,T,L)
# speedup vs baseline: 1.0098x; 1.0098x over previous
; __device__ __forceinline__ float sigmoidf_(float z) { return __builtin_amdgcn_rcpf(1.0f + __builtin_amdgcn_exp2f(-1.4426950408889634f * z)); }
;     __device__ __forceinline__ void load(Pre& p, const pg8::Unit& u, int ai, int m, int wr, int wc, int fr, int fq) const {
;         const int row = u.pm * 256 + ai * 128 + wr * 64 + m * 16 + fr;
;         if (MODE == EM_PROJ || MODE == EM_GATES) p.rs = ((const float*)(ws + WS_RINV0))[row];
;     __device__ __forceinline__ float compute(const Pre& p, f32x4 (&acc)[2][2][4][2], const f32x4 (&cv)[2][2], const pg8::Unit& u, int ai, int m, int wr, int wc, int fr, int fq) const {
;     ...
;                 const int col = u.pn * 256 + ct; float w[8];
; #pragma unroll
;                 for (int j = 0; j < 8; ++j) w[j] = sigmoidf_(v[j] * rs) * 255.0f + 0.5f;
;                 u32x2 cd; cd.x = (unsigned)w[0] | ((unsigned)w[1] << 8) | ((unsigned)w[2] << 16) | ((unsigned)w[3] << 24); cd.y = (unsigned)w[4] | ((unsigned)w[5] << 8) | ((unsigned)w[6] << 16) | ((unsigned)w[7] << 24);
;                 *(u32x2*)(ws + WS_G8 + (size_t)row * 2048 + col) = cd;
.LBB0_676:
	v_lshl_add_u32 v164, s30, 8, v158
	v_ashrrev_i32_e32 v165, 31, v164
	v_lshl_add_u64 v[142:143], v[164:165], 2, s[10:11]
	global_load_dword v182, v[142:143], off
	v_or_b32_e32 v156, 16, v164
	v_or_b32_e32 v154, 32, v164
	v_or_b32_e32 v152, 48, v164
	v_add_u32_e32 v150, 0x80, v164
	v_add_u32_e32 v148, 0x90, v164
	v_add_u32_e32 v146, 0xa0, v164
	v_add_u32_e32 v144, 0xb0, v164
	v_ashrrev_i32_e32 v157, 31, v156
	v_ashrrev_i32_e32 v155, 31, v154
	v_ashrrev_i32_e32 v153, 31, v152
	v_ashrrev_i32_e32 v151, 31, v150
	v_ashrrev_i32_e32 v149, 31, v148
	v_ashrrev_i32_e32 v147, 31, v146
	v_ashrrev_i32_e32 v145, 31, v144
	v_lshlrev_b64 v[170:171], 11, v[164:165]
	v_lshl_add_u64 v[164:165], v[156:157], 2, s[10:11]
	v_lshl_add_u64 v[166:167], v[154:155], 2, s[10:11]
	v_lshl_add_u64 v[168:169], v[152:153], 2, s[10:11]
	v_lshl_add_u64 v[172:173], v[150:151], 2, s[10:11]
	v_lshl_add_u64 v[174:175], v[148:149], 2, s[10:11]
	v_lshl_add_u64 v[176:177], v[146:147], 2, s[10:11]
	v_lshl_add_u64 v[178:179], v[144:145], 2, s[10:11]
	global_load_dword v183, v[164:165], off
	global_load_dword v184, v[166:167], off
	s_nop 0
	global_load_dword v168, v[168:169], off
	s_nop 0
	global_load_dword v167, v[172:173], off
	global_load_dword v166, v[174:175], off
	global_load_dword v165, v[176:177], off
	global_load_dword v164, v[178:179], off
	v_lshl_or_b32 v142, s60, 8, v160
	v_ashrrev_i32_e32 v143, 31, v142
	v_lshl_add_u64 v[180:181], s[12:13], 0, v[170:171]
	v_lshl_add_u64 v[172:173], v[180:181], 0, v[142:143]
	v_readlane_b32 s66, v255, 7
	v_readlane_b32 s67, v255, 8
	s_mov_b32 s79, 0
	s_waitcnt vmcnt(7)
	v_mul_f32_e32 v174, 0xbfb8aa3b, v182
	v_pk_mul_f32 v[120:121], v[120:121], v[174:175] op_sel_hi:[1,0]
	v_pk_mul_f32 v[122:123], v[122:123], v[174:175] op_sel_hi:[1,0]
	v_pk_mul_f32 v[124:125], v[124:125], v[174:175] op_sel_hi:[1,0]
	v_pk_mul_f32 v[126:127], v[126:127], v[174:175] op_sel_hi:[1,0]
	v_exp_f32_e32 v120, v120
	v_exp_f32_e32 v121, v121
	v_exp_f32_e32 v122, v122
	v_exp_f32_e32 v123, v123
	v_exp_f32_e32 v124, v124
	v_exp_f32_e32 v125, v125
	v_exp_f32_e32 v126, v126
	v_exp_f32_e32 v127, v127
	v_pk_add_f32 v[120:121], v[120:121], 1.0 op_sel_hi:[1,0]
	v_pk_add_f32 v[122:123], v[122:123], 1.0 op_sel_hi:[1,0]
	v_pk_add_f32 v[124:125], v[124:125], 1.0 op_sel_hi:[1,0]
	v_pk_add_f32 v[126:127], v[126:127], 1.0 op_sel_hi:[1,0]
	v_rcp_f32_e32 v120, v120
	v_rcp_f32_e32 v121, v121
	v_rcp_f32_e32 v122, v122
	v_rcp_f32_e32 v123, v123
	v_rcp_f32_e32 v124, v124
	v_rcp_f32_e32 v125, v125
	v_rcp_f32_e32 v126, v126
	v_rcp_f32_e32 v127, v127
	v_pk_fma_f32 v[120:121], v[120:121], s[14:15], 0.5 op_sel_hi:[1,0,0]
	v_pk_fma_f32 v[122:123], v[122:123], s[14:15], 0.5 op_sel_hi:[1,0,0]
	v_pk_fma_f32 v[124:125], v[124:125], s[14:15], 0.5 op_sel_hi:[1,0,0]
	v_pk_fma_f32 v[126:127], v[126:127], s[14:15], 0.5 op_sel_hi:[1,0,0]
	v_cvt_u32_f32_e32 v194, v124
	v_cvt_u32_f32_e32 v195, v120
	v_cvt_u32_f32_sdwa v194, v125 dst_sel:BYTE_1 dst_unused:UNUSED_PRESERVE src0_sel:DWORD
	v_cvt_u32_f32_sdwa v195, v121 dst_sel:BYTE_1 dst_unused:UNUSED_PRESERVE src0_sel:DWORD
	v_cvt_u32_f32_sdwa v194, v126 dst_sel:BYTE_2 dst_unused:UNUSED_PRESERVE src0_sel:DWORD
	v_cvt_u32_f32_sdwa v195, v122 dst_sel:BYTE_2 dst_unused:UNUSED_PRESERVE src0_sel:DWORD
	v_cvt_u32_f32_sdwa v194, v127 dst_sel:BYTE_3 dst_unused:UNUSED_PRESERVE src0_sel:DWORD
	v_cvt_u32_f32_sdwa v195, v123 dst_sel:BYTE_3 dst_unused:UNUSED_PRESERVE src0_sel:DWORD
	v_pk_mul_f32 v[112:113], v[112:113], v[174:175] op_sel_hi:[1,0]
	v_pk_mul_f32 v[114:115], v[114:115], v[174:175] op_sel_hi:[1,0]
	v_pk_mul_f32 v[116:117], v[116:117], v[174:175] op_sel_hi:[1,0]
	v_pk_mul_f32 v[118:119], v[118:119], v[174:175] op_sel_hi:[1,0]
	global_store_dwordx2 v[172:173], v[194:195], off
	v_exp_f32_e32 v112, v112
	v_exp_f32_e32 v113, v113
	v_exp_f32_e32 v114, v114
	v_exp_f32_e32 v115, v115
	v_exp_f32_e32 v116, v116
	v_exp_f32_e32 v117, v117
	v_exp_f32_e32 v118, v118
	v_exp_f32_e32 v119, v119
	v_pk_add_f32 v[112:113], v[112:113], 1.0 op_sel_hi:[1,0]
	v_pk_add_f32 v[114:115], v[114:115], 1.0 op_sel_hi:[1,0]
	v_pk_add_f32 v[116:117], v[116:117], 1.0 op_sel_hi:[1,0]
	v_pk_add_f32 v[118:119], v[118:119], 1.0 op_sel_hi:[1,0]
	v_rcp_f32_e32 v112, v112
	v_rcp_f32_e32 v113, v113
	v_rcp_f32_e32 v114, v114
	v_rcp_f32_e32 v115, v115
	v_rcp_f32_e32 v116, v116
	v_rcp_f32_e32 v117, v117
	v_rcp_f32_e32 v118, v118
	v_rcp_f32_e32 v119, v119
	v_pk_fma_f32 v[112:113], v[112:113], s[14:15], 0.5 op_sel_hi:[1,0,0]
	v_pk_fma_f32 v[114:115], v[114:115], s[14:15], 0.5 op_sel_hi:[1,0,0]
	v_pk_fma_f32 v[116:117], v[116:117], s[14:15], 0.5 op_sel_hi:[1,0,0]
	v_pk_fma_f32 v[118:119], v[118:119], s[14:15], 0.5 op_sel_hi:[1,0,0]
	v_cvt_u32_f32_e32 v196, v116
	v_cvt_u32_f32_e32 v197, v112
	v_cvt_u32_f32_sdwa v196, v117 dst_sel:BYTE_1 dst_unused:UNUSED_PRESERVE src0_sel:DWORD
	v_cvt_u32_f32_sdwa v197, v113 dst_sel:BYTE_1 dst_unused:UNUSED_PRESERVE src0_sel:DWORD
	v_cvt_u32_f32_sdwa v196, v118 dst_sel:BYTE_2 dst_unused:UNUSED_PRESERVE src0_sel:DWORD
	v_cvt_u32_f32_sdwa v197, v114 dst_sel:BYTE_2 dst_unused:UNUSED_PRESERVE src0_sel:DWORD
	v_cvt_u32_f32_sdwa v196, v119 dst_sel:BYTE_3 dst_unused:UNUSED_PRESERVE src0_sel:DWORD
	v_cvt_u32_f32_sdwa v197, v115 dst_sel:BYTE_3 dst_unused:UNUSED_PRESERVE src0_sel:DWORD
	s_waitcnt vmcnt(7)
; __device__ __forceinline__ float sigmoidf_(float z) { return __builtin_amdgcn_rcpf(1.0f + __builtin_amdgcn_exp2f(-1.4426950408889634f * z)); }
;     __device__ __forceinline__ float compute(const Pre& p, f32x4 (&acc)[2][2][4][2], const f32x4 (&cv)[2][2], const pg8::Unit& u, int ai, int m, int wr, int wc, int fr, int fq) const {
;     ...
;                 const int col = u.pn * 256 + ct; float w[8];
; #pragma unroll
;                 for (int j = 0; j < 8; ++j) w[j] = sigmoidf_(v[j] * rs) * 255.0f + 0.5f;
;                 u32x2 cd; cd.x = (unsigned)w[0] | ((unsigned)w[1] << 8) | ((unsigned)w[2] << 16) | ((unsigned)w[3] << 24); cd.y = (unsigned)w[4] | ((unsigned)w[5] << 8) | ((unsigned)w[6] << 16) | ((unsigned)w[7] << 24);
;                 *(u32x2*)(ws + WS_G8 + (size_t)row * 2048 + col) = cd;
	v_mul_f32_e32 v176, 0xbfb8aa3b, v183
	s_mov_b32 s78, 0x8000
	v_lshl_add_u64 v[204:205], v[172:173], 0, s[78:79]
	v_pk_mul_f32 v[104:105], v[104:105], v[176:177] op_sel_hi:[1,0]
	v_pk_mul_f32 v[106:107], v[106:107], v[176:177] op_sel_hi:[1,0]
	v_pk_mul_f32 v[108:109], v[108:109], v[176:177] op_sel_hi:[1,0]
	v_pk_mul_f32 v[110:111], v[110:111], v[176:177] op_sel_hi:[1,0]
	global_store_dwordx2 v[172:173], v[196:197], off offset:128
	v_exp_f32_e32 v104, v104
	v_exp_f32_e32 v105, v105
	v_exp_f32_e32 v106, v106
	v_exp_f32_e32 v107, v107
	v_exp_f32_e32 v108, v108
	v_exp_f32_e32 v109, v109
	v_exp_f32_e32 v110, v110
	v_exp_f32_e32 v111, v111
	v_pk_add_f32 v[104:105], v[104:105], 1.0 op_sel_hi:[1,0]
	v_pk_add_f32 v[106:107], v[106:107], 1.0 op_sel_hi:[1,0]
	v_pk_add_f32 v[108:109], v[108:109], 1.0 op_sel_hi:[1,0]
	v_pk_add_f32 v[110:111], v[110:111], 1.0 op_sel_hi:[1,0]
	v_rcp_f32_e32 v104, v104
	v_rcp_f32_e32 v105, v105
	v_rcp_f32_e32 v106, v106
	v_rcp_f32_e32 v107, v107
	v_rcp_f32_e32 v108, v108
	v_rcp_f32_e32 v109, v109
	v_rcp_f32_e32 v110, v110
	v_rcp_f32_e32 v111, v111
	v_pk_fma_f32 v[104:105], v[104:105], s[14:15], 0.5 op_sel_hi:[1,0,0]
	v_pk_fma_f32 v[106:107], v[106:107], s[14:15], 0.5 op_sel_hi:[1,0,0]
	v_pk_fma_f32 v[108:109], v[108:109], s[14:15], 0.5 op_sel_hi:[1,0,0]
	v_pk_fma_f32 v[110:111], v[110:111], s[14:15], 0.5 op_sel_hi:[1,0,0]
	v_cvt_u32_f32_e32 v198, v108
	v_cvt_u32_f32_e32 v199, v104
	v_cvt_u32_f32_sdwa v198, v109 dst_sel:BYTE_1 dst_unused:UNUSED_PRESERVE src0_sel:DWORD
	v_cvt_u32_f32_sdwa v199, v105 dst_sel:BYTE_1 dst_unused:UNUSED_PRESERVE src0_sel:DWORD
	v_cvt_u32_f32_sdwa v198, v110 dst_sel:BYTE_2 dst_unused:UNUSED_PRESERVE src0_sel:DWORD
	v_cvt_u32_f32_sdwa v199, v106 dst_sel:BYTE_2 dst_unused:UNUSED_PRESERVE src0_sel:DWORD
	v_cvt_u32_f32_sdwa v198, v111 dst_sel:BYTE_3 dst_unused:UNUSED_PRESERVE src0_sel:DWORD
	v_cvt_u32_f32_sdwa v199, v107 dst_sel:BYTE_3 dst_unused:UNUSED_PRESERVE src0_sel:DWORD
	v_pk_mul_f32 v[96:97], v[96:97], v[176:177] op_sel_hi:[1,0]
	v_pk_mul_f32 v[98:99], v[98:99], v[176:177] op_sel_hi:[1,0]
	v_pk_mul_f32 v[100:101], v[100:101], v[176:177] op_sel_hi:[1,0]
	v_pk_mul_f32 v[102:103], v[102:103], v[176:177] op_sel_hi:[1,0]
	global_store_dwordx2 v[204:205], v[198:199], off
	v_exp_f32_e32 v96, v96
	v_exp_f32_e32 v97, v97
	v_exp_f32_e32 v98, v98
	v_exp_f32_e32 v99, v99
	v_exp_f32_e32 v100, v100
	v_exp_f32_e32 v101, v101
	v_exp_f32_e32 v102, v102
	v_exp_f32_e32 v103, v103
	v_pk_add_f32 v[96:97], v[96:97], 1.0 op_sel_hi:[1,0]
	v_pk_add_f32 v[98:99], v[98:99], 1.0 op_sel_hi:[1,0]
	v_pk_add_f32 v[100:101], v[100:101], 1.0 op_sel_hi:[1,0]
	v_pk_add_f32 v[102:103], v[102:103], 1.0 op_sel_hi:[1,0]
	v_rcp_f32_e32 v96, v96
	v_rcp_f32_e32 v97, v97
	v_rcp_f32_e32 v98, v98
	v_rcp_f32_e32 v99, v99
	v_rcp_f32_e32 v100, v100
	v_rcp_f32_e32 v101, v101
	v_rcp_f32_e32 v102, v102
	v_rcp_f32_e32 v103, v103
	v_pk_fma_f32 v[96:97], v[96:97], s[14:15], 0.5 op_sel_hi:[1,0,0]
	v_pk_fma_f32 v[98:99], v[98:99], s[14:15], 0.5 op_sel_hi:[1,0,0]
	v_pk_fma_f32 v[100:101], v[100:101], s[14:15], 0.5 op_sel_hi:[1,0,0]
	v_pk_fma_f32 v[102:103], v[102:103], s[14:15], 0.5 op_sel_hi:[1,0,0]
	v_cvt_u32_f32_e32 v200, v100
	v_cvt_u32_f32_e32 v201, v96
	v_cvt_u32_f32_sdwa v200, v101 dst_sel:BYTE_1 dst_unused:UNUSED_PRESERVE src0_sel:DWORD
	v_cvt_u32_f32_sdwa v201, v97 dst_sel:BYTE_1 dst_unused:UNUSED_PRESERVE src0_sel:DWORD
	v_cvt_u32_f32_sdwa v200, v102 dst_sel:BYTE_2 dst_unused:UNUSED_PRESERVE src0_sel:DWORD
	v_cvt_u32_f32_sdwa v201, v98 dst_sel:BYTE_2 dst_unused:UNUSED_PRESERVE src0_sel:DWORD
	v_cvt_u32_f32_sdwa v200, v103 dst_sel:BYTE_3 dst_unused:UNUSED_PRESERVE src0_sel:DWORD
	v_cvt_u32_f32_sdwa v201, v99 dst_sel:BYTE_3 dst_unused:UNUSED_PRESERVE src0_sel:DWORD
	s_waitcnt vmcnt(8)
	v_mul_f32_e32 v178, 0xbfb8aa3b, v184
	s_mov_b32 s78, 0x10000
	v_lshl_add_u64 v[202:203], v[172:173], 0, s[78:79]
	v_pk_mul_f32 v[88:89], v[88:89], v[178:179] op_sel_hi:[1,0]
	v_pk_mul_f32 v[90:91], v[90:91], v[178:179] op_sel_hi:[1,0]
	v_pk_mul_f32 v[92:93], v[92:93], v[178:179] op_sel_hi:[1,0]
	v_pk_mul_f32 v[94:95], v[94:95], v[178:179] op_sel_hi:[1,0]
	global_store_dwordx2 v[204:205], v[200:201], off offset:128
	v_exp_f32_e32 v88, v88
	v_exp_f32_e32 v89, v89
	v_exp_f32_e32 v90, v90
	v_exp_f32_e32 v91, v91
	v_exp_f32_e32 v92, v92
	v_exp_f32_e32 v93, v93
	v_exp_f32_e32 v94, v94
	v_exp_f32_e32 v95, v95
	v_pk_add_f32 v[88:89], v[88:89], 1.0 op_sel_hi:[1,0]
	v_pk_add_f32 v[90:91], v[90:91], 1.0 op_sel_hi:[1,0]
	v_pk_add_f32 v[92:93], v[92:93], 1.0 op_sel_hi:[1,0]
	v_pk_add_f32 v[94:95], v[94:95], 1.0 op_sel_hi:[1,0]
	v_rcp_f32_e32 v88, v88
	v_rcp_f32_e32 v89, v89
	v_rcp_f32_e32 v90, v90
	v_rcp_f32_e32 v91, v91
	v_rcp_f32_e32 v92, v92
	v_rcp_f32_e32 v93, v93
	v_rcp_f32_e32 v94, v94
	v_rcp_f32_e32 v95, v95
	v_pk_fma_f32 v[88:89], v[88:89], s[14:15], 0.5 op_sel_hi:[1,0,0]
	v_pk_fma_f32 v[90:91], v[90:91], s[14:15], 0.5 op_sel_hi:[1,0,0]
	v_pk_fma_f32 v[92:93], v[92:93], s[14:15], 0.5 op_sel_hi:[1,0,0]
	v_pk_fma_f32 v[94:95], v[94:95], s[14:15], 0.5 op_sel_hi:[1,0,0]
	v_cvt_u32_f32_e32 v194, v92
	v_cvt_u32_f32_e32 v195, v88
	v_cvt_u32_f32_sdwa v194, v93 dst_sel:BYTE_1 dst_unused:UNUSED_PRESERVE src0_sel:DWORD
	v_cvt_u32_f32_sdwa v195, v89 dst_sel:BYTE_1 dst_unused:UNUSED_PRESERVE src0_sel:DWORD
	v_cvt_u32_f32_sdwa v194, v94 dst_sel:BYTE_2 dst_unused:UNUSED_PRESERVE src0_sel:DWORD
	v_cvt_u32_f32_sdwa v195, v90 dst_sel:BYTE_2 dst_unused:UNUSED_PRESERVE src0_sel:DWORD
	v_cvt_u32_f32_sdwa v194, v95 dst_sel:BYTE_3 dst_unused:UNUSED_PRESERVE src0_sel:DWORD
	v_cvt_u32_f32_sdwa v195, v91 dst_sel:BYTE_3 dst_unused:UNUSED_PRESERVE src0_sel:DWORD
; __device__ __forceinline__ float sigmoidf_(float z) { return __builtin_amdgcn_rcpf(1.0f + __builtin_amdgcn_exp2f(-1.4426950408889634f * z)); }
;     __device__ __forceinline__ float compute(const Pre& p, f32x4 (&acc)[2][2][4][2], const f32x4 (&cv)[2][2], const pg8::Unit& u, int ai, int m, int wr, int wc, int fr, int fq) const {
;     ...
;                 const int col = u.pn * 256 + ct; float w[8];
; #pragma unroll
;                 for (int j = 0; j < 8; ++j) w[j] = sigmoidf_(v[j] * rs) * 255.0f + 0.5f;
;                 u32x2 cd; cd.x = (unsigned)w[0] | ((unsigned)w[1] << 8) | ((unsigned)w[2] << 16) | ((unsigned)w[3] << 24); cd.y = (unsigned)w[4] | ((unsigned)w[5] << 8) | ((unsigned)w[6] << 16) | ((unsigned)w[7] << 24);
;                 *(u32x2*)(ws + WS_G8 + (size_t)row * 2048 + col) = cd;
	v_pk_mul_f32 v[80:81], v[80:81], v[178:179] op_sel_hi:[1,0]
	v_pk_mul_f32 v[82:83], v[82:83], v[178:179] op_sel_hi:[1,0]
	v_pk_mul_f32 v[84:85], v[84:85], v[178:179] op_sel_hi:[1,0]
	v_pk_mul_f32 v[86:87], v[86:87], v[178:179] op_sel_hi:[1,0]
	global_store_dwordx2 v[202:203], v[194:195], off
	v_exp_f32_e32 v80, v80
	v_exp_f32_e32 v81, v81
	v_exp_f32_e32 v82, v82
	v_exp_f32_e32 v83, v83
	v_exp_f32_e32 v84, v84
	v_exp_f32_e32 v85, v85
	v_exp_f32_e32 v86, v86
	v_exp_f32_e32 v87, v87
	v_pk_add_f32 v[80:81], v[80:81], 1.0 op_sel_hi:[1,0]
	v_pk_add_f32 v[82:83], v[82:83], 1.0 op_sel_hi:[1,0]
	v_pk_add_f32 v[84:85], v[84:85], 1.0 op_sel_hi:[1,0]
	v_pk_add_f32 v[86:87], v[86:87], 1.0 op_sel_hi:[1,0]
	v_rcp_f32_e32 v80, v80
	v_rcp_f32_e32 v81, v81
	v_rcp_f32_e32 v82, v82
	v_rcp_f32_e32 v83, v83
	v_rcp_f32_e32 v84, v84
	v_rcp_f32_e32 v85, v85
	v_rcp_f32_e32 v86, v86
	v_rcp_f32_e32 v87, v87
	v_pk_fma_f32 v[80:81], v[80:81], s[14:15], 0.5 op_sel_hi:[1,0,0]
	v_pk_fma_f32 v[82:83], v[82:83], s[14:15], 0.5 op_sel_hi:[1,0,0]
	v_pk_fma_f32 v[84:85], v[84:85], s[14:15], 0.5 op_sel_hi:[1,0,0]
	v_pk_fma_f32 v[86:87], v[86:87], s[14:15], 0.5 op_sel_hi:[1,0,0]
	v_cvt_u32_f32_e32 v196, v84
	v_cvt_u32_f32_e32 v197, v80
	v_cvt_u32_f32_sdwa v196, v85 dst_sel:BYTE_1 dst_unused:UNUSED_PRESERVE src0_sel:DWORD
	v_cvt_u32_f32_sdwa v197, v81 dst_sel:BYTE_1 dst_unused:UNUSED_PRESERVE src0_sel:DWORD
	v_cvt_u32_f32_sdwa v196, v86 dst_sel:BYTE_2 dst_unused:UNUSED_PRESERVE src0_sel:DWORD
	v_cvt_u32_f32_sdwa v197, v82 dst_sel:BYTE_2 dst_unused:UNUSED_PRESERVE src0_sel:DWORD
	v_cvt_u32_f32_sdwa v196, v87 dst_sel:BYTE_3 dst_unused:UNUSED_PRESERVE src0_sel:DWORD
	v_cvt_u32_f32_sdwa v197, v83 dst_sel:BYTE_3 dst_unused:UNUSED_PRESERVE src0_sel:DWORD
	s_waitcnt vmcnt(9)
	v_mul_f32_e32 v180, 0xbfb8aa3b, v168
	s_mov_b32 s78, 0x18000
	v_lshl_add_u64 v[204:205], v[172:173], 0, s[78:79]
	v_pk_mul_f32 v[72:73], v[72:73], v[180:181] op_sel_hi:[1,0]
	v_pk_mul_f32 v[74:75], v[74:75], v[180:181] op_sel_hi:[1,0]
	v_pk_mul_f32 v[76:77], v[76:77], v[180:181] op_sel_hi:[1,0]
	v_pk_mul_f32 v[78:79], v[78:79], v[180:181] op_sel_hi:[1,0]
	global_store_dwordx2 v[202:203], v[196:197], off offset:128
	v_exp_f32_e32 v72, v72
	v_exp_f32_e32 v73, v73
	v_exp_f32_e32 v74, v74
	v_exp_f32_e32 v75, v75
	v_exp_f32_e32 v76, v76
	v_exp_f32_e32 v77, v77
	v_exp_f32_e32 v78, v78
	v_exp_f32_e32 v79, v79
	v_pk_add_f32 v[72:73], v[72:73], 1.0 op_sel_hi:[1,0]
	v_pk_add_f32 v[74:75], v[74:75], 1.0 op_sel_hi:[1,0]
	v_pk_add_f32 v[76:77], v[76:77], 1.0 op_sel_hi:[1,0]
	v_pk_add_f32 v[78:79], v[78:79], 1.0 op_sel_hi:[1,0]
	v_rcp_f32_e32 v72, v72
	v_rcp_f32_e32 v73, v73
	v_rcp_f32_e32 v74, v74
	v_rcp_f32_e32 v75, v75
	v_rcp_f32_e32 v76, v76
	v_rcp_f32_e32 v77, v77
	v_rcp_f32_e32 v78, v78
	v_rcp_f32_e32 v79, v79
	v_pk_fma_f32 v[72:73], v[72:73], s[14:15], 0.5 op_sel_hi:[1,0,0]
	v_pk_fma_f32 v[74:75], v[74:75], s[14:15], 0.5 op_sel_hi:[1,0,0]
	v_pk_fma_f32 v[76:77], v[76:77], s[14:15], 0.5 op_sel_hi:[1,0,0]
	v_pk_fma_f32 v[78:79], v[78:79], s[14:15], 0.5 op_sel_hi:[1,0,0]
	v_cvt_u32_f32_e32 v198, v76
	v_cvt_u32_f32_e32 v199, v72
	v_cvt_u32_f32_sdwa v198, v77 dst_sel:BYTE_1 dst_unused:UNUSED_PRESERVE src0_sel:DWORD
	v_cvt_u32_f32_sdwa v199, v73 dst_sel:BYTE_1 dst_unused:UNUSED_PRESERVE src0_sel:DWORD
	v_cvt_u32_f32_sdwa v198, v78 dst_sel:BYTE_2 dst_unused:UNUSED_PRESERVE src0_sel:DWORD
	v_cvt_u32_f32_sdwa v199, v74 dst_sel:BYTE_2 dst_unused:UNUSED_PRESERVE src0_sel:DWORD
	v_cvt_u32_f32_sdwa v198, v79 dst_sel:BYTE_3 dst_unused:UNUSED_PRESERVE src0_sel:DWORD
	v_cvt_u32_f32_sdwa v199, v75 dst_sel:BYTE_3 dst_unused:UNUSED_PRESERVE src0_sel:DWORD
	v_pk_mul_f32 v[64:65], v[64:65], v[180:181] op_sel_hi:[1,0]
	v_pk_mul_f32 v[66:67], v[66:67], v[180:181] op_sel_hi:[1,0]
	v_pk_mul_f32 v[68:69], v[68:69], v[180:181] op_sel_hi:[1,0]
	v_pk_mul_f32 v[70:71], v[70:71], v[180:181] op_sel_hi:[1,0]
	global_store_dwordx2 v[204:205], v[198:199], off
	v_exp_f32_e32 v64, v64
	v_exp_f32_e32 v65, v65
	v_exp_f32_e32 v66, v66
	v_exp_f32_e32 v67, v67
	v_exp_f32_e32 v68, v68
	v_exp_f32_e32 v69, v69
	v_exp_f32_e32 v70, v70
	v_exp_f32_e32 v71, v71
	v_pk_add_f32 v[64:65], v[64:65], 1.0 op_sel_hi:[1,0]
	v_pk_add_f32 v[66:67], v[66:67], 1.0 op_sel_hi:[1,0]
	v_pk_add_f32 v[68:69], v[68:69], 1.0 op_sel_hi:[1,0]
	v_pk_add_f32 v[70:71], v[70:71], 1.0 op_sel_hi:[1,0]
	v_rcp_f32_e32 v64, v64
	v_rcp_f32_e32 v65, v65
	v_rcp_f32_e32 v66, v66
	v_rcp_f32_e32 v67, v67
	v_rcp_f32_e32 v68, v68
	v_rcp_f32_e32 v69, v69
	v_rcp_f32_e32 v70, v70
	v_rcp_f32_e32 v71, v71
	v_pk_fma_f32 v[64:65], v[64:65], s[14:15], 0.5 op_sel_hi:[1,0,0]
	v_pk_fma_f32 v[66:67], v[66:67], s[14:15], 0.5 op_sel_hi:[1,0,0]
	v_pk_fma_f32 v[68:69], v[68:69], s[14:15], 0.5 op_sel_hi:[1,0,0]
	v_pk_fma_f32 v[70:71], v[70:71], s[14:15], 0.5 op_sel_hi:[1,0,0]
	v_cvt_u32_f32_e32 v200, v68
	v_cvt_u32_f32_e32 v201, v64
	v_cvt_u32_f32_sdwa v200, v69 dst_sel:BYTE_1 dst_unused:UNUSED_PRESERVE src0_sel:DWORD
	v_cvt_u32_f32_sdwa v201, v65 dst_sel:BYTE_1 dst_unused:UNUSED_PRESERVE src0_sel:DWORD
	v_cvt_u32_f32_sdwa v200, v70 dst_sel:BYTE_2 dst_unused:UNUSED_PRESERVE src0_sel:DWORD
	v_cvt_u32_f32_sdwa v201, v66 dst_sel:BYTE_2 dst_unused:UNUSED_PRESERVE src0_sel:DWORD
	v_cvt_u32_f32_sdwa v200, v71 dst_sel:BYTE_3 dst_unused:UNUSED_PRESERVE src0_sel:DWORD
	v_cvt_u32_f32_sdwa v201, v67 dst_sel:BYTE_3 dst_unused:UNUSED_PRESERVE src0_sel:DWORD
	s_waitcnt vmcnt(10)
; __device__ __forceinline__ float sigmoidf_(float z) { return __builtin_amdgcn_rcpf(1.0f + __builtin_amdgcn_exp2f(-1.4426950408889634f * z)); }
;     __device__ __forceinline__ float compute(const Pre& p, f32x4 (&acc)[2][2][4][2], const f32x4 (&cv)[2][2], const pg8::Unit& u, int ai, int m, int wr, int wc, int fr, int fq) const {
;     ...
;                 const int col = u.pn * 256 + ct; float w[8];
; #pragma unroll
;                 for (int j = 0; j < 8; ++j) w[j] = sigmoidf_(v[j] * rs) * 255.0f + 0.5f;
;                 u32x2 cd; cd.x = (unsigned)w[0] | ((unsigned)w[1] << 8) | ((unsigned)w[2] << 16) | ((unsigned)w[3] << 24); cd.y = (unsigned)w[4] | ((unsigned)w[5] << 8) | ((unsigned)w[6] << 16) | ((unsigned)w[7] << 24);
;                 *(u32x2*)(ws + WS_G8 + (size_t)row * 2048 + col) = cd;
	v_mul_f32_e32 v186, 0xbfb8aa3b, v167
	s_mov_b32 s78, 0x40000
	v_lshl_add_u64 v[202:203], v[172:173], 0, s[78:79]
	v_pk_mul_f32 v[56:57], v[56:57], v[186:187] op_sel_hi:[1,0]
	v_pk_mul_f32 v[58:59], v[58:59], v[186:187] op_sel_hi:[1,0]
	v_pk_mul_f32 v[60:61], v[60:61], v[186:187] op_sel_hi:[1,0]
	v_pk_mul_f32 v[62:63], v[62:63], v[186:187] op_sel_hi:[1,0]
	global_store_dwordx2 v[204:205], v[200:201], off offset:128
	v_exp_f32_e32 v56, v56
	v_exp_f32_e32 v57, v57
	v_exp_f32_e32 v58, v58
	v_exp_f32_e32 v59, v59
	v_exp_f32_e32 v60, v60
	v_exp_f32_e32 v61, v61
	v_exp_f32_e32 v62, v62
	v_exp_f32_e32 v63, v63
	v_pk_add_f32 v[56:57], v[56:57], 1.0 op_sel_hi:[1,0]
	v_pk_add_f32 v[58:59], v[58:59], 1.0 op_sel_hi:[1,0]
	v_pk_add_f32 v[60:61], v[60:61], 1.0 op_sel_hi:[1,0]
	v_pk_add_f32 v[62:63], v[62:63], 1.0 op_sel_hi:[1,0]
	v_rcp_f32_e32 v56, v56
	v_rcp_f32_e32 v57, v57
	v_rcp_f32_e32 v58, v58
	v_rcp_f32_e32 v59, v59
	v_rcp_f32_e32 v60, v60
	v_rcp_f32_e32 v61, v61
	v_rcp_f32_e32 v62, v62
	v_rcp_f32_e32 v63, v63
	v_pk_fma_f32 v[56:57], v[56:57], s[14:15], 0.5 op_sel_hi:[1,0,0]
	v_pk_fma_f32 v[58:59], v[58:59], s[14:15], 0.5 op_sel_hi:[1,0,0]
	v_pk_fma_f32 v[60:61], v[60:61], s[14:15], 0.5 op_sel_hi:[1,0,0]
	v_pk_fma_f32 v[62:63], v[62:63], s[14:15], 0.5 op_sel_hi:[1,0,0]
	v_cvt_u32_f32_e32 v194, v60
	v_cvt_u32_f32_e32 v195, v56
	v_cvt_u32_f32_sdwa v194, v61 dst_sel:BYTE_1 dst_unused:UNUSED_PRESERVE src0_sel:DWORD
	v_cvt_u32_f32_sdwa v195, v57 dst_sel:BYTE_1 dst_unused:UNUSED_PRESERVE src0_sel:DWORD
	v_cvt_u32_f32_sdwa v194, v62 dst_sel:BYTE_2 dst_unused:UNUSED_PRESERVE src0_sel:DWORD
	v_cvt_u32_f32_sdwa v195, v58 dst_sel:BYTE_2 dst_unused:UNUSED_PRESERVE src0_sel:DWORD
	v_cvt_u32_f32_sdwa v194, v63 dst_sel:BYTE_3 dst_unused:UNUSED_PRESERVE src0_sel:DWORD
	v_cvt_u32_f32_sdwa v195, v59 dst_sel:BYTE_3 dst_unused:UNUSED_PRESERVE src0_sel:DWORD
	v_pk_mul_f32 v[48:49], v[48:49], v[186:187] op_sel_hi:[1,0]
	v_pk_mul_f32 v[50:51], v[50:51], v[186:187] op_sel_hi:[1,0]
	v_pk_mul_f32 v[52:53], v[52:53], v[186:187] op_sel_hi:[1,0]
	v_pk_mul_f32 v[54:55], v[54:55], v[186:187] op_sel_hi:[1,0]
	global_store_dwordx2 v[202:203], v[194:195], off
	v_exp_f32_e32 v48, v48
	v_exp_f32_e32 v49, v49
	v_exp_f32_e32 v50, v50
	v_exp_f32_e32 v51, v51
	v_exp_f32_e32 v52, v52
	v_exp_f32_e32 v53, v53
	v_exp_f32_e32 v54, v54
	v_exp_f32_e32 v55, v55
	v_pk_add_f32 v[48:49], v[48:49], 1.0 op_sel_hi:[1,0]
	v_pk_add_f32 v[50:51], v[50:51], 1.0 op_sel_hi:[1,0]
	v_pk_add_f32 v[52:53], v[52:53], 1.0 op_sel_hi:[1,0]
	v_pk_add_f32 v[54:55], v[54:55], 1.0 op_sel_hi:[1,0]
	v_rcp_f32_e32 v48, v48
	v_rcp_f32_e32 v49, v49
	v_rcp_f32_e32 v50, v50
	v_rcp_f32_e32 v51, v51
	v_rcp_f32_e32 v52, v52
	v_rcp_f32_e32 v53, v53
	v_rcp_f32_e32 v54, v54
	v_rcp_f32_e32 v55, v55
	v_pk_fma_f32 v[48:49], v[48:49], s[14:15], 0.5 op_sel_hi:[1,0,0]
	v_pk_fma_f32 v[50:51], v[50:51], s[14:15], 0.5 op_sel_hi:[1,0,0]
	v_pk_fma_f32 v[52:53], v[52:53], s[14:15], 0.5 op_sel_hi:[1,0,0]
	v_pk_fma_f32 v[54:55], v[54:55], s[14:15], 0.5 op_sel_hi:[1,0,0]
	v_cvt_u32_f32_e32 v196, v52
	v_cvt_u32_f32_e32 v197, v48
	v_cvt_u32_f32_sdwa v196, v53 dst_sel:BYTE_1 dst_unused:UNUSED_PRESERVE src0_sel:DWORD
	v_cvt_u32_f32_sdwa v197, v49 dst_sel:BYTE_1 dst_unused:UNUSED_PRESERVE src0_sel:DWORD
	v_cvt_u32_f32_sdwa v196, v54 dst_sel:BYTE_2 dst_unused:UNUSED_PRESERVE src0_sel:DWORD
	v_cvt_u32_f32_sdwa v197, v50 dst_sel:BYTE_2 dst_unused:UNUSED_PRESERVE src0_sel:DWORD
	v_cvt_u32_f32_sdwa v196, v55 dst_sel:BYTE_3 dst_unused:UNUSED_PRESERVE src0_sel:DWORD
	v_cvt_u32_f32_sdwa v197, v51 dst_sel:BYTE_3 dst_unused:UNUSED_PRESERVE src0_sel:DWORD
	s_waitcnt vmcnt(11)
	v_mul_f32_e32 v188, 0xbfb8aa3b, v166
	s_mov_b32 s78, 0x48000
	v_lshl_add_u64 v[204:205], v[172:173], 0, s[78:79]
	v_pk_mul_f32 v[40:41], v[40:41], v[188:189] op_sel_hi:[1,0]
	v_pk_mul_f32 v[42:43], v[42:43], v[188:189] op_sel_hi:[1,0]
	v_pk_mul_f32 v[44:45], v[44:45], v[188:189] op_sel_hi:[1,0]
	v_pk_mul_f32 v[46:47], v[46:47], v[188:189] op_sel_hi:[1,0]
	global_store_dwordx2 v[202:203], v[196:197], off offset:128
	v_exp_f32_e32 v40, v40
	v_exp_f32_e32 v41, v41
	v_exp_f32_e32 v42, v42
	v_exp_f32_e32 v43, v43
	v_exp_f32_e32 v44, v44
	v_exp_f32_e32 v45, v45
	v_exp_f32_e32 v46, v46
	v_exp_f32_e32 v47, v47
	v_pk_add_f32 v[40:41], v[40:41], 1.0 op_sel_hi:[1,0]
	v_pk_add_f32 v[42:43], v[42:43], 1.0 op_sel_hi:[1,0]
	v_pk_add_f32 v[44:45], v[44:45], 1.0 op_sel_hi:[1,0]
	v_pk_add_f32 v[46:47], v[46:47], 1.0 op_sel_hi:[1,0]
	v_rcp_f32_e32 v40, v40
	v_rcp_f32_e32 v41, v41
	v_rcp_f32_e32 v42, v42
	v_rcp_f32_e32 v43, v43
	v_rcp_f32_e32 v44, v44
	v_rcp_f32_e32 v45, v45
	v_rcp_f32_e32 v46, v46
	v_rcp_f32_e32 v47, v47
	v_pk_fma_f32 v[40:41], v[40:41], s[14:15], 0.5 op_sel_hi:[1,0,0]
	v_pk_fma_f32 v[42:43], v[42:43], s[14:15], 0.5 op_sel_hi:[1,0,0]
	v_pk_fma_f32 v[44:45], v[44:45], s[14:15], 0.5 op_sel_hi:[1,0,0]
	v_pk_fma_f32 v[46:47], v[46:47], s[14:15], 0.5 op_sel_hi:[1,0,0]
	v_cvt_u32_f32_e32 v198, v44
	v_cvt_u32_f32_e32 v199, v40
	v_cvt_u32_f32_sdwa v198, v45 dst_sel:BYTE_1 dst_unused:UNUSED_PRESERVE src0_sel:DWORD
	v_cvt_u32_f32_sdwa v199, v41 dst_sel:BYTE_1 dst_unused:UNUSED_PRESERVE src0_sel:DWORD
	v_cvt_u32_f32_sdwa v198, v46 dst_sel:BYTE_2 dst_unused:UNUSED_PRESERVE src0_sel:DWORD
	v_cvt_u32_f32_sdwa v199, v42 dst_sel:BYTE_2 dst_unused:UNUSED_PRESERVE src0_sel:DWORD
	v_cvt_u32_f32_sdwa v198, v47 dst_sel:BYTE_3 dst_unused:UNUSED_PRESERVE src0_sel:DWORD
	v_cvt_u32_f32_sdwa v199, v43 dst_sel:BYTE_3 dst_unused:UNUSED_PRESERVE src0_sel:DWORD
	v_pk_mul_f32 v[32:33], v[32:33], v[188:189] op_sel_hi:[1,0]
	v_pk_mul_f32 v[34:35], v[34:35], v[188:189] op_sel_hi:[1,0]
	v_pk_mul_f32 v[36:37], v[36:37], v[188:189] op_sel_hi:[1,0]
; __device__ __forceinline__ float sigmoidf_(float z) { return __builtin_amdgcn_rcpf(1.0f + __builtin_amdgcn_exp2f(-1.4426950408889634f * z)); }
;     __device__ __forceinline__ float compute(const Pre& p, f32x4 (&acc)[2][2][4][2], const f32x4 (&cv)[2][2], const pg8::Unit& u, int ai, int m, int wr, int wc, int fr, int fq) const {
;     ...
;                 const int col = u.pn * 256 + ct; float w[8];
; #pragma unroll
;                 for (int j = 0; j < 8; ++j) w[j] = sigmoidf_(v[j] * rs) * 255.0f + 0.5f;
;                 u32x2 cd; cd.x = (unsigned)w[0] | ((unsigned)w[1] << 8) | ((unsigned)w[2] << 16) | ((unsigned)w[3] << 24); cd.y = (unsigned)w[4] | ((unsigned)w[5] << 8) | ((unsigned)w[6] << 16) | ((unsigned)w[7] << 24);
;                 *(u32x2*)(ws + WS_G8 + (size_t)row * 2048 + col) = cd;
	v_pk_mul_f32 v[38:39], v[38:39], v[188:189] op_sel_hi:[1,0]
	global_store_dwordx2 v[204:205], v[198:199], off
	v_exp_f32_e32 v32, v32
	v_exp_f32_e32 v33, v33
	v_exp_f32_e32 v34, v34
	v_exp_f32_e32 v35, v35
	v_exp_f32_e32 v36, v36
	v_exp_f32_e32 v37, v37
	v_exp_f32_e32 v38, v38
	v_exp_f32_e32 v39, v39
	v_pk_add_f32 v[32:33], v[32:33], 1.0 op_sel_hi:[1,0]
	v_pk_add_f32 v[34:35], v[34:35], 1.0 op_sel_hi:[1,0]
	v_pk_add_f32 v[36:37], v[36:37], 1.0 op_sel_hi:[1,0]
	v_pk_add_f32 v[38:39], v[38:39], 1.0 op_sel_hi:[1,0]
	v_rcp_f32_e32 v32, v32
	v_rcp_f32_e32 v33, v33
	v_rcp_f32_e32 v34, v34
	v_rcp_f32_e32 v35, v35
	v_rcp_f32_e32 v36, v36
	v_rcp_f32_e32 v37, v37
	v_rcp_f32_e32 v38, v38
	v_rcp_f32_e32 v39, v39
	v_pk_fma_f32 v[32:33], v[32:33], s[14:15], 0.5 op_sel_hi:[1,0,0]
	v_pk_fma_f32 v[34:35], v[34:35], s[14:15], 0.5 op_sel_hi:[1,0,0]
	v_pk_fma_f32 v[36:37], v[36:37], s[14:15], 0.5 op_sel_hi:[1,0,0]
	v_pk_fma_f32 v[38:39], v[38:39], s[14:15], 0.5 op_sel_hi:[1,0,0]
	v_cvt_u32_f32_e32 v200, v36
	v_cvt_u32_f32_e32 v201, v32
	v_cvt_u32_f32_sdwa v200, v37 dst_sel:BYTE_1 dst_unused:UNUSED_PRESERVE src0_sel:DWORD
	v_cvt_u32_f32_sdwa v201, v33 dst_sel:BYTE_1 dst_unused:UNUSED_PRESERVE src0_sel:DWORD
	v_cvt_u32_f32_sdwa v200, v38 dst_sel:BYTE_2 dst_unused:UNUSED_PRESERVE src0_sel:DWORD
	v_cvt_u32_f32_sdwa v201, v34 dst_sel:BYTE_2 dst_unused:UNUSED_PRESERVE src0_sel:DWORD
	v_cvt_u32_f32_sdwa v200, v39 dst_sel:BYTE_3 dst_unused:UNUSED_PRESERVE src0_sel:DWORD
	v_cvt_u32_f32_sdwa v201, v35 dst_sel:BYTE_3 dst_unused:UNUSED_PRESERVE src0_sel:DWORD
	s_waitcnt vmcnt(12)
	v_mul_f32_e32 v190, 0xbfb8aa3b, v165
	s_mov_b32 s78, 0x50000
	v_lshl_add_u64 v[202:203], v[172:173], 0, s[78:79]
	v_pk_mul_f32 v[24:25], v[24:25], v[190:191] op_sel_hi:[1,0]
	v_pk_mul_f32 v[26:27], v[26:27], v[190:191] op_sel_hi:[1,0]
	v_pk_mul_f32 v[28:29], v[28:29], v[190:191] op_sel_hi:[1,0]
	v_pk_mul_f32 v[30:31], v[30:31], v[190:191] op_sel_hi:[1,0]
	global_store_dwordx2 v[204:205], v[200:201], off offset:128
	v_exp_f32_e32 v24, v24
	v_exp_f32_e32 v25, v25
	v_exp_f32_e32 v26, v26
	v_exp_f32_e32 v27, v27
	v_exp_f32_e32 v28, v28
	v_exp_f32_e32 v29, v29
	v_exp_f32_e32 v30, v30
	v_exp_f32_e32 v31, v31
	v_pk_add_f32 v[24:25], v[24:25], 1.0 op_sel_hi:[1,0]
	v_pk_add_f32 v[26:27], v[26:27], 1.0 op_sel_hi:[1,0]
	v_pk_add_f32 v[28:29], v[28:29], 1.0 op_sel_hi:[1,0]
	v_pk_add_f32 v[30:31], v[30:31], 1.0 op_sel_hi:[1,0]
	v_rcp_f32_e32 v24, v24
	v_rcp_f32_e32 v25, v25
	v_rcp_f32_e32 v26, v26
	v_rcp_f32_e32 v27, v27
	v_rcp_f32_e32 v28, v28
	v_rcp_f32_e32 v29, v29
	v_rcp_f32_e32 v30, v30
	v_rcp_f32_e32 v31, v31
	v_pk_fma_f32 v[24:25], v[24:25], s[14:15], 0.5 op_sel_hi:[1,0,0]
	v_pk_fma_f32 v[26:27], v[26:27], s[14:15], 0.5 op_sel_hi:[1,0,0]
	v_pk_fma_f32 v[28:29], v[28:29], s[14:15], 0.5 op_sel_hi:[1,0,0]
	v_pk_fma_f32 v[30:31], v[30:31], s[14:15], 0.5 op_sel_hi:[1,0,0]
	v_cvt_u32_f32_e32 v194, v28
	v_cvt_u32_f32_e32 v195, v24
	v_cvt_u32_f32_sdwa v194, v29 dst_sel:BYTE_1 dst_unused:UNUSED_PRESERVE src0_sel:DWORD
	v_cvt_u32_f32_sdwa v195, v25 dst_sel:BYTE_1 dst_unused:UNUSED_PRESERVE src0_sel:DWORD
	v_cvt_u32_f32_sdwa v194, v30 dst_sel:BYTE_2 dst_unused:UNUSED_PRESERVE src0_sel:DWORD
	v_cvt_u32_f32_sdwa v195, v26 dst_sel:BYTE_2 dst_unused:UNUSED_PRESERVE src0_sel:DWORD
	v_cvt_u32_f32_sdwa v194, v31 dst_sel:BYTE_3 dst_unused:UNUSED_PRESERVE src0_sel:DWORD
	v_cvt_u32_f32_sdwa v195, v27 dst_sel:BYTE_3 dst_unused:UNUSED_PRESERVE src0_sel:DWORD
	v_pk_mul_f32 v[16:17], v[16:17], v[190:191] op_sel_hi:[1,0]
	v_pk_mul_f32 v[18:19], v[18:19], v[190:191] op_sel_hi:[1,0]
	v_pk_mul_f32 v[20:21], v[20:21], v[190:191] op_sel_hi:[1,0]
	v_pk_mul_f32 v[22:23], v[22:23], v[190:191] op_sel_hi:[1,0]
	global_store_dwordx2 v[202:203], v[194:195], off
	v_exp_f32_e32 v16, v16
	v_exp_f32_e32 v17, v17
	v_exp_f32_e32 v18, v18
	v_exp_f32_e32 v19, v19
	v_exp_f32_e32 v20, v20
	v_exp_f32_e32 v21, v21
	v_exp_f32_e32 v22, v22
	v_exp_f32_e32 v23, v23
	v_pk_add_f32 v[16:17], v[16:17], 1.0 op_sel_hi:[1,0]
	v_pk_add_f32 v[18:19], v[18:19], 1.0 op_sel_hi:[1,0]
	v_pk_add_f32 v[20:21], v[20:21], 1.0 op_sel_hi:[1,0]
	v_pk_add_f32 v[22:23], v[22:23], 1.0 op_sel_hi:[1,0]
	v_rcp_f32_e32 v16, v16
	v_rcp_f32_e32 v17, v17
	v_rcp_f32_e32 v18, v18
	v_rcp_f32_e32 v19, v19
	v_rcp_f32_e32 v20, v20
	v_rcp_f32_e32 v21, v21
	v_rcp_f32_e32 v22, v22
	v_rcp_f32_e32 v23, v23
	v_pk_fma_f32 v[16:17], v[16:17], s[14:15], 0.5 op_sel_hi:[1,0,0]
	v_pk_fma_f32 v[18:19], v[18:19], s[14:15], 0.5 op_sel_hi:[1,0,0]
	v_pk_fma_f32 v[20:21], v[20:21], s[14:15], 0.5 op_sel_hi:[1,0,0]
	v_pk_fma_f32 v[22:23], v[22:23], s[14:15], 0.5 op_sel_hi:[1,0,0]
	v_cvt_u32_f32_e32 v196, v20
	v_cvt_u32_f32_e32 v197, v16
	v_cvt_u32_f32_sdwa v196, v21 dst_sel:BYTE_1 dst_unused:UNUSED_PRESERVE src0_sel:DWORD
	v_cvt_u32_f32_sdwa v197, v17 dst_sel:BYTE_1 dst_unused:UNUSED_PRESERVE src0_sel:DWORD
	v_cvt_u32_f32_sdwa v196, v22 dst_sel:BYTE_2 dst_unused:UNUSED_PRESERVE src0_sel:DWORD
	v_cvt_u32_f32_sdwa v197, v18 dst_sel:BYTE_2 dst_unused:UNUSED_PRESERVE src0_sel:DWORD
	v_cvt_u32_f32_sdwa v196, v23 dst_sel:BYTE_3 dst_unused:UNUSED_PRESERVE src0_sel:DWORD
	v_cvt_u32_f32_sdwa v197, v19 dst_sel:BYTE_3 dst_unused:UNUSED_PRESERVE src0_sel:DWORD
	s_waitcnt vmcnt(13)
; __device__ __forceinline__ float sigmoidf_(float z) { return __builtin_amdgcn_rcpf(1.0f + __builtin_amdgcn_exp2f(-1.4426950408889634f * z)); }
; #define PG8_BAR __builtin_amdgcn_s_barrier()
; template <class Epi, class Sched>
; __device__ __forceinline__ void gemm_phase(LAS unsigned char* lds, const Gemm g, const Sched& S, const Epi& E, int wave_id) {
;     ...
;         if (wr == 0) PG8_BAR;
;         E(acc, cur, wr, wc, fr, fq);
;         if (!has_next) break;
; #pragma unroll
;         for (int a = 0; a < 2; ++a)
; #pragma unroll
;             for (int b = 0; b < 2; ++b)
; #pragma unroll
;                 for (int m = 0; m < 4; ++m)
; #pragma unroll
;                     for (int n = 0; n < 2; ++n) acc[a][b][m][n] = (f32x4){0.f, 0.f, 0.f, 0.f};
;         cur = nxt; cA = nA; cB = nB; ++ui;
;         if (wr == 1) PG8_BAR;
;     __device__ __forceinline__ float compute(const Pre& p, f32x4 (&acc)[2][2][4][2], const f32x4 (&cv)[2][2], const pg8::Unit& u, int ai, int m, int wr, int wc, int fr, int fq) const {
;     ...
;             } else if (MODE == EM_GATES) {
;                 const int col = u.pn * 256 + ct; float w[8];
; #pragma unroll
;                 for (int j = 0; j < 8; ++j) w[j] = sigmoidf_(v[j] * rs) * 255.0f + 0.5f;
;                 u32x2 cd; cd.x = (unsigned)w[0] | ((unsigned)w[1] << 8) | ((unsigned)w[2] << 16) | ((unsigned)w[3] << 24); cd.y = (unsigned)w[4] | ((unsigned)w[5] << 8) | ((unsigned)w[6] << 16) | ((unsigned)w[7] << 24);
;                 *(u32x2*)(ws + WS_G8 + (size_t)row * 2048 + col) = cd;
	v_mul_f32_e32 v192, 0xbfb8aa3b, v164
	s_mov_b32 s78, 0x58000
	v_lshl_add_u64 v[204:205], v[172:173], 0, s[78:79]
	v_pk_mul_f32 v[8:9], v[8:9], v[192:193] op_sel_hi:[1,0]
	v_pk_mul_f32 v[10:11], v[10:11], v[192:193] op_sel_hi:[1,0]
	v_pk_mul_f32 v[12:13], v[12:13], v[192:193] op_sel_hi:[1,0]
	v_pk_mul_f32 v[14:15], v[14:15], v[192:193] op_sel_hi:[1,0]
	global_store_dwordx2 v[202:203], v[196:197], off offset:128
	v_exp_f32_e32 v8, v8
	v_exp_f32_e32 v9, v9
	v_exp_f32_e32 v10, v10
	v_exp_f32_e32 v11, v11
	v_exp_f32_e32 v12, v12
	v_exp_f32_e32 v13, v13
	v_exp_f32_e32 v14, v14
	v_exp_f32_e32 v15, v15
	v_pk_add_f32 v[8:9], v[8:9], 1.0 op_sel_hi:[1,0]
	v_pk_add_f32 v[10:11], v[10:11], 1.0 op_sel_hi:[1,0]
	v_pk_add_f32 v[12:13], v[12:13], 1.0 op_sel_hi:[1,0]
	v_pk_add_f32 v[14:15], v[14:15], 1.0 op_sel_hi:[1,0]
	v_rcp_f32_e32 v8, v8
	v_rcp_f32_e32 v9, v9
	v_rcp_f32_e32 v10, v10
	v_rcp_f32_e32 v11, v11
	v_rcp_f32_e32 v12, v12
	v_rcp_f32_e32 v13, v13
	v_rcp_f32_e32 v14, v14
	v_rcp_f32_e32 v15, v15
	v_pk_fma_f32 v[8:9], v[8:9], s[14:15], 0.5 op_sel_hi:[1,0,0]
	v_pk_fma_f32 v[10:11], v[10:11], s[14:15], 0.5 op_sel_hi:[1,0,0]
	v_pk_fma_f32 v[12:13], v[12:13], s[14:15], 0.5 op_sel_hi:[1,0,0]
	v_pk_fma_f32 v[14:15], v[14:15], s[14:15], 0.5 op_sel_hi:[1,0,0]
	v_cvt_u32_f32_e32 v198, v12
	v_cvt_u32_f32_e32 v199, v8
	v_cvt_u32_f32_sdwa v198, v13 dst_sel:BYTE_1 dst_unused:UNUSED_PRESERVE src0_sel:DWORD
	v_cvt_u32_f32_sdwa v199, v9 dst_sel:BYTE_1 dst_unused:UNUSED_PRESERVE src0_sel:DWORD
	v_cvt_u32_f32_sdwa v198, v14 dst_sel:BYTE_2 dst_unused:UNUSED_PRESERVE src0_sel:DWORD
	v_cvt_u32_f32_sdwa v199, v10 dst_sel:BYTE_2 dst_unused:UNUSED_PRESERVE src0_sel:DWORD
	v_cvt_u32_f32_sdwa v198, v15 dst_sel:BYTE_3 dst_unused:UNUSED_PRESERVE src0_sel:DWORD
	v_cvt_u32_f32_sdwa v199, v11 dst_sel:BYTE_3 dst_unused:UNUSED_PRESERVE src0_sel:DWORD
	v_pk_mul_f32 v[0:1], v[0:1], v[192:193] op_sel_hi:[1,0]
	v_pk_mul_f32 v[2:3], v[2:3], v[192:193] op_sel_hi:[1,0]
	v_pk_mul_f32 v[4:5], v[4:5], v[192:193] op_sel_hi:[1,0]
	v_pk_mul_f32 v[6:7], v[6:7], v[192:193] op_sel_hi:[1,0]
	global_store_dwordx2 v[204:205], v[198:199], off
	v_exp_f32_e32 v0, v0
	v_exp_f32_e32 v1, v1
	v_exp_f32_e32 v2, v2
	v_exp_f32_e32 v3, v3
	v_exp_f32_e32 v4, v4
	v_exp_f32_e32 v5, v5
	v_exp_f32_e32 v6, v6
	v_exp_f32_e32 v7, v7
	v_pk_add_f32 v[0:1], v[0:1], 1.0 op_sel_hi:[1,0]
	v_pk_add_f32 v[2:3], v[2:3], 1.0 op_sel_hi:[1,0]
	v_pk_add_f32 v[4:5], v[4:5], 1.0 op_sel_hi:[1,0]
	v_pk_add_f32 v[6:7], v[6:7], 1.0 op_sel_hi:[1,0]
	v_rcp_f32_e32 v0, v0
	v_rcp_f32_e32 v1, v1
	v_rcp_f32_e32 v2, v2
	v_rcp_f32_e32 v3, v3
	v_rcp_f32_e32 v4, v4
	v_rcp_f32_e32 v5, v5
	v_rcp_f32_e32 v6, v6
	v_rcp_f32_e32 v7, v7
	v_pk_fma_f32 v[0:1], v[0:1], s[14:15], 0.5 op_sel_hi:[1,0,0]
	v_pk_fma_f32 v[2:3], v[2:3], s[14:15], 0.5 op_sel_hi:[1,0,0]
	v_pk_fma_f32 v[4:5], v[4:5], s[14:15], 0.5 op_sel_hi:[1,0,0]
	v_pk_fma_f32 v[6:7], v[6:7], s[14:15], 0.5 op_sel_hi:[1,0,0]
	v_cvt_u32_f32_e32 v200, v4
	v_cvt_u32_f32_e32 v201, v0
	v_cvt_u32_f32_sdwa v200, v5 dst_sel:BYTE_1 dst_unused:UNUSED_PRESERVE src0_sel:DWORD
	v_cvt_u32_f32_sdwa v201, v1 dst_sel:BYTE_1 dst_unused:UNUSED_PRESERVE src0_sel:DWORD
	v_cvt_u32_f32_sdwa v200, v6 dst_sel:BYTE_2 dst_unused:UNUSED_PRESERVE src0_sel:DWORD
	v_cvt_u32_f32_sdwa v201, v2 dst_sel:BYTE_2 dst_unused:UNUSED_PRESERVE src0_sel:DWORD
	v_cvt_u32_f32_sdwa v200, v7 dst_sel:BYTE_3 dst_unused:UNUSED_PRESERVE src0_sel:DWORD
	v_cvt_u32_f32_sdwa v201, v3 dst_sel:BYTE_3 dst_unused:UNUSED_PRESERVE src0_sel:DWORD
	s_nop 0
	global_store_dwordx2 v[204:205], v[200:201], off offset:128
	s_andn2_b64 vcc, exec, s[24:25]
	s_mov_b64 s[24:25], -1
	s_cbranch_vccnz .LBB0_664
	s_andn2_b64 vcc, exec, s[4:5]
	s_cbranch_vccnz .LBB0_663
	s_barrier
	s_branch .LBB0_663

; __device__ __forceinline__ float sigmoidf_(float z) { return __builtin_amdgcn_rcpf(1.0f + __builtin_amdgcn_exp2f(-1.4426950408889634f * z)); }
;     __device__ __forceinline__ void load(Pre& p, const pg8::Unit& u, int ai, int m, int wr, int wc, int fr, int fq) const {
;         const int row = u.pm * 256 + ai * 128 + wr * 64 + m * 16 + fr;
;         if (MODE == EM_PROJ || MODE == EM_GATES) p.rs = ((const float*)(ws + WS_RINV0))[row];
;     __device__ __forceinline__ float compute(const Pre& p, f32x4 (&acc)[2][2][4][2], const f32x4 (&cv)[2][2], const pg8::Unit& u, int ai, int m, int wr, int wc, int fr, int fq) const {
;     ...
;             } else if (MODE == EM_GATES) {
;                 const int col = u.pn * 256 + ct; float w[8];
; #pragma unroll
;                 for (int j = 0; j < 8; ++j) w[j] = sigmoidf_(v[j] * rs) * 255.0f + 0.5f;
;                 u32x2 cd; cd.x = (unsigned)w[0] | ((unsigned)w[1] << 8) | ((unsigned)w[2] << 16) | ((unsigned)w[3] << 24); cd.y = (unsigned)w[4] | ((unsigned)w[5] << 8) | ((unsigned)w[6] << 16) | ((unsigned)w[7] << 24);
;                 *(u32x2*)(ws + WS_G8 + (size_t)row * 2048 + col) = cd;
.LBB0_731:
	v_lshl_add_u32 v164, s28, 8, v158
	v_ashrrev_i32_e32 v165, 31, v164
	v_lshl_add_u64 v[142:143], v[164:165], 2, s[10:11]
	global_load_dword v182, v[142:143], off
	v_or_b32_e32 v156, 16, v164
	v_or_b32_e32 v154, 32, v164
	v_or_b32_e32 v152, 48, v164
	v_add_u32_e32 v150, 0x80, v164
	v_add_u32_e32 v148, 0x90, v164
	v_add_u32_e32 v146, 0xa0, v164
	v_add_u32_e32 v144, 0xb0, v164
	v_ashrrev_i32_e32 v157, 31, v156
	v_ashrrev_i32_e32 v155, 31, v154
	v_ashrrev_i32_e32 v153, 31, v152
	v_ashrrev_i32_e32 v151, 31, v150
	v_ashrrev_i32_e32 v149, 31, v148
	v_ashrrev_i32_e32 v147, 31, v146
	v_ashrrev_i32_e32 v145, 31, v144
	v_lshlrev_b64 v[170:171], 11, v[164:165]
	v_lshl_add_u64 v[164:165], v[156:157], 2, s[10:11]
	v_lshl_add_u64 v[166:167], v[154:155], 2, s[10:11]
	v_lshl_add_u64 v[168:169], v[152:153], 2, s[10:11]
	v_lshl_add_u64 v[172:173], v[150:151], 2, s[10:11]
	v_lshl_add_u64 v[174:175], v[148:149], 2, s[10:11]
	v_lshl_add_u64 v[176:177], v[146:147], 2, s[10:11]
	v_lshl_add_u64 v[178:179], v[144:145], 2, s[10:11]
	global_load_dword v183, v[164:165], off
	global_load_dword v184, v[166:167], off
	s_nop 0
	global_load_dword v168, v[168:169], off
	s_nop 0
	global_load_dword v167, v[172:173], off
	global_load_dword v166, v[174:175], off
	global_load_dword v165, v[176:177], off
	global_load_dword v164, v[178:179], off
	v_lshl_or_b32 v142, s58, 8, v160
	v_ashrrev_i32_e32 v143, 31, v142
	v_lshl_add_u64 v[180:181], s[12:13], 0, v[170:171]
	v_lshl_add_u64 v[172:173], v[180:181], 0, v[142:143]
	v_readlane_b32 s66, v255, 7
	v_readlane_b32 s67, v255, 8
	s_mov_b32 s79, 0
	s_waitcnt vmcnt(7)
	v_mul_f32_e32 v174, 0xbfb8aa3b, v182
	v_pk_mul_f32 v[120:121], v[120:121], v[174:175] op_sel_hi:[1,0]
	v_pk_mul_f32 v[122:123], v[122:123], v[174:175] op_sel_hi:[1,0]
	v_pk_mul_f32 v[124:125], v[124:125], v[174:175] op_sel_hi:[1,0]
	v_pk_mul_f32 v[126:127], v[126:127], v[174:175] op_sel_hi:[1,0]
	v_exp_f32_e32 v120, v120
	v_exp_f32_e32 v121, v121
	v_exp_f32_e32 v122, v122
	v_exp_f32_e32 v123, v123
	v_exp_f32_e32 v124, v124
	v_exp_f32_e32 v125, v125
	v_exp_f32_e32 v126, v126
	v_exp_f32_e32 v127, v127
	v_pk_add_f32 v[120:121], v[120:121], 1.0 op_sel_hi:[1,0]
	v_pk_add_f32 v[122:123], v[122:123], 1.0 op_sel_hi:[1,0]
	v_pk_add_f32 v[124:125], v[124:125], 1.0 op_sel_hi:[1,0]
	v_pk_add_f32 v[126:127], v[126:127], 1.0 op_sel_hi:[1,0]
	v_rcp_f32_e32 v120, v120
	v_rcp_f32_e32 v121, v121
	v_rcp_f32_e32 v122, v122
	v_rcp_f32_e32 v123, v123
	v_rcp_f32_e32 v124, v124
	v_rcp_f32_e32 v125, v125
	v_rcp_f32_e32 v126, v126
	v_rcp_f32_e32 v127, v127
	v_pk_fma_f32 v[120:121], v[120:121], s[14:15], 0.5 op_sel_hi:[1,0,0]
	v_pk_fma_f32 v[122:123], v[122:123], s[14:15], 0.5 op_sel_hi:[1,0,0]
	v_pk_fma_f32 v[124:125], v[124:125], s[14:15], 0.5 op_sel_hi:[1,0,0]
	v_pk_fma_f32 v[126:127], v[126:127], s[14:15], 0.5 op_sel_hi:[1,0,0]
	v_cvt_u32_f32_e32 v194, v124
	v_cvt_u32_f32_e32 v195, v120
	v_cvt_u32_f32_sdwa v194, v125 dst_sel:BYTE_1 dst_unused:UNUSED_PRESERVE src0_sel:DWORD
	v_cvt_u32_f32_sdwa v195, v121 dst_sel:BYTE_1 dst_unused:UNUSED_PRESERVE src0_sel:DWORD
	v_cvt_u32_f32_sdwa v194, v126 dst_sel:BYTE_2 dst_unused:UNUSED_PRESERVE src0_sel:DWORD
	v_cvt_u32_f32_sdwa v195, v122 dst_sel:BYTE_2 dst_unused:UNUSED_PRESERVE src0_sel:DWORD
	v_cvt_u32_f32_sdwa v194, v127 dst_sel:BYTE_3 dst_unused:UNUSED_PRESERVE src0_sel:DWORD
	v_cvt_u32_f32_sdwa v195, v123 dst_sel:BYTE_3 dst_unused:UNUSED_PRESERVE src0_sel:DWORD
	v_pk_mul_f32 v[112:113], v[112:113], v[174:175] op_sel_hi:[1,0]
	v_pk_mul_f32 v[114:115], v[114:115], v[174:175] op_sel_hi:[1,0]
	v_pk_mul_f32 v[116:117], v[116:117], v[174:175] op_sel_hi:[1,0]
	v_pk_mul_f32 v[118:119], v[118:119], v[174:175] op_sel_hi:[1,0]
	global_store_dwordx2 v[172:173], v[194:195], off
	v_exp_f32_e32 v112, v112
	v_exp_f32_e32 v113, v113
	v_exp_f32_e32 v114, v114
	v_exp_f32_e32 v115, v115
	v_exp_f32_e32 v116, v116
	v_exp_f32_e32 v117, v117
	v_exp_f32_e32 v118, v118
	v_exp_f32_e32 v119, v119
	v_pk_add_f32 v[112:113], v[112:113], 1.0 op_sel_hi:[1,0]
	v_pk_add_f32 v[114:115], v[114:115], 1.0 op_sel_hi:[1,0]
	v_pk_add_f32 v[116:117], v[116:117], 1.0 op_sel_hi:[1,0]
	v_pk_add_f32 v[118:119], v[118:119], 1.0 op_sel_hi:[1,0]
	v_rcp_f32_e32 v112, v112
	v_rcp_f32_e32 v113, v113
	v_rcp_f32_e32 v114, v114
	v_rcp_f32_e32 v115, v115
	v_rcp_f32_e32 v116, v116
	v_rcp_f32_e32 v117, v117
	v_rcp_f32_e32 v118, v118
	v_rcp_f32_e32 v119, v119
	v_pk_fma_f32 v[112:113], v[112:113], s[14:15], 0.5 op_sel_hi:[1,0,0]
	v_pk_fma_f32 v[114:115], v[114:115], s[14:15], 0.5 op_sel_hi:[1,0,0]
	v_pk_fma_f32 v[116:117], v[116:117], s[14:15], 0.5 op_sel_hi:[1,0,0]
	v_pk_fma_f32 v[118:119], v[118:119], s[14:15], 0.5 op_sel_hi:[1,0,0]
	v_cvt_u32_f32_e32 v196, v116
	v_cvt_u32_f32_e32 v197, v112
	v_cvt_u32_f32_sdwa v196, v117 dst_sel:BYTE_1 dst_unused:UNUSED_PRESERVE src0_sel:DWORD
	v_cvt_u32_f32_sdwa v197, v113 dst_sel:BYTE_1 dst_unused:UNUSED_PRESERVE src0_sel:DWORD
	v_cvt_u32_f32_sdwa v196, v118 dst_sel:BYTE_2 dst_unused:UNUSED_PRESERVE src0_sel:DWORD
	v_cvt_u32_f32_sdwa v197, v114 dst_sel:BYTE_2 dst_unused:UNUSED_PRESERVE src0_sel:DWORD
	v_cvt_u32_f32_sdwa v196, v119 dst_sel:BYTE_3 dst_unused:UNUSED_PRESERVE src0_sel:DWORD
	v_cvt_u32_f32_sdwa v197, v115 dst_sel:BYTE_3 dst_unused:UNUSED_PRESERVE src0_sel:DWORD
	s_waitcnt vmcnt(7)
; __device__ __forceinline__ float sigmoidf_(float z) { return __builtin_amdgcn_rcpf(1.0f + __builtin_amdgcn_exp2f(-1.4426950408889634f * z)); }
;     __device__ __forceinline__ float compute(const Pre& p, f32x4 (&acc)[2][2][4][2], const f32x4 (&cv)[2][2], const pg8::Unit& u, int ai, int m, int wr, int wc, int fr, int fq) const {
;     ...
;             } else if (MODE == EM_GATES) {
;                 const int col = u.pn * 256 + ct; float w[8];
; #pragma unroll
;                 for (int j = 0; j < 8; ++j) w[j] = sigmoidf_(v[j] * rs) * 255.0f + 0.5f;
;                 u32x2 cd; cd.x = (unsigned)w[0] | ((unsigned)w[1] << 8) | ((unsigned)w[2] << 16) | ((unsigned)w[3] << 24); cd.y = (unsigned)w[4] | ((unsigned)w[5] << 8) | ((unsigned)w[6] << 16) | ((unsigned)w[7] << 24);
;                 *(u32x2*)(ws + WS_G8 + (size_t)row * 2048 + col) = cd;
	v_mul_f32_e32 v176, 0xbfb8aa3b, v183
	s_mov_b32 s78, 0x8000
	v_lshl_add_u64 v[204:205], v[172:173], 0, s[78:79]
	v_pk_mul_f32 v[104:105], v[104:105], v[176:177] op_sel_hi:[1,0]
	v_pk_mul_f32 v[106:107], v[106:107], v[176:177] op_sel_hi:[1,0]
	v_pk_mul_f32 v[108:109], v[108:109], v[176:177] op_sel_hi:[1,0]
	v_pk_mul_f32 v[110:111], v[110:111], v[176:177] op_sel_hi:[1,0]
	global_store_dwordx2 v[172:173], v[196:197], off offset:128
	v_exp_f32_e32 v104, v104
	v_exp_f32_e32 v105, v105
	v_exp_f32_e32 v106, v106
	v_exp_f32_e32 v107, v107
	v_exp_f32_e32 v108, v108
	v_exp_f32_e32 v109, v109
	v_exp_f32_e32 v110, v110
	v_exp_f32_e32 v111, v111
	v_pk_add_f32 v[104:105], v[104:105], 1.0 op_sel_hi:[1,0]
	v_pk_add_f32 v[106:107], v[106:107], 1.0 op_sel_hi:[1,0]
	v_pk_add_f32 v[108:109], v[108:109], 1.0 op_sel_hi:[1,0]
	v_pk_add_f32 v[110:111], v[110:111], 1.0 op_sel_hi:[1,0]
	v_rcp_f32_e32 v104, v104
	v_rcp_f32_e32 v105, v105
	v_rcp_f32_e32 v106, v106
	v_rcp_f32_e32 v107, v107
	v_rcp_f32_e32 v108, v108
	v_rcp_f32_e32 v109, v109
	v_rcp_f32_e32 v110, v110
	v_rcp_f32_e32 v111, v111
	v_pk_fma_f32 v[104:105], v[104:105], s[14:15], 0.5 op_sel_hi:[1,0,0]
	v_pk_fma_f32 v[106:107], v[106:107], s[14:15], 0.5 op_sel_hi:[1,0,0]
	v_pk_fma_f32 v[108:109], v[108:109], s[14:15], 0.5 op_sel_hi:[1,0,0]
	v_pk_fma_f32 v[110:111], v[110:111], s[14:15], 0.5 op_sel_hi:[1,0,0]
	v_cvt_u32_f32_e32 v198, v108
	v_cvt_u32_f32_e32 v199, v104
	v_cvt_u32_f32_sdwa v198, v109 dst_sel:BYTE_1 dst_unused:UNUSED_PRESERVE src0_sel:DWORD
	v_cvt_u32_f32_sdwa v199, v105 dst_sel:BYTE_1 dst_unused:UNUSED_PRESERVE src0_sel:DWORD
	v_cvt_u32_f32_sdwa v198, v110 dst_sel:BYTE_2 dst_unused:UNUSED_PRESERVE src0_sel:DWORD
	v_cvt_u32_f32_sdwa v199, v106 dst_sel:BYTE_2 dst_unused:UNUSED_PRESERVE src0_sel:DWORD
	v_cvt_u32_f32_sdwa v198, v111 dst_sel:BYTE_3 dst_unused:UNUSED_PRESERVE src0_sel:DWORD
	v_cvt_u32_f32_sdwa v199, v107 dst_sel:BYTE_3 dst_unused:UNUSED_PRESERVE src0_sel:DWORD
	v_pk_mul_f32 v[96:97], v[96:97], v[176:177] op_sel_hi:[1,0]
	v_pk_mul_f32 v[98:99], v[98:99], v[176:177] op_sel_hi:[1,0]
	v_pk_mul_f32 v[100:101], v[100:101], v[176:177] op_sel_hi:[1,0]
	v_pk_mul_f32 v[102:103], v[102:103], v[176:177] op_sel_hi:[1,0]
	global_store_dwordx2 v[204:205], v[198:199], off
	v_exp_f32_e32 v96, v96
	v_exp_f32_e32 v97, v97
	v_exp_f32_e32 v98, v98
	v_exp_f32_e32 v99, v99
	v_exp_f32_e32 v100, v100
	v_exp_f32_e32 v101, v101
	v_exp_f32_e32 v102, v102
	v_exp_f32_e32 v103, v103
	v_pk_add_f32 v[96:97], v[96:97], 1.0 op_sel_hi:[1,0]
	v_pk_add_f32 v[98:99], v[98:99], 1.0 op_sel_hi:[1,0]
	v_pk_add_f32 v[100:101], v[100:101], 1.0 op_sel_hi:[1,0]
	v_pk_add_f32 v[102:103], v[102:103], 1.0 op_sel_hi:[1,0]
	v_rcp_f32_e32 v96, v96
	v_rcp_f32_e32 v97, v97
	v_rcp_f32_e32 v98, v98
	v_rcp_f32_e32 v99, v99
	v_rcp_f32_e32 v100, v100
	v_rcp_f32_e32 v101, v101
	v_rcp_f32_e32 v102, v102
	v_rcp_f32_e32 v103, v103
	v_pk_fma_f32 v[96:97], v[96:97], s[14:15], 0.5 op_sel_hi:[1,0,0]
	v_pk_fma_f32 v[98:99], v[98:99], s[14:15], 0.5 op_sel_hi:[1,0,0]
	v_pk_fma_f32 v[100:101], v[100:101], s[14:15], 0.5 op_sel_hi:[1,0,0]
	v_pk_fma_f32 v[102:103], v[102:103], s[14:15], 0.5 op_sel_hi:[1,0,0]
	v_cvt_u32_f32_e32 v200, v100
	v_cvt_u32_f32_e32 v201, v96
	v_cvt_u32_f32_sdwa v200, v101 dst_sel:BYTE_1 dst_unused:UNUSED_PRESERVE src0_sel:DWORD
	v_cvt_u32_f32_sdwa v201, v97 dst_sel:BYTE_1 dst_unused:UNUSED_PRESERVE src0_sel:DWORD
	v_cvt_u32_f32_sdwa v200, v102 dst_sel:BYTE_2 dst_unused:UNUSED_PRESERVE src0_sel:DWORD
	v_cvt_u32_f32_sdwa v201, v98 dst_sel:BYTE_2 dst_unused:UNUSED_PRESERVE src0_sel:DWORD
	v_cvt_u32_f32_sdwa v200, v103 dst_sel:BYTE_3 dst_unused:UNUSED_PRESERVE src0_sel:DWORD
	v_cvt_u32_f32_sdwa v201, v99 dst_sel:BYTE_3 dst_unused:UNUSED_PRESERVE src0_sel:DWORD
	s_waitcnt vmcnt(8)
	v_mul_f32_e32 v178, 0xbfb8aa3b, v184
	s_mov_b32 s78, 0x10000
	v_lshl_add_u64 v[202:203], v[172:173], 0, s[78:79]
	v_pk_mul_f32 v[88:89], v[88:89], v[178:179] op_sel_hi:[1,0]
	v_pk_mul_f32 v[90:91], v[90:91], v[178:179] op_sel_hi:[1,0]
	v_pk_mul_f32 v[92:93], v[92:93], v[178:179] op_sel_hi:[1,0]
	v_pk_mul_f32 v[94:95], v[94:95], v[178:179] op_sel_hi:[1,0]
	global_store_dwordx2 v[204:205], v[200:201], off offset:128
	v_exp_f32_e32 v88, v88
	v_exp_f32_e32 v89, v89
	v_exp_f32_e32 v90, v90
	v_exp_f32_e32 v91, v91
	v_exp_f32_e32 v92, v92
	v_exp_f32_e32 v93, v93
	v_exp_f32_e32 v94, v94
	v_exp_f32_e32 v95, v95
	v_pk_add_f32 v[88:89], v[88:89], 1.0 op_sel_hi:[1,0]
	v_pk_add_f32 v[90:91], v[90:91], 1.0 op_sel_hi:[1,0]
	v_pk_add_f32 v[92:93], v[92:93], 1.0 op_sel_hi:[1,0]
	v_pk_add_f32 v[94:95], v[94:95], 1.0 op_sel_hi:[1,0]
	v_rcp_f32_e32 v88, v88
	v_rcp_f32_e32 v89, v89
	v_rcp_f32_e32 v90, v90
	v_rcp_f32_e32 v91, v91
	v_rcp_f32_e32 v92, v92
	v_rcp_f32_e32 v93, v93
	v_rcp_f32_e32 v94, v94
	v_rcp_f32_e32 v95, v95
	v_pk_fma_f32 v[88:89], v[88:89], s[14:15], 0.5 op_sel_hi:[1,0,0]
	v_pk_fma_f32 v[90:91], v[90:91], s[14:15], 0.5 op_sel_hi:[1,0,0]
	v_pk_fma_f32 v[92:93], v[92:93], s[14:15], 0.5 op_sel_hi:[1,0,0]
	v_pk_fma_f32 v[94:95], v[94:95], s[14:15], 0.5 op_sel_hi:[1,0,0]
	v_cvt_u32_f32_e32 v194, v92
	v_cvt_u32_f32_e32 v195, v88
	v_cvt_u32_f32_sdwa v194, v93 dst_sel:BYTE_1 dst_unused:UNUSED_PRESERVE src0_sel:DWORD
	v_cvt_u32_f32_sdwa v195, v89 dst_sel:BYTE_1 dst_unused:UNUSED_PRESERVE src0_sel:DWORD
	v_cvt_u32_f32_sdwa v194, v94 dst_sel:BYTE_2 dst_unused:UNUSED_PRESERVE src0_sel:DWORD
	v_cvt_u32_f32_sdwa v195, v90 dst_sel:BYTE_2 dst_unused:UNUSED_PRESERVE src0_sel:DWORD
	v_cvt_u32_f32_sdwa v194, v95 dst_sel:BYTE_3 dst_unused:UNUSED_PRESERVE src0_sel:DWORD
	v_cvt_u32_f32_sdwa v195, v91 dst_sel:BYTE_3 dst_unused:UNUSED_PRESERVE src0_sel:DWORD
; __device__ __forceinline__ float sigmoidf_(float z) { return __builtin_amdgcn_rcpf(1.0f + __builtin_amdgcn_exp2f(-1.4426950408889634f * z)); }
;     __device__ __forceinline__ float compute(const Pre& p, f32x4 (&acc)[2][2][4][2], const f32x4 (&cv)[2][2], const pg8::Unit& u, int ai, int m, int wr, int wc, int fr, int fq) const {
;     ...
;             } else if (MODE == EM_GATES) {
;                 const int col = u.pn * 256 + ct; float w[8];
; #pragma unroll
;                 for (int j = 0; j < 8; ++j) w[j] = sigmoidf_(v[j] * rs) * 255.0f + 0.5f;
;                 u32x2 cd; cd.x = (unsigned)w[0] | ((unsigned)w[1] << 8) | ((unsigned)w[2] << 16) | ((unsigned)w[3] << 24); cd.y = (unsigned)w[4] | ((unsigned)w[5] << 8) | ((unsigned)w[6] << 16) | ((unsigned)w[7] << 24);
;                 *(u32x2*)(ws + WS_G8 + (size_t)row * 2048 + col) = cd;
	v_pk_mul_f32 v[80:81], v[80:81], v[178:179] op_sel_hi:[1,0]
	v_pk_mul_f32 v[82:83], v[82:83], v[178:179] op_sel_hi:[1,0]
	v_pk_mul_f32 v[84:85], v[84:85], v[178:179] op_sel_hi:[1,0]
	v_pk_mul_f32 v[86:87], v[86:87], v[178:179] op_sel_hi:[1,0]
	global_store_dwordx2 v[202:203], v[194:195], off
	v_exp_f32_e32 v80, v80
	v_exp_f32_e32 v81, v81
	v_exp_f32_e32 v82, v82
	v_exp_f32_e32 v83, v83
	v_exp_f32_e32 v84, v84
	v_exp_f32_e32 v85, v85
	v_exp_f32_e32 v86, v86
	v_exp_f32_e32 v87, v87
	v_pk_add_f32 v[80:81], v[80:81], 1.0 op_sel_hi:[1,0]
	v_pk_add_f32 v[82:83], v[82:83], 1.0 op_sel_hi:[1,0]
	v_pk_add_f32 v[84:85], v[84:85], 1.0 op_sel_hi:[1,0]
	v_pk_add_f32 v[86:87], v[86:87], 1.0 op_sel_hi:[1,0]
	v_rcp_f32_e32 v80, v80
	v_rcp_f32_e32 v81, v81
	v_rcp_f32_e32 v82, v82
	v_rcp_f32_e32 v83, v83
	v_rcp_f32_e32 v84, v84
	v_rcp_f32_e32 v85, v85
	v_rcp_f32_e32 v86, v86
	v_rcp_f32_e32 v87, v87
	v_pk_fma_f32 v[80:81], v[80:81], s[14:15], 0.5 op_sel_hi:[1,0,0]
	v_pk_fma_f32 v[82:83], v[82:83], s[14:15], 0.5 op_sel_hi:[1,0,0]
	v_pk_fma_f32 v[84:85], v[84:85], s[14:15], 0.5 op_sel_hi:[1,0,0]
	v_pk_fma_f32 v[86:87], v[86:87], s[14:15], 0.5 op_sel_hi:[1,0,0]
	v_cvt_u32_f32_e32 v196, v84
	v_cvt_u32_f32_e32 v197, v80
	v_cvt_u32_f32_sdwa v196, v85 dst_sel:BYTE_1 dst_unused:UNUSED_PRESERVE src0_sel:DWORD
	v_cvt_u32_f32_sdwa v197, v81 dst_sel:BYTE_1 dst_unused:UNUSED_PRESERVE src0_sel:DWORD
	v_cvt_u32_f32_sdwa v196, v86 dst_sel:BYTE_2 dst_unused:UNUSED_PRESERVE src0_sel:DWORD
	v_cvt_u32_f32_sdwa v197, v82 dst_sel:BYTE_2 dst_unused:UNUSED_PRESERVE src0_sel:DWORD
	v_cvt_u32_f32_sdwa v196, v87 dst_sel:BYTE_3 dst_unused:UNUSED_PRESERVE src0_sel:DWORD
	v_cvt_u32_f32_sdwa v197, v83 dst_sel:BYTE_3 dst_unused:UNUSED_PRESERVE src0_sel:DWORD
	s_waitcnt vmcnt(9)
	v_mul_f32_e32 v180, 0xbfb8aa3b, v168
	s_mov_b32 s78, 0x18000
	v_lshl_add_u64 v[204:205], v[172:173], 0, s[78:79]
	v_pk_mul_f32 v[72:73], v[72:73], v[180:181] op_sel_hi:[1,0]
	v_pk_mul_f32 v[74:75], v[74:75], v[180:181] op_sel_hi:[1,0]
	v_pk_mul_f32 v[76:77], v[76:77], v[180:181] op_sel_hi:[1,0]
	v_pk_mul_f32 v[78:79], v[78:79], v[180:181] op_sel_hi:[1,0]
	global_store_dwordx2 v[202:203], v[196:197], off offset:128
	v_exp_f32_e32 v72, v72
	v_exp_f32_e32 v73, v73
	v_exp_f32_e32 v74, v74
	v_exp_f32_e32 v75, v75
	v_exp_f32_e32 v76, v76
	v_exp_f32_e32 v77, v77
	v_exp_f32_e32 v78, v78
	v_exp_f32_e32 v79, v79
	v_pk_add_f32 v[72:73], v[72:73], 1.0 op_sel_hi:[1,0]
	v_pk_add_f32 v[74:75], v[74:75], 1.0 op_sel_hi:[1,0]
	v_pk_add_f32 v[76:77], v[76:77], 1.0 op_sel_hi:[1,0]
	v_pk_add_f32 v[78:79], v[78:79], 1.0 op_sel_hi:[1,0]
	v_rcp_f32_e32 v72, v72
	v_rcp_f32_e32 v73, v73
	v_rcp_f32_e32 v74, v74
	v_rcp_f32_e32 v75, v75
	v_rcp_f32_e32 v76, v76
	v_rcp_f32_e32 v77, v77
	v_rcp_f32_e32 v78, v78
	v_rcp_f32_e32 v79, v79
	v_pk_fma_f32 v[72:73], v[72:73], s[14:15], 0.5 op_sel_hi:[1,0,0]
	v_pk_fma_f32 v[74:75], v[74:75], s[14:15], 0.5 op_sel_hi:[1,0,0]
	v_pk_fma_f32 v[76:77], v[76:77], s[14:15], 0.5 op_sel_hi:[1,0,0]
	v_pk_fma_f32 v[78:79], v[78:79], s[14:15], 0.5 op_sel_hi:[1,0,0]
	v_cvt_u32_f32_e32 v198, v76
	v_cvt_u32_f32_e32 v199, v72
	v_cvt_u32_f32_sdwa v198, v77 dst_sel:BYTE_1 dst_unused:UNUSED_PRESERVE src0_sel:DWORD
	v_cvt_u32_f32_sdwa v199, v73 dst_sel:BYTE_1 dst_unused:UNUSED_PRESERVE src0_sel:DWORD
	v_cvt_u32_f32_sdwa v198, v78 dst_sel:BYTE_2 dst_unused:UNUSED_PRESERVE src0_sel:DWORD
	v_cvt_u32_f32_sdwa v199, v74 dst_sel:BYTE_2 dst_unused:UNUSED_PRESERVE src0_sel:DWORD
	v_cvt_u32_f32_sdwa v198, v79 dst_sel:BYTE_3 dst_unused:UNUSED_PRESERVE src0_sel:DWORD
	v_cvt_u32_f32_sdwa v199, v75 dst_sel:BYTE_3 dst_unused:UNUSED_PRESERVE src0_sel:DWORD
	v_pk_mul_f32 v[64:65], v[64:65], v[180:181] op_sel_hi:[1,0]
	v_pk_mul_f32 v[66:67], v[66:67], v[180:181] op_sel_hi:[1,0]
	v_pk_mul_f32 v[68:69], v[68:69], v[180:181] op_sel_hi:[1,0]
	v_pk_mul_f32 v[70:71], v[70:71], v[180:181] op_sel_hi:[1,0]
	global_store_dwordx2 v[204:205], v[198:199], off
	v_exp_f32_e32 v64, v64
	v_exp_f32_e32 v65, v65
	v_exp_f32_e32 v66, v66
	v_exp_f32_e32 v67, v67
	v_exp_f32_e32 v68, v68
	v_exp_f32_e32 v69, v69
	v_exp_f32_e32 v70, v70
	v_exp_f32_e32 v71, v71
	v_pk_add_f32 v[64:65], v[64:65], 1.0 op_sel_hi:[1,0]
	v_pk_add_f32 v[66:67], v[66:67], 1.0 op_sel_hi:[1,0]
	v_pk_add_f32 v[68:69], v[68:69], 1.0 op_sel_hi:[1,0]
	v_pk_add_f32 v[70:71], v[70:71], 1.0 op_sel_hi:[1,0]
	v_rcp_f32_e32 v64, v64
	v_rcp_f32_e32 v65, v65
	v_rcp_f32_e32 v66, v66
	v_rcp_f32_e32 v67, v67
	v_rcp_f32_e32 v68, v68
	v_rcp_f32_e32 v69, v69
	v_rcp_f32_e32 v70, v70
	v_rcp_f32_e32 v71, v71
	v_pk_fma_f32 v[64:65], v[64:65], s[14:15], 0.5 op_sel_hi:[1,0,0]
	v_pk_fma_f32 v[66:67], v[66:67], s[14:15], 0.5 op_sel_hi:[1,0,0]
	v_pk_fma_f32 v[68:69], v[68:69], s[14:15], 0.5 op_sel_hi:[1,0,0]
	v_pk_fma_f32 v[70:71], v[70:71], s[14:15], 0.5 op_sel_hi:[1,0,0]
	v_cvt_u32_f32_e32 v200, v68
	v_cvt_u32_f32_e32 v201, v64
	v_cvt_u32_f32_sdwa v200, v69 dst_sel:BYTE_1 dst_unused:UNUSED_PRESERVE src0_sel:DWORD
	v_cvt_u32_f32_sdwa v201, v65 dst_sel:BYTE_1 dst_unused:UNUSED_PRESERVE src0_sel:DWORD
	v_cvt_u32_f32_sdwa v200, v70 dst_sel:BYTE_2 dst_unused:UNUSED_PRESERVE src0_sel:DWORD
	v_cvt_u32_f32_sdwa v201, v66 dst_sel:BYTE_2 dst_unused:UNUSED_PRESERVE src0_sel:DWORD
	v_cvt_u32_f32_sdwa v200, v71 dst_sel:BYTE_3 dst_unused:UNUSED_PRESERVE src0_sel:DWORD
	v_cvt_u32_f32_sdwa v201, v67 dst_sel:BYTE_3 dst_unused:UNUSED_PRESERVE src0_sel:DWORD
	s_waitcnt vmcnt(10)
; __device__ __forceinline__ float sigmoidf_(float z) { return __builtin_amdgcn_rcpf(1.0f + __builtin_amdgcn_exp2f(-1.4426950408889634f * z)); }
;     __device__ __forceinline__ float compute(const Pre& p, f32x4 (&acc)[2][2][4][2], const f32x4 (&cv)[2][2], const pg8::Unit& u, int ai, int m, int wr, int wc, int fr, int fq) const {
;     ...
;             } else if (MODE == EM_GATES) {
;                 const int col = u.pn * 256 + ct; float w[8];
; #pragma unroll
;                 for (int j = 0; j < 8; ++j) w[j] = sigmoidf_(v[j] * rs) * 255.0f + 0.5f;
;                 u32x2 cd; cd.x = (unsigned)w[0] | ((unsigned)w[1] << 8) | ((unsigned)w[2] << 16) | ((unsigned)w[3] << 24); cd.y = (unsigned)w[4] | ((unsigned)w[5] << 8) | ((unsigned)w[6] << 16) | ((unsigned)w[7] << 24);
;                 *(u32x2*)(ws + WS_G8 + (size_t)row * 2048 + col) = cd;
	v_mul_f32_e32 v186, 0xbfb8aa3b, v167
	s_mov_b32 s78, 0x40000
	v_lshl_add_u64 v[202:203], v[172:173], 0, s[78:79]
	v_pk_mul_f32 v[56:57], v[56:57], v[186:187] op_sel_hi:[1,0]
	v_pk_mul_f32 v[58:59], v[58:59], v[186:187] op_sel_hi:[1,0]
	v_pk_mul_f32 v[60:61], v[60:61], v[186:187] op_sel_hi:[1,0]
	v_pk_mul_f32 v[62:63], v[62:63], v[186:187] op_sel_hi:[1,0]
	global_store_dwordx2 v[204:205], v[200:201], off offset:128
	v_exp_f32_e32 v56, v56
	v_exp_f32_e32 v57, v57
	v_exp_f32_e32 v58, v58
	v_exp_f32_e32 v59, v59
	v_exp_f32_e32 v60, v60
	v_exp_f32_e32 v61, v61
	v_exp_f32_e32 v62, v62
	v_exp_f32_e32 v63, v63
	v_pk_add_f32 v[56:57], v[56:57], 1.0 op_sel_hi:[1,0]
	v_pk_add_f32 v[58:59], v[58:59], 1.0 op_sel_hi:[1,0]
	v_pk_add_f32 v[60:61], v[60:61], 1.0 op_sel_hi:[1,0]
	v_pk_add_f32 v[62:63], v[62:63], 1.0 op_sel_hi:[1,0]
	v_rcp_f32_e32 v56, v56
	v_rcp_f32_e32 v57, v57
	v_rcp_f32_e32 v58, v58
	v_rcp_f32_e32 v59, v59
	v_rcp_f32_e32 v60, v60
	v_rcp_f32_e32 v61, v61
	v_rcp_f32_e32 v62, v62
	v_rcp_f32_e32 v63, v63
	v_pk_fma_f32 v[56:57], v[56:57], s[14:15], 0.5 op_sel_hi:[1,0,0]
	v_pk_fma_f32 v[58:59], v[58:59], s[14:15], 0.5 op_sel_hi:[1,0,0]
	v_pk_fma_f32 v[60:61], v[60:61], s[14:15], 0.5 op_sel_hi:[1,0,0]
	v_pk_fma_f32 v[62:63], v[62:63], s[14:15], 0.5 op_sel_hi:[1,0,0]
	v_cvt_u32_f32_e32 v194, v60
	v_cvt_u32_f32_e32 v195, v56
	v_cvt_u32_f32_sdwa v194, v61 dst_sel:BYTE_1 dst_unused:UNUSED_PRESERVE src0_sel:DWORD
	v_cvt_u32_f32_sdwa v195, v57 dst_sel:BYTE_1 dst_unused:UNUSED_PRESERVE src0_sel:DWORD
	v_cvt_u32_f32_sdwa v194, v62 dst_sel:BYTE_2 dst_unused:UNUSED_PRESERVE src0_sel:DWORD
	v_cvt_u32_f32_sdwa v195, v58 dst_sel:BYTE_2 dst_unused:UNUSED_PRESERVE src0_sel:DWORD
	v_cvt_u32_f32_sdwa v194, v63 dst_sel:BYTE_3 dst_unused:UNUSED_PRESERVE src0_sel:DWORD
	v_cvt_u32_f32_sdwa v195, v59 dst_sel:BYTE_3 dst_unused:UNUSED_PRESERVE src0_sel:DWORD
	v_pk_mul_f32 v[48:49], v[48:49], v[186:187] op_sel_hi:[1,0]
	v_pk_mul_f32 v[50:51], v[50:51], v[186:187] op_sel_hi:[1,0]
	v_pk_mul_f32 v[52:53], v[52:53], v[186:187] op_sel_hi:[1,0]
	v_pk_mul_f32 v[54:55], v[54:55], v[186:187] op_sel_hi:[1,0]
	global_store_dwordx2 v[202:203], v[194:195], off
	v_exp_f32_e32 v48, v48
	v_exp_f32_e32 v49, v49
	v_exp_f32_e32 v50, v50
	v_exp_f32_e32 v51, v51
	v_exp_f32_e32 v52, v52
	v_exp_f32_e32 v53, v53
	v_exp_f32_e32 v54, v54
	v_exp_f32_e32 v55, v55
	v_pk_add_f32 v[48:49], v[48:49], 1.0 op_sel_hi:[1,0]
	v_pk_add_f32 v[50:51], v[50:51], 1.0 op_sel_hi:[1,0]
	v_pk_add_f32 v[52:53], v[52:53], 1.0 op_sel_hi:[1,0]
	v_pk_add_f32 v[54:55], v[54:55], 1.0 op_sel_hi:[1,0]
	v_rcp_f32_e32 v48, v48
	v_rcp_f32_e32 v49, v49
	v_rcp_f32_e32 v50, v50
	v_rcp_f32_e32 v51, v51
	v_rcp_f32_e32 v52, v52
	v_rcp_f32_e32 v53, v53
	v_rcp_f32_e32 v54, v54
	v_rcp_f32_e32 v55, v55
	v_pk_fma_f32 v[48:49], v[48:49], s[14:15], 0.5 op_sel_hi:[1,0,0]
	v_pk_fma_f32 v[50:51], v[50:51], s[14:15], 0.5 op_sel_hi:[1,0,0]
	v_pk_fma_f32 v[52:53], v[52:53], s[14:15], 0.5 op_sel_hi:[1,0,0]
	v_pk_fma_f32 v[54:55], v[54:55], s[14:15], 0.5 op_sel_hi:[1,0,0]
	v_cvt_u32_f32_e32 v196, v52
	v_cvt_u32_f32_e32 v197, v48
	v_cvt_u32_f32_sdwa v196, v53 dst_sel:BYTE_1 dst_unused:UNUSED_PRESERVE src0_sel:DWORD
	v_cvt_u32_f32_sdwa v197, v49 dst_sel:BYTE_1 dst_unused:UNUSED_PRESERVE src0_sel:DWORD
	v_cvt_u32_f32_sdwa v196, v54 dst_sel:BYTE_2 dst_unused:UNUSED_PRESERVE src0_sel:DWORD
	v_cvt_u32_f32_sdwa v197, v50 dst_sel:BYTE_2 dst_unused:UNUSED_PRESERVE src0_sel:DWORD
	v_cvt_u32_f32_sdwa v196, v55 dst_sel:BYTE_3 dst_unused:UNUSED_PRESERVE src0_sel:DWORD
	v_cvt_u32_f32_sdwa v197, v51 dst_sel:BYTE_3 dst_unused:UNUSED_PRESERVE src0_sel:DWORD
	s_waitcnt vmcnt(11)
	v_mul_f32_e32 v188, 0xbfb8aa3b, v166
	s_mov_b32 s78, 0x48000
	v_lshl_add_u64 v[204:205], v[172:173], 0, s[78:79]
	v_pk_mul_f32 v[40:41], v[40:41], v[188:189] op_sel_hi:[1,0]
	v_pk_mul_f32 v[42:43], v[42:43], v[188:189] op_sel_hi:[1,0]
	v_pk_mul_f32 v[44:45], v[44:45], v[188:189] op_sel_hi:[1,0]
	v_pk_mul_f32 v[46:47], v[46:47], v[188:189] op_sel_hi:[1,0]
	global_store_dwordx2 v[202:203], v[196:197], off offset:128
	v_exp_f32_e32 v40, v40
	v_exp_f32_e32 v41, v41
	v_exp_f32_e32 v42, v42
	v_exp_f32_e32 v43, v43
	v_exp_f32_e32 v44, v44
	v_exp_f32_e32 v45, v45
	v_exp_f32_e32 v46, v46
	v_exp_f32_e32 v47, v47
	v_pk_add_f32 v[40:41], v[40:41], 1.0 op_sel_hi:[1,0]
	v_pk_add_f32 v[42:43], v[42:43], 1.0 op_sel_hi:[1,0]
	v_pk_add_f32 v[44:45], v[44:45], 1.0 op_sel_hi:[1,0]
	v_pk_add_f32 v[46:47], v[46:47], 1.0 op_sel_hi:[1,0]
	v_rcp_f32_e32 v40, v40
	v_rcp_f32_e32 v41, v41
	v_rcp_f32_e32 v42, v42
	v_rcp_f32_e32 v43, v43
	v_rcp_f32_e32 v44, v44
	v_rcp_f32_e32 v45, v45
	v_rcp_f32_e32 v46, v46
	v_rcp_f32_e32 v47, v47
	v_pk_fma_f32 v[40:41], v[40:41], s[14:15], 0.5 op_sel_hi:[1,0,0]
	v_pk_fma_f32 v[42:43], v[42:43], s[14:15], 0.5 op_sel_hi:[1,0,0]
	v_pk_fma_f32 v[44:45], v[44:45], s[14:15], 0.5 op_sel_hi:[1,0,0]
	v_pk_fma_f32 v[46:47], v[46:47], s[14:15], 0.5 op_sel_hi:[1,0,0]
	v_cvt_u32_f32_e32 v198, v44
	v_cvt_u32_f32_e32 v199, v40
	v_cvt_u32_f32_sdwa v198, v45 dst_sel:BYTE_1 dst_unused:UNUSED_PRESERVE src0_sel:DWORD
	v_cvt_u32_f32_sdwa v199, v41 dst_sel:BYTE_1 dst_unused:UNUSED_PRESERVE src0_sel:DWORD
	v_cvt_u32_f32_sdwa v198, v46 dst_sel:BYTE_2 dst_unused:UNUSED_PRESERVE src0_sel:DWORD
	v_cvt_u32_f32_sdwa v199, v42 dst_sel:BYTE_2 dst_unused:UNUSED_PRESERVE src0_sel:DWORD
	v_cvt_u32_f32_sdwa v198, v47 dst_sel:BYTE_3 dst_unused:UNUSED_PRESERVE src0_sel:DWORD
	v_cvt_u32_f32_sdwa v199, v43 dst_sel:BYTE_3 dst_unused:UNUSED_PRESERVE src0_sel:DWORD
	v_pk_mul_f32 v[32:33], v[32:33], v[188:189] op_sel_hi:[1,0]
	v_pk_mul_f32 v[34:35], v[34:35], v[188:189] op_sel_hi:[1,0]
	v_pk_mul_f32 v[36:37], v[36:37], v[188:189] op_sel_hi:[1,0]
; __device__ __forceinline__ float sigmoidf_(float z) { return __builtin_amdgcn_rcpf(1.0f + __builtin_amdgcn_exp2f(-1.4426950408889634f * z)); }
;     __device__ __forceinline__ float compute(const Pre& p, f32x4 (&acc)[2][2][4][2], const f32x4 (&cv)[2][2], const pg8::Unit& u, int ai, int m, int wr, int wc, int fr, int fq) const {
;     ...
;             } else if (MODE == EM_GATES) {
;                 const int col = u.pn * 256 + ct; float w[8];
; #pragma unroll
;                 for (int j = 0; j < 8; ++j) w[j] = sigmoidf_(v[j] * rs) * 255.0f + 0.5f;
;                 u32x2 cd; cd.x = (unsigned)w[0] | ((unsigned)w[1] << 8) | ((unsigned)w[2] << 16) | ((unsigned)w[3] << 24); cd.y = (unsigned)w[4] | ((unsigned)w[5] << 8) | ((unsigned)w[6] << 16) | ((unsigned)w[7] << 24);
;                 *(u32x2*)(ws + WS_G8 + (size_t)row * 2048 + col) = cd;
	v_pk_mul_f32 v[38:39], v[38:39], v[188:189] op_sel_hi:[1,0]
	global_store_dwordx2 v[204:205], v[198:199], off
	v_exp_f32_e32 v32, v32
	v_exp_f32_e32 v33, v33
	v_exp_f32_e32 v34, v34
	v_exp_f32_e32 v35, v35
	v_exp_f32_e32 v36, v36
	v_exp_f32_e32 v37, v37
	v_exp_f32_e32 v38, v38
	v_exp_f32_e32 v39, v39
	v_pk_add_f32 v[32:33], v[32:33], 1.0 op_sel_hi:[1,0]
	v_pk_add_f32 v[34:35], v[34:35], 1.0 op_sel_hi:[1,0]
	v_pk_add_f32 v[36:37], v[36:37], 1.0 op_sel_hi:[1,0]
	v_pk_add_f32 v[38:39], v[38:39], 1.0 op_sel_hi:[1,0]
	v_rcp_f32_e32 v32, v32
	v_rcp_f32_e32 v33, v33
	v_rcp_f32_e32 v34, v34
	v_rcp_f32_e32 v35, v35
	v_rcp_f32_e32 v36, v36
	v_rcp_f32_e32 v37, v37
	v_rcp_f32_e32 v38, v38
	v_rcp_f32_e32 v39, v39
	v_pk_fma_f32 v[32:33], v[32:33], s[14:15], 0.5 op_sel_hi:[1,0,0]
	v_pk_fma_f32 v[34:35], v[34:35], s[14:15], 0.5 op_sel_hi:[1,0,0]
	v_pk_fma_f32 v[36:37], v[36:37], s[14:15], 0.5 op_sel_hi:[1,0,0]
	v_pk_fma_f32 v[38:39], v[38:39], s[14:15], 0.5 op_sel_hi:[1,0,0]
	v_cvt_u32_f32_e32 v200, v36
	v_cvt_u32_f32_e32 v201, v32
	v_cvt_u32_f32_sdwa v200, v37 dst_sel:BYTE_1 dst_unused:UNUSED_PRESERVE src0_sel:DWORD
	v_cvt_u32_f32_sdwa v201, v33 dst_sel:BYTE_1 dst_unused:UNUSED_PRESERVE src0_sel:DWORD
	v_cvt_u32_f32_sdwa v200, v38 dst_sel:BYTE_2 dst_unused:UNUSED_PRESERVE src0_sel:DWORD
	v_cvt_u32_f32_sdwa v201, v34 dst_sel:BYTE_2 dst_unused:UNUSED_PRESERVE src0_sel:DWORD
	v_cvt_u32_f32_sdwa v200, v39 dst_sel:BYTE_3 dst_unused:UNUSED_PRESERVE src0_sel:DWORD
	v_cvt_u32_f32_sdwa v201, v35 dst_sel:BYTE_3 dst_unused:UNUSED_PRESERVE src0_sel:DWORD
	s_waitcnt vmcnt(12)
	v_mul_f32_e32 v190, 0xbfb8aa3b, v165
	s_mov_b32 s78, 0x50000
	v_lshl_add_u64 v[202:203], v[172:173], 0, s[78:79]
	v_pk_mul_f32 v[24:25], v[24:25], v[190:191] op_sel_hi:[1,0]
	v_pk_mul_f32 v[26:27], v[26:27], v[190:191] op_sel_hi:[1,0]
	v_pk_mul_f32 v[28:29], v[28:29], v[190:191] op_sel_hi:[1,0]
	v_pk_mul_f32 v[30:31], v[30:31], v[190:191] op_sel_hi:[1,0]
	global_store_dwordx2 v[204:205], v[200:201], off offset:128
	v_exp_f32_e32 v24, v24
	v_exp_f32_e32 v25, v25
	v_exp_f32_e32 v26, v26
	v_exp_f32_e32 v27, v27
	v_exp_f32_e32 v28, v28
	v_exp_f32_e32 v29, v29
	v_exp_f32_e32 v30, v30
	v_exp_f32_e32 v31, v31
	v_pk_add_f32 v[24:25], v[24:25], 1.0 op_sel_hi:[1,0]
	v_pk_add_f32 v[26:27], v[26:27], 1.0 op_sel_hi:[1,0]
	v_pk_add_f32 v[28:29], v[28:29], 1.0 op_sel_hi:[1,0]
	v_pk_add_f32 v[30:31], v[30:31], 1.0 op_sel_hi:[1,0]
	v_rcp_f32_e32 v24, v24
	v_rcp_f32_e32 v25, v25
	v_rcp_f32_e32 v26, v26
	v_rcp_f32_e32 v27, v27
	v_rcp_f32_e32 v28, v28
	v_rcp_f32_e32 v29, v29
	v_rcp_f32_e32 v30, v30
	v_rcp_f32_e32 v31, v31
	v_pk_fma_f32 v[24:25], v[24:25], s[14:15], 0.5 op_sel_hi:[1,0,0]
	v_pk_fma_f32 v[26:27], v[26:27], s[14:15], 0.5 op_sel_hi:[1,0,0]
	v_pk_fma_f32 v[28:29], v[28:29], s[14:15], 0.5 op_sel_hi:[1,0,0]
	v_pk_fma_f32 v[30:31], v[30:31], s[14:15], 0.5 op_sel_hi:[1,0,0]
	v_cvt_u32_f32_e32 v194, v28
	v_cvt_u32_f32_e32 v195, v24
	v_cvt_u32_f32_sdwa v194, v29 dst_sel:BYTE_1 dst_unused:UNUSED_PRESERVE src0_sel:DWORD
	v_cvt_u32_f32_sdwa v195, v25 dst_sel:BYTE_1 dst_unused:UNUSED_PRESERVE src0_sel:DWORD
	v_cvt_u32_f32_sdwa v194, v30 dst_sel:BYTE_2 dst_unused:UNUSED_PRESERVE src0_sel:DWORD
	v_cvt_u32_f32_sdwa v195, v26 dst_sel:BYTE_2 dst_unused:UNUSED_PRESERVE src0_sel:DWORD
	v_cvt_u32_f32_sdwa v194, v31 dst_sel:BYTE_3 dst_unused:UNUSED_PRESERVE src0_sel:DWORD
	v_cvt_u32_f32_sdwa v195, v27 dst_sel:BYTE_3 dst_unused:UNUSED_PRESERVE src0_sel:DWORD
	v_pk_mul_f32 v[16:17], v[16:17], v[190:191] op_sel_hi:[1,0]
	v_pk_mul_f32 v[18:19], v[18:19], v[190:191] op_sel_hi:[1,0]
	v_pk_mul_f32 v[20:21], v[20:21], v[190:191] op_sel_hi:[1,0]
	v_pk_mul_f32 v[22:23], v[22:23], v[190:191] op_sel_hi:[1,0]
	global_store_dwordx2 v[202:203], v[194:195], off
	v_exp_f32_e32 v16, v16
	v_exp_f32_e32 v17, v17
	v_exp_f32_e32 v18, v18
	v_exp_f32_e32 v19, v19
	v_exp_f32_e32 v20, v20
	v_exp_f32_e32 v21, v21
	v_exp_f32_e32 v22, v22
	v_exp_f32_e32 v23, v23
	v_pk_add_f32 v[16:17], v[16:17], 1.0 op_sel_hi:[1,0]
	v_pk_add_f32 v[18:19], v[18:19], 1.0 op_sel_hi:[1,0]
	v_pk_add_f32 v[20:21], v[20:21], 1.0 op_sel_hi:[1,0]
	v_pk_add_f32 v[22:23], v[22:23], 1.0 op_sel_hi:[1,0]
	v_rcp_f32_e32 v16, v16
	v_rcp_f32_e32 v17, v17
	v_rcp_f32_e32 v18, v18
	v_rcp_f32_e32 v19, v19
	v_rcp_f32_e32 v20, v20
	v_rcp_f32_e32 v21, v21
	v_rcp_f32_e32 v22, v22
	v_rcp_f32_e32 v23, v23
	v_pk_fma_f32 v[16:17], v[16:17], s[14:15], 0.5 op_sel_hi:[1,0,0]
	v_pk_fma_f32 v[18:19], v[18:19], s[14:15], 0.5 op_sel_hi:[1,0,0]
	v_pk_fma_f32 v[20:21], v[20:21], s[14:15], 0.5 op_sel_hi:[1,0,0]
	v_pk_fma_f32 v[22:23], v[22:23], s[14:15], 0.5 op_sel_hi:[1,0,0]
	v_cvt_u32_f32_e32 v196, v20
	v_cvt_u32_f32_e32 v197, v16
	v_cvt_u32_f32_sdwa v196, v21 dst_sel:BYTE_1 dst_unused:UNUSED_PRESERVE src0_sel:DWORD
	v_cvt_u32_f32_sdwa v197, v17 dst_sel:BYTE_1 dst_unused:UNUSED_PRESERVE src0_sel:DWORD
	v_cvt_u32_f32_sdwa v196, v22 dst_sel:BYTE_2 dst_unused:UNUSED_PRESERVE src0_sel:DWORD
	v_cvt_u32_f32_sdwa v197, v18 dst_sel:BYTE_2 dst_unused:UNUSED_PRESERVE src0_sel:DWORD
	v_cvt_u32_f32_sdwa v196, v23 dst_sel:BYTE_3 dst_unused:UNUSED_PRESERVE src0_sel:DWORD
	v_cvt_u32_f32_sdwa v197, v19 dst_sel:BYTE_3 dst_unused:UNUSED_PRESERVE src0_sel:DWORD
	s_waitcnt vmcnt(13)
; __device__ __forceinline__ float sigmoidf_(float z) { return __builtin_amdgcn_rcpf(1.0f + __builtin_amdgcn_exp2f(-1.4426950408889634f * z)); }
; #define PG8_BAR __builtin_amdgcn_s_barrier()
; template <class Epi, class Sched>
; __device__ __forceinline__ void gemm_phase(LAS unsigned char* lds, const Gemm g, const Sched& S, const Epi& E, int wave_id) {
;     ...
;         if (wr == 0) PG8_BAR;
;         E(acc, cur, wr, wc, fr, fq);
;         if (!has_next) break;
; #pragma unroll
;         for (int a = 0; a < 2; ++a)
; #pragma unroll
;             for (int b = 0; b < 2; ++b)
; #pragma unroll
;                 for (int m = 0; m < 4; ++m)
; #pragma unroll
;                     for (int n = 0; n < 2; ++n) acc[a][b][m][n] = (f32x4){0.f, 0.f, 0.f, 0.f};
;         cur = nxt; cA = nA; cB = nB; ++ui;
;         if (wr == 1) PG8_BAR;
;     __device__ __forceinline__ float compute(const Pre& p, f32x4 (&acc)[2][2][4][2], const f32x4 (&cv)[2][2], const pg8::Unit& u, int ai, int m, int wr, int wc, int fr, int fq) const {
;     ...
;             } else if (MODE == EM_GATES) {
;                 const int col = u.pn * 256 + ct; float w[8];
; #pragma unroll
;                 for (int j = 0; j < 8; ++j) w[j] = sigmoidf_(v[j] * rs) * 255.0f + 0.5f;
;                 u32x2 cd; cd.x = (unsigned)w[0] | ((unsigned)w[1] << 8) | ((unsigned)w[2] << 16) | ((unsigned)w[3] << 24); cd.y = (unsigned)w[4] | ((unsigned)w[5] << 8) | ((unsigned)w[6] << 16) | ((unsigned)w[7] << 24);
;                 *(u32x2*)(ws + WS_G8 + (size_t)row * 2048 + col) = cd;
	v_mul_f32_e32 v192, 0xbfb8aa3b, v164
	s_mov_b32 s78, 0x58000
	v_lshl_add_u64 v[204:205], v[172:173], 0, s[78:79]
	v_pk_mul_f32 v[8:9], v[8:9], v[192:193] op_sel_hi:[1,0]
	v_pk_mul_f32 v[10:11], v[10:11], v[192:193] op_sel_hi:[1,0]
	v_pk_mul_f32 v[12:13], v[12:13], v[192:193] op_sel_hi:[1,0]
	v_pk_mul_f32 v[14:15], v[14:15], v[192:193] op_sel_hi:[1,0]
	global_store_dwordx2 v[202:203], v[196:197], off offset:128
	v_exp_f32_e32 v8, v8
	v_exp_f32_e32 v9, v9
	v_exp_f32_e32 v10, v10
	v_exp_f32_e32 v11, v11
	v_exp_f32_e32 v12, v12
	v_exp_f32_e32 v13, v13
	v_exp_f32_e32 v14, v14
	v_exp_f32_e32 v15, v15
	v_pk_add_f32 v[8:9], v[8:9], 1.0 op_sel_hi:[1,0]
	v_pk_add_f32 v[10:11], v[10:11], 1.0 op_sel_hi:[1,0]
	v_pk_add_f32 v[12:13], v[12:13], 1.0 op_sel_hi:[1,0]
	v_pk_add_f32 v[14:15], v[14:15], 1.0 op_sel_hi:[1,0]
	v_rcp_f32_e32 v8, v8
	v_rcp_f32_e32 v9, v9
	v_rcp_f32_e32 v10, v10
	v_rcp_f32_e32 v11, v11
	v_rcp_f32_e32 v12, v12
	v_rcp_f32_e32 v13, v13
	v_rcp_f32_e32 v14, v14
	v_rcp_f32_e32 v15, v15
	v_pk_fma_f32 v[8:9], v[8:9], s[14:15], 0.5 op_sel_hi:[1,0,0]
	v_pk_fma_f32 v[10:11], v[10:11], s[14:15], 0.5 op_sel_hi:[1,0,0]
	v_pk_fma_f32 v[12:13], v[12:13], s[14:15], 0.5 op_sel_hi:[1,0,0]
	v_pk_fma_f32 v[14:15], v[14:15], s[14:15], 0.5 op_sel_hi:[1,0,0]
	v_cvt_u32_f32_e32 v198, v12
	v_cvt_u32_f32_e32 v199, v8
	v_cvt_u32_f32_sdwa v198, v13 dst_sel:BYTE_1 dst_unused:UNUSED_PRESERVE src0_sel:DWORD
	v_cvt_u32_f32_sdwa v199, v9 dst_sel:BYTE_1 dst_unused:UNUSED_PRESERVE src0_sel:DWORD
	v_cvt_u32_f32_sdwa v198, v14 dst_sel:BYTE_2 dst_unused:UNUSED_PRESERVE src0_sel:DWORD
	v_cvt_u32_f32_sdwa v199, v10 dst_sel:BYTE_2 dst_unused:UNUSED_PRESERVE src0_sel:DWORD
	v_cvt_u32_f32_sdwa v198, v15 dst_sel:BYTE_3 dst_unused:UNUSED_PRESERVE src0_sel:DWORD
	v_cvt_u32_f32_sdwa v199, v11 dst_sel:BYTE_3 dst_unused:UNUSED_PRESERVE src0_sel:DWORD
	v_pk_mul_f32 v[0:1], v[0:1], v[192:193] op_sel_hi:[1,0]
	v_pk_mul_f32 v[2:3], v[2:3], v[192:193] op_sel_hi:[1,0]
	v_pk_mul_f32 v[4:5], v[4:5], v[192:193] op_sel_hi:[1,0]
	v_pk_mul_f32 v[6:7], v[6:7], v[192:193] op_sel_hi:[1,0]
	global_store_dwordx2 v[204:205], v[198:199], off
	v_exp_f32_e32 v0, v0
	v_exp_f32_e32 v1, v1
	v_exp_f32_e32 v2, v2
	v_exp_f32_e32 v3, v3
	v_exp_f32_e32 v4, v4
	v_exp_f32_e32 v5, v5
	v_exp_f32_e32 v6, v6
	v_exp_f32_e32 v7, v7
	v_pk_add_f32 v[0:1], v[0:1], 1.0 op_sel_hi:[1,0]
	v_pk_add_f32 v[2:3], v[2:3], 1.0 op_sel_hi:[1,0]
	v_pk_add_f32 v[4:5], v[4:5], 1.0 op_sel_hi:[1,0]
	v_pk_add_f32 v[6:7], v[6:7], 1.0 op_sel_hi:[1,0]
	v_rcp_f32_e32 v0, v0
	v_rcp_f32_e32 v1, v1
	v_rcp_f32_e32 v2, v2
	v_rcp_f32_e32 v3, v3
	v_rcp_f32_e32 v4, v4
	v_rcp_f32_e32 v5, v5
	v_rcp_f32_e32 v6, v6
	v_rcp_f32_e32 v7, v7
	v_pk_fma_f32 v[0:1], v[0:1], s[14:15], 0.5 op_sel_hi:[1,0,0]
	v_pk_fma_f32 v[2:3], v[2:3], s[14:15], 0.5 op_sel_hi:[1,0,0]
	v_pk_fma_f32 v[4:5], v[4:5], s[14:15], 0.5 op_sel_hi:[1,0,0]
	v_pk_fma_f32 v[6:7], v[6:7], s[14:15], 0.5 op_sel_hi:[1,0,0]
	v_cvt_u32_f32_e32 v200, v4
	v_cvt_u32_f32_e32 v201, v0
	v_cvt_u32_f32_sdwa v200, v5 dst_sel:BYTE_1 dst_unused:UNUSED_PRESERVE src0_sel:DWORD
	v_cvt_u32_f32_sdwa v201, v1 dst_sel:BYTE_1 dst_unused:UNUSED_PRESERVE src0_sel:DWORD
	v_cvt_u32_f32_sdwa v200, v6 dst_sel:BYTE_2 dst_unused:UNUSED_PRESERVE src0_sel:DWORD
	v_cvt_u32_f32_sdwa v201, v2 dst_sel:BYTE_2 dst_unused:UNUSED_PRESERVE src0_sel:DWORD
	v_cvt_u32_f32_sdwa v200, v7 dst_sel:BYTE_3 dst_unused:UNUSED_PRESERVE src0_sel:DWORD
	v_cvt_u32_f32_sdwa v201, v3 dst_sel:BYTE_3 dst_unused:UNUSED_PRESERVE src0_sel:DWORD
	s_nop 0
	global_store_dwordx2 v[204:205], v[200:201], off offset:128
	s_andn2_b64 vcc, exec, s[22:23]
	s_mov_b64 s[22:23], -1
	s_cbranch_vccnz .LBB0_719
	s_andn2_b64 vcc, exec, s[4:5]
	s_cbranch_vccnz .LBB0_718
	s_barrier
	s_branch .LBB0_718

; __device__ __forceinline__ float sigmoidf_(float z) { return __builtin_amdgcn_rcpf(1.0f + __builtin_amdgcn_exp2f(-1.4426950408889634f * z)); }
;     __device__ __forceinline__ void load(Pre& p, const pg8::Unit& u, int ai, int m, int wr, int wc, int fr, int fq) const {
;         const int row = u.pm * 256 + ai * 128 + wr * 64 + m * 16 + fr;
;         if (MODE == EM_PROJ || MODE == EM_GATES) p.rs = ((const float*)(ws + WS_RINV0))[row];
;     __device__ __forceinline__ float compute(const Pre& p, f32x4 (&acc)[2][2][4][2], const f32x4 (&cv)[2][2], const pg8::Unit& u, int ai, int m, int wr, int wc, int fr, int fq) const {
;     ...
;             } else if (MODE == EM_GATES) {
;                 const int col = u.pn * 256 + ct; float w[8];
; #pragma unroll
;                 for (int j = 0; j < 8; ++j) w[j] = sigmoidf_(v[j] * rs) * 255.0f + 0.5f;
;                 u32x2 cd; cd.x = (unsigned)w[0] | ((unsigned)w[1] << 8) | ((unsigned)w[2] << 16) | ((unsigned)w[3] << 24); cd.y = (unsigned)w[4] | ((unsigned)w[5] << 8) | ((unsigned)w[6] << 16) | ((unsigned)w[7] << 24);
;                 *(u32x2*)(ws + WS_G8 + (size_t)row * 2048 + col) = cd;
.LBB0_807:
	v_lshl_add_u32 v162, s28, 8, v156
	v_ashrrev_i32_e32 v163, 31, v162
	v_lshl_add_u64 v[140:141], v[162:163], 2, s[12:13]
	global_load_dword v180, v[140:141], off
	v_or_b32_e32 v154, 16, v162
	v_or_b32_e32 v152, 32, v162
	v_or_b32_e32 v150, 48, v162
	v_add_u32_e32 v148, 0x80, v162
	v_add_u32_e32 v146, 0x90, v162
	v_add_u32_e32 v144, 0xa0, v162
	v_add_u32_e32 v142, 0xb0, v162
	v_ashrrev_i32_e32 v155, 31, v154
	v_ashrrev_i32_e32 v153, 31, v152
	v_ashrrev_i32_e32 v151, 31, v150
	v_ashrrev_i32_e32 v149, 31, v148
	v_ashrrev_i32_e32 v147, 31, v146
	v_ashrrev_i32_e32 v145, 31, v144
	v_ashrrev_i32_e32 v143, 31, v142
	v_lshlrev_b64 v[168:169], 11, v[162:163]
	v_lshl_add_u64 v[162:163], v[154:155], 2, s[12:13]
	v_lshl_add_u64 v[164:165], v[152:153], 2, s[12:13]
	v_lshl_add_u64 v[166:167], v[150:151], 2, s[12:13]
	v_lshl_add_u64 v[170:171], v[148:149], 2, s[12:13]
	v_lshl_add_u64 v[172:173], v[146:147], 2, s[12:13]
	v_lshl_add_u64 v[174:175], v[144:145], 2, s[12:13]
	v_lshl_add_u64 v[176:177], v[142:143], 2, s[12:13]
	global_load_dword v181, v[162:163], off
	global_load_dword v182, v[164:165], off
	s_nop 0
	global_load_dword v166, v[166:167], off
	s_nop 0
	global_load_dword v165, v[170:171], off
	global_load_dword v164, v[172:173], off
	global_load_dword v163, v[174:175], off
	global_load_dword v162, v[176:177], off
	v_lshl_or_b32 v140, s26, 8, v158
	v_ashrrev_i32_e32 v141, 31, v140
	v_lshl_add_u64 v[178:179], s[14:15], 0, v[168:169]
	v_lshl_add_u64 v[170:171], v[178:179], 0, v[140:141]
	s_mov_b32 s79, 0
	s_waitcnt vmcnt(7)
	v_mul_f32_e32 v172, 0xbfb8aa3b, v180
	v_pk_mul_f32 v[120:121], v[120:121], v[172:173] op_sel_hi:[1,0]
	v_pk_mul_f32 v[122:123], v[122:123], v[172:173] op_sel_hi:[1,0]
	v_pk_mul_f32 v[124:125], v[124:125], v[172:173] op_sel_hi:[1,0]
	v_pk_mul_f32 v[126:127], v[126:127], v[172:173] op_sel_hi:[1,0]
	v_exp_f32_e32 v120, v120
	v_exp_f32_e32 v121, v121
	v_exp_f32_e32 v122, v122
	v_exp_f32_e32 v123, v123
	v_exp_f32_e32 v124, v124
	v_exp_f32_e32 v125, v125
	v_exp_f32_e32 v126, v126
	v_exp_f32_e32 v127, v127
	v_pk_add_f32 v[120:121], v[120:121], 1.0 op_sel_hi:[1,0]
	v_pk_add_f32 v[122:123], v[122:123], 1.0 op_sel_hi:[1,0]
	v_pk_add_f32 v[124:125], v[124:125], 1.0 op_sel_hi:[1,0]
	v_pk_add_f32 v[126:127], v[126:127], 1.0 op_sel_hi:[1,0]
	v_rcp_f32_e32 v120, v120
	v_rcp_f32_e32 v121, v121
	v_rcp_f32_e32 v122, v122
	v_rcp_f32_e32 v123, v123
	v_rcp_f32_e32 v124, v124
	v_rcp_f32_e32 v125, v125
	v_rcp_f32_e32 v126, v126
	v_rcp_f32_e32 v127, v127
	v_pk_fma_f32 v[120:121], v[120:121], s[20:21], 0.5 op_sel_hi:[1,0,0]
	v_pk_fma_f32 v[122:123], v[122:123], s[20:21], 0.5 op_sel_hi:[1,0,0]
	v_pk_fma_f32 v[124:125], v[124:125], s[20:21], 0.5 op_sel_hi:[1,0,0]
	v_pk_fma_f32 v[126:127], v[126:127], s[20:21], 0.5 op_sel_hi:[1,0,0]
	v_cvt_u32_f32_e32 v192, v124
	v_cvt_u32_f32_e32 v193, v120
	v_cvt_u32_f32_sdwa v192, v125 dst_sel:BYTE_1 dst_unused:UNUSED_PRESERVE src0_sel:DWORD
	v_cvt_u32_f32_sdwa v193, v121 dst_sel:BYTE_1 dst_unused:UNUSED_PRESERVE src0_sel:DWORD
	v_cvt_u32_f32_sdwa v192, v126 dst_sel:BYTE_2 dst_unused:UNUSED_PRESERVE src0_sel:DWORD
	v_cvt_u32_f32_sdwa v193, v122 dst_sel:BYTE_2 dst_unused:UNUSED_PRESERVE src0_sel:DWORD
	v_cvt_u32_f32_sdwa v192, v127 dst_sel:BYTE_3 dst_unused:UNUSED_PRESERVE src0_sel:DWORD
	v_cvt_u32_f32_sdwa v193, v123 dst_sel:BYTE_3 dst_unused:UNUSED_PRESERVE src0_sel:DWORD
	v_pk_mul_f32 v[112:113], v[112:113], v[172:173] op_sel_hi:[1,0]
	v_pk_mul_f32 v[114:115], v[114:115], v[172:173] op_sel_hi:[1,0]
	v_pk_mul_f32 v[116:117], v[116:117], v[172:173] op_sel_hi:[1,0]
	v_pk_mul_f32 v[118:119], v[118:119], v[172:173] op_sel_hi:[1,0]
	global_store_dwordx2 v[170:171], v[192:193], off
	v_exp_f32_e32 v112, v112
	v_exp_f32_e32 v113, v113
	v_exp_f32_e32 v114, v114
	v_exp_f32_e32 v115, v115
	v_exp_f32_e32 v116, v116
	v_exp_f32_e32 v117, v117
	v_exp_f32_e32 v118, v118
	v_exp_f32_e32 v119, v119
	v_pk_add_f32 v[112:113], v[112:113], 1.0 op_sel_hi:[1,0]
	v_pk_add_f32 v[114:115], v[114:115], 1.0 op_sel_hi:[1,0]
	v_pk_add_f32 v[116:117], v[116:117], 1.0 op_sel_hi:[1,0]
	v_pk_add_f32 v[118:119], v[118:119], 1.0 op_sel_hi:[1,0]
	v_rcp_f32_e32 v112, v112
	v_rcp_f32_e32 v113, v113
	v_rcp_f32_e32 v114, v114
	v_rcp_f32_e32 v115, v115
	v_rcp_f32_e32 v116, v116
	v_rcp_f32_e32 v117, v117
	v_rcp_f32_e32 v118, v118
	v_rcp_f32_e32 v119, v119
	v_pk_fma_f32 v[112:113], v[112:113], s[20:21], 0.5 op_sel_hi:[1,0,0]
	v_pk_fma_f32 v[114:115], v[114:115], s[20:21], 0.5 op_sel_hi:[1,0,0]
	v_pk_fma_f32 v[116:117], v[116:117], s[20:21], 0.5 op_sel_hi:[1,0,0]
	v_pk_fma_f32 v[118:119], v[118:119], s[20:21], 0.5 op_sel_hi:[1,0,0]
	v_cvt_u32_f32_e32 v194, v116
	v_cvt_u32_f32_e32 v195, v112
	v_cvt_u32_f32_sdwa v194, v117 dst_sel:BYTE_1 dst_unused:UNUSED_PRESERVE src0_sel:DWORD
	v_cvt_u32_f32_sdwa v195, v113 dst_sel:BYTE_1 dst_unused:UNUSED_PRESERVE src0_sel:DWORD
	v_cvt_u32_f32_sdwa v194, v118 dst_sel:BYTE_2 dst_unused:UNUSED_PRESERVE src0_sel:DWORD
	v_cvt_u32_f32_sdwa v195, v114 dst_sel:BYTE_2 dst_unused:UNUSED_PRESERVE src0_sel:DWORD
	v_cvt_u32_f32_sdwa v194, v119 dst_sel:BYTE_3 dst_unused:UNUSED_PRESERVE src0_sel:DWORD
	v_cvt_u32_f32_sdwa v195, v115 dst_sel:BYTE_3 dst_unused:UNUSED_PRESERVE src0_sel:DWORD
	s_waitcnt vmcnt(7)
; __device__ __forceinline__ float sigmoidf_(float z) { return __builtin_amdgcn_rcpf(1.0f + __builtin_amdgcn_exp2f(-1.4426950408889634f * z)); }
;     __device__ __forceinline__ float compute(const Pre& p, f32x4 (&acc)[2][2][4][2], const f32x4 (&cv)[2][2], const pg8::Unit& u, int ai, int m, int wr, int wc, int fr, int fq) const {
;     ...
;             } else if (MODE == EM_GATES) {
;                 const int col = u.pn * 256 + ct; float w[8];
; #pragma unroll
;                 for (int j = 0; j < 8; ++j) w[j] = sigmoidf_(v[j] * rs) * 255.0f + 0.5f;
;                 u32x2 cd; cd.x = (unsigned)w[0] | ((unsigned)w[1] << 8) | ((unsigned)w[2] << 16) | ((unsigned)w[3] << 24); cd.y = (unsigned)w[4] | ((unsigned)w[5] << 8) | ((unsigned)w[6] << 16) | ((unsigned)w[7] << 24);
;                 *(u32x2*)(ws + WS_G8 + (size_t)row * 2048 + col) = cd;
	v_mul_f32_e32 v174, 0xbfb8aa3b, v181
	s_mov_b32 s78, 0x8000
	v_lshl_add_u64 v[202:203], v[170:171], 0, s[78:79]
	v_pk_mul_f32 v[104:105], v[104:105], v[174:175] op_sel_hi:[1,0]
	v_pk_mul_f32 v[106:107], v[106:107], v[174:175] op_sel_hi:[1,0]
	v_pk_mul_f32 v[108:109], v[108:109], v[174:175] op_sel_hi:[1,0]
	v_pk_mul_f32 v[110:111], v[110:111], v[174:175] op_sel_hi:[1,0]
	global_store_dwordx2 v[170:171], v[194:195], off offset:128
	v_exp_f32_e32 v104, v104
	v_exp_f32_e32 v105, v105
	v_exp_f32_e32 v106, v106
	v_exp_f32_e32 v107, v107
	v_exp_f32_e32 v108, v108
	v_exp_f32_e32 v109, v109
	v_exp_f32_e32 v110, v110
	v_exp_f32_e32 v111, v111
	v_pk_add_f32 v[104:105], v[104:105], 1.0 op_sel_hi:[1,0]
	v_pk_add_f32 v[106:107], v[106:107], 1.0 op_sel_hi:[1,0]
	v_pk_add_f32 v[108:109], v[108:109], 1.0 op_sel_hi:[1,0]
	v_pk_add_f32 v[110:111], v[110:111], 1.0 op_sel_hi:[1,0]
	v_rcp_f32_e32 v104, v104
	v_rcp_f32_e32 v105, v105
	v_rcp_f32_e32 v106, v106
	v_rcp_f32_e32 v107, v107
	v_rcp_f32_e32 v108, v108
	v_rcp_f32_e32 v109, v109
	v_rcp_f32_e32 v110, v110
	v_rcp_f32_e32 v111, v111
	v_pk_fma_f32 v[104:105], v[104:105], s[20:21], 0.5 op_sel_hi:[1,0,0]
	v_pk_fma_f32 v[106:107], v[106:107], s[20:21], 0.5 op_sel_hi:[1,0,0]
	v_pk_fma_f32 v[108:109], v[108:109], s[20:21], 0.5 op_sel_hi:[1,0,0]
	v_pk_fma_f32 v[110:111], v[110:111], s[20:21], 0.5 op_sel_hi:[1,0,0]
	v_cvt_u32_f32_e32 v196, v108
	v_cvt_u32_f32_e32 v197, v104
	v_cvt_u32_f32_sdwa v196, v109 dst_sel:BYTE_1 dst_unused:UNUSED_PRESERVE src0_sel:DWORD
	v_cvt_u32_f32_sdwa v197, v105 dst_sel:BYTE_1 dst_unused:UNUSED_PRESERVE src0_sel:DWORD
	v_cvt_u32_f32_sdwa v196, v110 dst_sel:BYTE_2 dst_unused:UNUSED_PRESERVE src0_sel:DWORD
	v_cvt_u32_f32_sdwa v197, v106 dst_sel:BYTE_2 dst_unused:UNUSED_PRESERVE src0_sel:DWORD
	v_cvt_u32_f32_sdwa v196, v111 dst_sel:BYTE_3 dst_unused:UNUSED_PRESERVE src0_sel:DWORD
	v_cvt_u32_f32_sdwa v197, v107 dst_sel:BYTE_3 dst_unused:UNUSED_PRESERVE src0_sel:DWORD
	v_pk_mul_f32 v[96:97], v[96:97], v[174:175] op_sel_hi:[1,0]
	v_pk_mul_f32 v[98:99], v[98:99], v[174:175] op_sel_hi:[1,0]
	v_pk_mul_f32 v[100:101], v[100:101], v[174:175] op_sel_hi:[1,0]
	v_pk_mul_f32 v[102:103], v[102:103], v[174:175] op_sel_hi:[1,0]
	global_store_dwordx2 v[202:203], v[196:197], off
	v_exp_f32_e32 v96, v96
	v_exp_f32_e32 v97, v97
	v_exp_f32_e32 v98, v98
	v_exp_f32_e32 v99, v99
	v_exp_f32_e32 v100, v100
	v_exp_f32_e32 v101, v101
	v_exp_f32_e32 v102, v102
	v_exp_f32_e32 v103, v103
	v_pk_add_f32 v[96:97], v[96:97], 1.0 op_sel_hi:[1,0]
	v_pk_add_f32 v[98:99], v[98:99], 1.0 op_sel_hi:[1,0]
	v_pk_add_f32 v[100:101], v[100:101], 1.0 op_sel_hi:[1,0]
	v_pk_add_f32 v[102:103], v[102:103], 1.0 op_sel_hi:[1,0]
	v_rcp_f32_e32 v96, v96
	v_rcp_f32_e32 v97, v97
	v_rcp_f32_e32 v98, v98
	v_rcp_f32_e32 v99, v99
	v_rcp_f32_e32 v100, v100
	v_rcp_f32_e32 v101, v101
	v_rcp_f32_e32 v102, v102
	v_rcp_f32_e32 v103, v103
	v_pk_fma_f32 v[96:97], v[96:97], s[20:21], 0.5 op_sel_hi:[1,0,0]
	v_pk_fma_f32 v[98:99], v[98:99], s[20:21], 0.5 op_sel_hi:[1,0,0]
	v_pk_fma_f32 v[100:101], v[100:101], s[20:21], 0.5 op_sel_hi:[1,0,0]
	v_pk_fma_f32 v[102:103], v[102:103], s[20:21], 0.5 op_sel_hi:[1,0,0]
	v_cvt_u32_f32_e32 v198, v100
	v_cvt_u32_f32_e32 v199, v96
	v_cvt_u32_f32_sdwa v198, v101 dst_sel:BYTE_1 dst_unused:UNUSED_PRESERVE src0_sel:DWORD
	v_cvt_u32_f32_sdwa v199, v97 dst_sel:BYTE_1 dst_unused:UNUSED_PRESERVE src0_sel:DWORD
	v_cvt_u32_f32_sdwa v198, v102 dst_sel:BYTE_2 dst_unused:UNUSED_PRESERVE src0_sel:DWORD
	v_cvt_u32_f32_sdwa v199, v98 dst_sel:BYTE_2 dst_unused:UNUSED_PRESERVE src0_sel:DWORD
	v_cvt_u32_f32_sdwa v198, v103 dst_sel:BYTE_3 dst_unused:UNUSED_PRESERVE src0_sel:DWORD
	v_cvt_u32_f32_sdwa v199, v99 dst_sel:BYTE_3 dst_unused:UNUSED_PRESERVE src0_sel:DWORD
	s_waitcnt vmcnt(8)
	v_mul_f32_e32 v176, 0xbfb8aa3b, v182
	s_mov_b32 s78, 0x10000
	v_lshl_add_u64 v[200:201], v[170:171], 0, s[78:79]
	v_pk_mul_f32 v[88:89], v[88:89], v[176:177] op_sel_hi:[1,0]
	v_pk_mul_f32 v[90:91], v[90:91], v[176:177] op_sel_hi:[1,0]
	v_pk_mul_f32 v[92:93], v[92:93], v[176:177] op_sel_hi:[1,0]
	v_pk_mul_f32 v[94:95], v[94:95], v[176:177] op_sel_hi:[1,0]
	global_store_dwordx2 v[202:203], v[198:199], off offset:128
	v_exp_f32_e32 v88, v88
	v_exp_f32_e32 v89, v89
	v_exp_f32_e32 v90, v90
	v_exp_f32_e32 v91, v91
	v_exp_f32_e32 v92, v92
	v_exp_f32_e32 v93, v93
	v_exp_f32_e32 v94, v94
	v_exp_f32_e32 v95, v95
	v_pk_add_f32 v[88:89], v[88:89], 1.0 op_sel_hi:[1,0]
	v_pk_add_f32 v[90:91], v[90:91], 1.0 op_sel_hi:[1,0]
	v_pk_add_f32 v[92:93], v[92:93], 1.0 op_sel_hi:[1,0]
	v_pk_add_f32 v[94:95], v[94:95], 1.0 op_sel_hi:[1,0]
	v_rcp_f32_e32 v88, v88
	v_rcp_f32_e32 v89, v89
	v_rcp_f32_e32 v90, v90
	v_rcp_f32_e32 v91, v91
	v_rcp_f32_e32 v92, v92
	v_rcp_f32_e32 v93, v93
	v_rcp_f32_e32 v94, v94
	v_rcp_f32_e32 v95, v95
	v_pk_fma_f32 v[88:89], v[88:89], s[20:21], 0.5 op_sel_hi:[1,0,0]
	v_pk_fma_f32 v[90:91], v[90:91], s[20:21], 0.5 op_sel_hi:[1,0,0]
	v_pk_fma_f32 v[92:93], v[92:93], s[20:21], 0.5 op_sel_hi:[1,0,0]
	v_pk_fma_f32 v[94:95], v[94:95], s[20:21], 0.5 op_sel_hi:[1,0,0]
	v_cvt_u32_f32_e32 v192, v92
	v_cvt_u32_f32_e32 v193, v88
	v_cvt_u32_f32_sdwa v192, v93 dst_sel:BYTE_1 dst_unused:UNUSED_PRESERVE src0_sel:DWORD
	v_cvt_u32_f32_sdwa v193, v89 dst_sel:BYTE_1 dst_unused:UNUSED_PRESERVE src0_sel:DWORD
	v_cvt_u32_f32_sdwa v192, v94 dst_sel:BYTE_2 dst_unused:UNUSED_PRESERVE src0_sel:DWORD
	v_cvt_u32_f32_sdwa v193, v90 dst_sel:BYTE_2 dst_unused:UNUSED_PRESERVE src0_sel:DWORD
	v_cvt_u32_f32_sdwa v192, v95 dst_sel:BYTE_3 dst_unused:UNUSED_PRESERVE src0_sel:DWORD
	v_cvt_u32_f32_sdwa v193, v91 dst_sel:BYTE_3 dst_unused:UNUSED_PRESERVE src0_sel:DWORD
; __device__ __forceinline__ float sigmoidf_(float z) { return __builtin_amdgcn_rcpf(1.0f + __builtin_amdgcn_exp2f(-1.4426950408889634f * z)); }
;     __device__ __forceinline__ float compute(const Pre& p, f32x4 (&acc)[2][2][4][2], const f32x4 (&cv)[2][2], const pg8::Unit& u, int ai, int m, int wr, int wc, int fr, int fq) const {
;     ...
;             } else if (MODE == EM_GATES) {
;                 const int col = u.pn * 256 + ct; float w[8];
; #pragma unroll
;                 for (int j = 0; j < 8; ++j) w[j] = sigmoidf_(v[j] * rs) * 255.0f + 0.5f;
;                 u32x2 cd; cd.x = (unsigned)w[0] | ((unsigned)w[1] << 8) | ((unsigned)w[2] << 16) | ((unsigned)w[3] << 24); cd.y = (unsigned)w[4] | ((unsigned)w[5] << 8) | ((unsigned)w[6] << 16) | ((unsigned)w[7] << 24);
;                 *(u32x2*)(ws + WS_G8 + (size_t)row * 2048 + col) = cd;
	v_pk_mul_f32 v[80:81], v[80:81], v[176:177] op_sel_hi:[1,0]
	v_pk_mul_f32 v[82:83], v[82:83], v[176:177] op_sel_hi:[1,0]
	v_pk_mul_f32 v[84:85], v[84:85], v[176:177] op_sel_hi:[1,0]
	v_pk_mul_f32 v[86:87], v[86:87], v[176:177] op_sel_hi:[1,0]
	global_store_dwordx2 v[200:201], v[192:193], off
	v_exp_f32_e32 v80, v80
	v_exp_f32_e32 v81, v81
	v_exp_f32_e32 v82, v82
	v_exp_f32_e32 v83, v83
	v_exp_f32_e32 v84, v84
	v_exp_f32_e32 v85, v85
	v_exp_f32_e32 v86, v86
	v_exp_f32_e32 v87, v87
	v_pk_add_f32 v[80:81], v[80:81], 1.0 op_sel_hi:[1,0]
	v_pk_add_f32 v[82:83], v[82:83], 1.0 op_sel_hi:[1,0]
	v_pk_add_f32 v[84:85], v[84:85], 1.0 op_sel_hi:[1,0]
	v_pk_add_f32 v[86:87], v[86:87], 1.0 op_sel_hi:[1,0]
	v_rcp_f32_e32 v80, v80
	v_rcp_f32_e32 v81, v81
	v_rcp_f32_e32 v82, v82
	v_rcp_f32_e32 v83, v83
	v_rcp_f32_e32 v84, v84
	v_rcp_f32_e32 v85, v85
	v_rcp_f32_e32 v86, v86
	v_rcp_f32_e32 v87, v87
	v_pk_fma_f32 v[80:81], v[80:81], s[20:21], 0.5 op_sel_hi:[1,0,0]
	v_pk_fma_f32 v[82:83], v[82:83], s[20:21], 0.5 op_sel_hi:[1,0,0]
	v_pk_fma_f32 v[84:85], v[84:85], s[20:21], 0.5 op_sel_hi:[1,0,0]
	v_pk_fma_f32 v[86:87], v[86:87], s[20:21], 0.5 op_sel_hi:[1,0,0]
	v_cvt_u32_f32_e32 v194, v84
	v_cvt_u32_f32_e32 v195, v80
	v_cvt_u32_f32_sdwa v194, v85 dst_sel:BYTE_1 dst_unused:UNUSED_PRESERVE src0_sel:DWORD
	v_cvt_u32_f32_sdwa v195, v81 dst_sel:BYTE_1 dst_unused:UNUSED_PRESERVE src0_sel:DWORD
	v_cvt_u32_f32_sdwa v194, v86 dst_sel:BYTE_2 dst_unused:UNUSED_PRESERVE src0_sel:DWORD
	v_cvt_u32_f32_sdwa v195, v82 dst_sel:BYTE_2 dst_unused:UNUSED_PRESERVE src0_sel:DWORD
	v_cvt_u32_f32_sdwa v194, v87 dst_sel:BYTE_3 dst_unused:UNUSED_PRESERVE src0_sel:DWORD
	v_cvt_u32_f32_sdwa v195, v83 dst_sel:BYTE_3 dst_unused:UNUSED_PRESERVE src0_sel:DWORD
	s_waitcnt vmcnt(9)
	v_mul_f32_e32 v178, 0xbfb8aa3b, v166
	s_mov_b32 s78, 0x18000
	v_lshl_add_u64 v[202:203], v[170:171], 0, s[78:79]
	v_pk_mul_f32 v[72:73], v[72:73], v[178:179] op_sel_hi:[1,0]
	v_pk_mul_f32 v[74:75], v[74:75], v[178:179] op_sel_hi:[1,0]
	v_pk_mul_f32 v[76:77], v[76:77], v[178:179] op_sel_hi:[1,0]
	v_pk_mul_f32 v[78:79], v[78:79], v[178:179] op_sel_hi:[1,0]
	global_store_dwordx2 v[200:201], v[194:195], off offset:128
	v_exp_f32_e32 v72, v72
	v_exp_f32_e32 v73, v73
	v_exp_f32_e32 v74, v74
	v_exp_f32_e32 v75, v75
	v_exp_f32_e32 v76, v76
	v_exp_f32_e32 v77, v77
	v_exp_f32_e32 v78, v78
	v_exp_f32_e32 v79, v79
	v_pk_add_f32 v[72:73], v[72:73], 1.0 op_sel_hi:[1,0]
	v_pk_add_f32 v[74:75], v[74:75], 1.0 op_sel_hi:[1,0]
	v_pk_add_f32 v[76:77], v[76:77], 1.0 op_sel_hi:[1,0]
	v_pk_add_f32 v[78:79], v[78:79], 1.0 op_sel_hi:[1,0]
	v_rcp_f32_e32 v72, v72
	v_rcp_f32_e32 v73, v73
	v_rcp_f32_e32 v74, v74
	v_rcp_f32_e32 v75, v75
	v_rcp_f32_e32 v76, v76
	v_rcp_f32_e32 v77, v77
	v_rcp_f32_e32 v78, v78
	v_rcp_f32_e32 v79, v79
	v_pk_fma_f32 v[72:73], v[72:73], s[20:21], 0.5 op_sel_hi:[1,0,0]
	v_pk_fma_f32 v[74:75], v[74:75], s[20:21], 0.5 op_sel_hi:[1,0,0]
	v_pk_fma_f32 v[76:77], v[76:77], s[20:21], 0.5 op_sel_hi:[1,0,0]
	v_pk_fma_f32 v[78:79], v[78:79], s[20:21], 0.5 op_sel_hi:[1,0,0]
	v_cvt_u32_f32_e32 v196, v76
	v_cvt_u32_f32_e32 v197, v72
	v_cvt_u32_f32_sdwa v196, v77 dst_sel:BYTE_1 dst_unused:UNUSED_PRESERVE src0_sel:DWORD
	v_cvt_u32_f32_sdwa v197, v73 dst_sel:BYTE_1 dst_unused:UNUSED_PRESERVE src0_sel:DWORD
	v_cvt_u32_f32_sdwa v196, v78 dst_sel:BYTE_2 dst_unused:UNUSED_PRESERVE src0_sel:DWORD
	v_cvt_u32_f32_sdwa v197, v74 dst_sel:BYTE_2 dst_unused:UNUSED_PRESERVE src0_sel:DWORD
	v_cvt_u32_f32_sdwa v196, v79 dst_sel:BYTE_3 dst_unused:UNUSED_PRESERVE src0_sel:DWORD
	v_cvt_u32_f32_sdwa v197, v75 dst_sel:BYTE_3 dst_unused:UNUSED_PRESERVE src0_sel:DWORD
	v_pk_mul_f32 v[64:65], v[64:65], v[178:179] op_sel_hi:[1,0]
	v_pk_mul_f32 v[66:67], v[66:67], v[178:179] op_sel_hi:[1,0]
	v_pk_mul_f32 v[68:69], v[68:69], v[178:179] op_sel_hi:[1,0]
	v_pk_mul_f32 v[70:71], v[70:71], v[178:179] op_sel_hi:[1,0]
	global_store_dwordx2 v[202:203], v[196:197], off
	v_exp_f32_e32 v64, v64
	v_exp_f32_e32 v65, v65
	v_exp_f32_e32 v66, v66
	v_exp_f32_e32 v67, v67
	v_exp_f32_e32 v68, v68
	v_exp_f32_e32 v69, v69
	v_exp_f32_e32 v70, v70
	v_exp_f32_e32 v71, v71
	v_pk_add_f32 v[64:65], v[64:65], 1.0 op_sel_hi:[1,0]
	v_pk_add_f32 v[66:67], v[66:67], 1.0 op_sel_hi:[1,0]
	v_pk_add_f32 v[68:69], v[68:69], 1.0 op_sel_hi:[1,0]
	v_pk_add_f32 v[70:71], v[70:71], 1.0 op_sel_hi:[1,0]
	v_rcp_f32_e32 v64, v64
	v_rcp_f32_e32 v65, v65
	v_rcp_f32_e32 v66, v66
	v_rcp_f32_e32 v67, v67
	v_rcp_f32_e32 v68, v68
	v_rcp_f32_e32 v69, v69
	v_rcp_f32_e32 v70, v70
	v_rcp_f32_e32 v71, v71
	v_pk_fma_f32 v[64:65], v[64:65], s[20:21], 0.5 op_sel_hi:[1,0,0]
	v_pk_fma_f32 v[66:67], v[66:67], s[20:21], 0.5 op_sel_hi:[1,0,0]
	v_pk_fma_f32 v[68:69], v[68:69], s[20:21], 0.5 op_sel_hi:[1,0,0]
	v_pk_fma_f32 v[70:71], v[70:71], s[20:21], 0.5 op_sel_hi:[1,0,0]
	v_cvt_u32_f32_e32 v198, v68
	v_cvt_u32_f32_e32 v199, v64
	v_cvt_u32_f32_sdwa v198, v69 dst_sel:BYTE_1 dst_unused:UNUSED_PRESERVE src0_sel:DWORD
	v_cvt_u32_f32_sdwa v199, v65 dst_sel:BYTE_1 dst_unused:UNUSED_PRESERVE src0_sel:DWORD
	v_cvt_u32_f32_sdwa v198, v70 dst_sel:BYTE_2 dst_unused:UNUSED_PRESERVE src0_sel:DWORD
	v_cvt_u32_f32_sdwa v199, v66 dst_sel:BYTE_2 dst_unused:UNUSED_PRESERVE src0_sel:DWORD
	v_cvt_u32_f32_sdwa v198, v71 dst_sel:BYTE_3 dst_unused:UNUSED_PRESERVE src0_sel:DWORD
	v_cvt_u32_f32_sdwa v199, v67 dst_sel:BYTE_3 dst_unused:UNUSED_PRESERVE src0_sel:DWORD
	s_waitcnt vmcnt(10)
; __device__ __forceinline__ float sigmoidf_(float z) { return __builtin_amdgcn_rcpf(1.0f + __builtin_amdgcn_exp2f(-1.4426950408889634f * z)); }
;     __device__ __forceinline__ float compute(const Pre& p, f32x4 (&acc)[2][2][4][2], const f32x4 (&cv)[2][2], const pg8::Unit& u, int ai, int m, int wr, int wc, int fr, int fq) const {
;     ...
;             } else if (MODE == EM_GATES) {
;                 const int col = u.pn * 256 + ct; float w[8];
; #pragma unroll
;                 for (int j = 0; j < 8; ++j) w[j] = sigmoidf_(v[j] * rs) * 255.0f + 0.5f;
;                 u32x2 cd; cd.x = (unsigned)w[0] | ((unsigned)w[1] << 8) | ((unsigned)w[2] << 16) | ((unsigned)w[3] << 24); cd.y = (unsigned)w[4] | ((unsigned)w[5] << 8) | ((unsigned)w[6] << 16) | ((unsigned)w[7] << 24);
;                 *(u32x2*)(ws + WS_G8 + (size_t)row * 2048 + col) = cd;
	v_mul_f32_e32 v184, 0xbfb8aa3b, v165
	s_mov_b32 s78, 0x40000
	v_lshl_add_u64 v[200:201], v[170:171], 0, s[78:79]
	v_pk_mul_f32 v[56:57], v[56:57], v[184:185] op_sel_hi:[1,0]
	v_pk_mul_f32 v[58:59], v[58:59], v[184:185] op_sel_hi:[1,0]
	v_pk_mul_f32 v[60:61], v[60:61], v[184:185] op_sel_hi:[1,0]
	v_pk_mul_f32 v[62:63], v[62:63], v[184:185] op_sel_hi:[1,0]
	global_store_dwordx2 v[202:203], v[198:199], off offset:128
	v_exp_f32_e32 v56, v56
	v_exp_f32_e32 v57, v57
	v_exp_f32_e32 v58, v58
	v_exp_f32_e32 v59, v59
	v_exp_f32_e32 v60, v60
	v_exp_f32_e32 v61, v61
	v_exp_f32_e32 v62, v62
	v_exp_f32_e32 v63, v63
	v_pk_add_f32 v[56:57], v[56:57], 1.0 op_sel_hi:[1,0]
	v_pk_add_f32 v[58:59], v[58:59], 1.0 op_sel_hi:[1,0]
	v_pk_add_f32 v[60:61], v[60:61], 1.0 op_sel_hi:[1,0]
	v_pk_add_f32 v[62:63], v[62:63], 1.0 op_sel_hi:[1,0]
	v_rcp_f32_e32 v56, v56
	v_rcp_f32_e32 v57, v57
	v_rcp_f32_e32 v58, v58
	v_rcp_f32_e32 v59, v59
	v_rcp_f32_e32 v60, v60
	v_rcp_f32_e32 v61, v61
	v_rcp_f32_e32 v62, v62
	v_rcp_f32_e32 v63, v63
	v_pk_fma_f32 v[56:57], v[56:57], s[20:21], 0.5 op_sel_hi:[1,0,0]
	v_pk_fma_f32 v[58:59], v[58:59], s[20:21], 0.5 op_sel_hi:[1,0,0]
	v_pk_fma_f32 v[60:61], v[60:61], s[20:21], 0.5 op_sel_hi:[1,0,0]
	v_pk_fma_f32 v[62:63], v[62:63], s[20:21], 0.5 op_sel_hi:[1,0,0]
	v_cvt_u32_f32_e32 v192, v60
	v_cvt_u32_f32_e32 v193, v56
	v_cvt_u32_f32_sdwa v192, v61 dst_sel:BYTE_1 dst_unused:UNUSED_PRESERVE src0_sel:DWORD
	v_cvt_u32_f32_sdwa v193, v57 dst_sel:BYTE_1 dst_unused:UNUSED_PRESERVE src0_sel:DWORD
	v_cvt_u32_f32_sdwa v192, v62 dst_sel:BYTE_2 dst_unused:UNUSED_PRESERVE src0_sel:DWORD
	v_cvt_u32_f32_sdwa v193, v58 dst_sel:BYTE_2 dst_unused:UNUSED_PRESERVE src0_sel:DWORD
	v_cvt_u32_f32_sdwa v192, v63 dst_sel:BYTE_3 dst_unused:UNUSED_PRESERVE src0_sel:DWORD
	v_cvt_u32_f32_sdwa v193, v59 dst_sel:BYTE_3 dst_unused:UNUSED_PRESERVE src0_sel:DWORD
	v_pk_mul_f32 v[48:49], v[48:49], v[184:185] op_sel_hi:[1,0]
	v_pk_mul_f32 v[50:51], v[50:51], v[184:185] op_sel_hi:[1,0]
	v_pk_mul_f32 v[52:53], v[52:53], v[184:185] op_sel_hi:[1,0]
	v_pk_mul_f32 v[54:55], v[54:55], v[184:185] op_sel_hi:[1,0]
	global_store_dwordx2 v[200:201], v[192:193], off
	v_exp_f32_e32 v48, v48
	v_exp_f32_e32 v49, v49
	v_exp_f32_e32 v50, v50
	v_exp_f32_e32 v51, v51
	v_exp_f32_e32 v52, v52
	v_exp_f32_e32 v53, v53
	v_exp_f32_e32 v54, v54
	v_exp_f32_e32 v55, v55
	v_pk_add_f32 v[48:49], v[48:49], 1.0 op_sel_hi:[1,0]
	v_pk_add_f32 v[50:51], v[50:51], 1.0 op_sel_hi:[1,0]
	v_pk_add_f32 v[52:53], v[52:53], 1.0 op_sel_hi:[1,0]
	v_pk_add_f32 v[54:55], v[54:55], 1.0 op_sel_hi:[1,0]
	v_rcp_f32_e32 v48, v48
	v_rcp_f32_e32 v49, v49
	v_rcp_f32_e32 v50, v50
	v_rcp_f32_e32 v51, v51
	v_rcp_f32_e32 v52, v52
	v_rcp_f32_e32 v53, v53
	v_rcp_f32_e32 v54, v54
	v_rcp_f32_e32 v55, v55
	v_pk_fma_f32 v[48:49], v[48:49], s[20:21], 0.5 op_sel_hi:[1,0,0]
	v_pk_fma_f32 v[50:51], v[50:51], s[20:21], 0.5 op_sel_hi:[1,0,0]
	v_pk_fma_f32 v[52:53], v[52:53], s[20:21], 0.5 op_sel_hi:[1,0,0]
	v_pk_fma_f32 v[54:55], v[54:55], s[20:21], 0.5 op_sel_hi:[1,0,0]
	v_cvt_u32_f32_e32 v194, v52
	v_cvt_u32_f32_e32 v195, v48
	v_cvt_u32_f32_sdwa v194, v53 dst_sel:BYTE_1 dst_unused:UNUSED_PRESERVE src0_sel:DWORD
	v_cvt_u32_f32_sdwa v195, v49 dst_sel:BYTE_1 dst_unused:UNUSED_PRESERVE src0_sel:DWORD
	v_cvt_u32_f32_sdwa v194, v54 dst_sel:BYTE_2 dst_unused:UNUSED_PRESERVE src0_sel:DWORD
	v_cvt_u32_f32_sdwa v195, v50 dst_sel:BYTE_2 dst_unused:UNUSED_PRESERVE src0_sel:DWORD
	v_cvt_u32_f32_sdwa v194, v55 dst_sel:BYTE_3 dst_unused:UNUSED_PRESERVE src0_sel:DWORD
	v_cvt_u32_f32_sdwa v195, v51 dst_sel:BYTE_3 dst_unused:UNUSED_PRESERVE src0_sel:DWORD
	s_waitcnt vmcnt(11)
	v_mul_f32_e32 v186, 0xbfb8aa3b, v164
	s_mov_b32 s78, 0x48000
	v_lshl_add_u64 v[202:203], v[170:171], 0, s[78:79]
	v_pk_mul_f32 v[40:41], v[40:41], v[186:187] op_sel_hi:[1,0]
	v_pk_mul_f32 v[42:43], v[42:43], v[186:187] op_sel_hi:[1,0]
	v_pk_mul_f32 v[44:45], v[44:45], v[186:187] op_sel_hi:[1,0]
	v_pk_mul_f32 v[46:47], v[46:47], v[186:187] op_sel_hi:[1,0]
	global_store_dwordx2 v[200:201], v[194:195], off offset:128
	v_exp_f32_e32 v40, v40
	v_exp_f32_e32 v41, v41
	v_exp_f32_e32 v42, v42
	v_exp_f32_e32 v43, v43
	v_exp_f32_e32 v44, v44
	v_exp_f32_e32 v45, v45
	v_exp_f32_e32 v46, v46
	v_exp_f32_e32 v47, v47
	v_pk_add_f32 v[40:41], v[40:41], 1.0 op_sel_hi:[1,0]
	v_pk_add_f32 v[42:43], v[42:43], 1.0 op_sel_hi:[1,0]
	v_pk_add_f32 v[44:45], v[44:45], 1.0 op_sel_hi:[1,0]
	v_pk_add_f32 v[46:47], v[46:47], 1.0 op_sel_hi:[1,0]
	v_rcp_f32_e32 v40, v40
	v_rcp_f32_e32 v41, v41
	v_rcp_f32_e32 v42, v42
	v_rcp_f32_e32 v43, v43
	v_rcp_f32_e32 v44, v44
	v_rcp_f32_e32 v45, v45
	v_rcp_f32_e32 v46, v46
	v_rcp_f32_e32 v47, v47
	v_pk_fma_f32 v[40:41], v[40:41], s[20:21], 0.5 op_sel_hi:[1,0,0]
	v_pk_fma_f32 v[42:43], v[42:43], s[20:21], 0.5 op_sel_hi:[1,0,0]
	v_pk_fma_f32 v[44:45], v[44:45], s[20:21], 0.5 op_sel_hi:[1,0,0]
	v_pk_fma_f32 v[46:47], v[46:47], s[20:21], 0.5 op_sel_hi:[1,0,0]
	v_cvt_u32_f32_e32 v196, v44
	v_cvt_u32_f32_e32 v197, v40
	v_cvt_u32_f32_sdwa v196, v45 dst_sel:BYTE_1 dst_unused:UNUSED_PRESERVE src0_sel:DWORD
	v_cvt_u32_f32_sdwa v197, v41 dst_sel:BYTE_1 dst_unused:UNUSED_PRESERVE src0_sel:DWORD
	v_cvt_u32_f32_sdwa v196, v46 dst_sel:BYTE_2 dst_unused:UNUSED_PRESERVE src0_sel:DWORD
	v_cvt_u32_f32_sdwa v197, v42 dst_sel:BYTE_2 dst_unused:UNUSED_PRESERVE src0_sel:DWORD
	v_cvt_u32_f32_sdwa v196, v47 dst_sel:BYTE_3 dst_unused:UNUSED_PRESERVE src0_sel:DWORD
	v_cvt_u32_f32_sdwa v197, v43 dst_sel:BYTE_3 dst_unused:UNUSED_PRESERVE src0_sel:DWORD
	v_pk_mul_f32 v[32:33], v[32:33], v[186:187] op_sel_hi:[1,0]
	v_pk_mul_f32 v[34:35], v[34:35], v[186:187] op_sel_hi:[1,0]
	v_pk_mul_f32 v[36:37], v[36:37], v[186:187] op_sel_hi:[1,0]
; __device__ __forceinline__ float sigmoidf_(float z) { return __builtin_amdgcn_rcpf(1.0f + __builtin_amdgcn_exp2f(-1.4426950408889634f * z)); }
;     __device__ __forceinline__ float compute(const Pre& p, f32x4 (&acc)[2][2][4][2], const f32x4 (&cv)[2][2], const pg8::Unit& u, int ai, int m, int wr, int wc, int fr, int fq) const {
;     ...
;             } else if (MODE == EM_GATES) {
;                 const int col = u.pn * 256 + ct; float w[8];
; #pragma unroll
;                 for (int j = 0; j < 8; ++j) w[j] = sigmoidf_(v[j] * rs) * 255.0f + 0.5f;
;                 u32x2 cd; cd.x = (unsigned)w[0] | ((unsigned)w[1] << 8) | ((unsigned)w[2] << 16) | ((unsigned)w[3] << 24); cd.y = (unsigned)w[4] | ((unsigned)w[5] << 8) | ((unsigned)w[6] << 16) | ((unsigned)w[7] << 24);
;                 *(u32x2*)(ws + WS_G8 + (size_t)row * 2048 + col) = cd;
	v_pk_mul_f32 v[38:39], v[38:39], v[186:187] op_sel_hi:[1,0]
	global_store_dwordx2 v[202:203], v[196:197], off
	v_exp_f32_e32 v32, v32
	v_exp_f32_e32 v33, v33
	v_exp_f32_e32 v34, v34
	v_exp_f32_e32 v35, v35
	v_exp_f32_e32 v36, v36
	v_exp_f32_e32 v37, v37
	v_exp_f32_e32 v38, v38
	v_exp_f32_e32 v39, v39
	v_pk_add_f32 v[32:33], v[32:33], 1.0 op_sel_hi:[1,0]
	v_pk_add_f32 v[34:35], v[34:35], 1.0 op_sel_hi:[1,0]
	v_pk_add_f32 v[36:37], v[36:37], 1.0 op_sel_hi:[1,0]
	v_pk_add_f32 v[38:39], v[38:39], 1.0 op_sel_hi:[1,0]
	v_rcp_f32_e32 v32, v32
	v_rcp_f32_e32 v33, v33
	v_rcp_f32_e32 v34, v34
	v_rcp_f32_e32 v35, v35
	v_rcp_f32_e32 v36, v36
	v_rcp_f32_e32 v37, v37
	v_rcp_f32_e32 v38, v38
	v_rcp_f32_e32 v39, v39
	v_pk_fma_f32 v[32:33], v[32:33], s[20:21], 0.5 op_sel_hi:[1,0,0]
	v_pk_fma_f32 v[34:35], v[34:35], s[20:21], 0.5 op_sel_hi:[1,0,0]
	v_pk_fma_f32 v[36:37], v[36:37], s[20:21], 0.5 op_sel_hi:[1,0,0]
	v_pk_fma_f32 v[38:39], v[38:39], s[20:21], 0.5 op_sel_hi:[1,0,0]
	v_cvt_u32_f32_e32 v198, v36
	v_cvt_u32_f32_e32 v199, v32
	v_cvt_u32_f32_sdwa v198, v37 dst_sel:BYTE_1 dst_unused:UNUSED_PRESERVE src0_sel:DWORD
	v_cvt_u32_f32_sdwa v199, v33 dst_sel:BYTE_1 dst_unused:UNUSED_PRESERVE src0_sel:DWORD
	v_cvt_u32_f32_sdwa v198, v38 dst_sel:BYTE_2 dst_unused:UNUSED_PRESERVE src0_sel:DWORD
	v_cvt_u32_f32_sdwa v199, v34 dst_sel:BYTE_2 dst_unused:UNUSED_PRESERVE src0_sel:DWORD
	v_cvt_u32_f32_sdwa v198, v39 dst_sel:BYTE_3 dst_unused:UNUSED_PRESERVE src0_sel:DWORD
	v_cvt_u32_f32_sdwa v199, v35 dst_sel:BYTE_3 dst_unused:UNUSED_PRESERVE src0_sel:DWORD
	s_waitcnt vmcnt(12)
	v_mul_f32_e32 v188, 0xbfb8aa3b, v163
	s_mov_b32 s78, 0x50000
	v_lshl_add_u64 v[200:201], v[170:171], 0, s[78:79]
	v_pk_mul_f32 v[24:25], v[24:25], v[188:189] op_sel_hi:[1,0]
	v_pk_mul_f32 v[26:27], v[26:27], v[188:189] op_sel_hi:[1,0]
	v_pk_mul_f32 v[28:29], v[28:29], v[188:189] op_sel_hi:[1,0]
	v_pk_mul_f32 v[30:31], v[30:31], v[188:189] op_sel_hi:[1,0]
	global_store_dwordx2 v[202:203], v[198:199], off offset:128
	v_exp_f32_e32 v24, v24
	v_exp_f32_e32 v25, v25
	v_exp_f32_e32 v26, v26
	v_exp_f32_e32 v27, v27
	v_exp_f32_e32 v28, v28
	v_exp_f32_e32 v29, v29
	v_exp_f32_e32 v30, v30
	v_exp_f32_e32 v31, v31
	v_pk_add_f32 v[24:25], v[24:25], 1.0 op_sel_hi:[1,0]
	v_pk_add_f32 v[26:27], v[26:27], 1.0 op_sel_hi:[1,0]
	v_pk_add_f32 v[28:29], v[28:29], 1.0 op_sel_hi:[1,0]
	v_pk_add_f32 v[30:31], v[30:31], 1.0 op_sel_hi:[1,0]
	v_rcp_f32_e32 v24, v24
	v_rcp_f32_e32 v25, v25
	v_rcp_f32_e32 v26, v26
	v_rcp_f32_e32 v27, v27
	v_rcp_f32_e32 v28, v28
	v_rcp_f32_e32 v29, v29
	v_rcp_f32_e32 v30, v30
	v_rcp_f32_e32 v31, v31
	v_pk_fma_f32 v[24:25], v[24:25], s[20:21], 0.5 op_sel_hi:[1,0,0]
	v_pk_fma_f32 v[26:27], v[26:27], s[20:21], 0.5 op_sel_hi:[1,0,0]
	v_pk_fma_f32 v[28:29], v[28:29], s[20:21], 0.5 op_sel_hi:[1,0,0]
	v_pk_fma_f32 v[30:31], v[30:31], s[20:21], 0.5 op_sel_hi:[1,0,0]
	v_cvt_u32_f32_e32 v192, v28
	v_cvt_u32_f32_e32 v193, v24
	v_cvt_u32_f32_sdwa v192, v29 dst_sel:BYTE_1 dst_unused:UNUSED_PRESERVE src0_sel:DWORD
	v_cvt_u32_f32_sdwa v193, v25 dst_sel:BYTE_1 dst_unused:UNUSED_PRESERVE src0_sel:DWORD
	v_cvt_u32_f32_sdwa v192, v30 dst_sel:BYTE_2 dst_unused:UNUSED_PRESERVE src0_sel:DWORD
	v_cvt_u32_f32_sdwa v193, v26 dst_sel:BYTE_2 dst_unused:UNUSED_PRESERVE src0_sel:DWORD
	v_cvt_u32_f32_sdwa v192, v31 dst_sel:BYTE_3 dst_unused:UNUSED_PRESERVE src0_sel:DWORD
	v_cvt_u32_f32_sdwa v193, v27 dst_sel:BYTE_3 dst_unused:UNUSED_PRESERVE src0_sel:DWORD
	v_pk_mul_f32 v[16:17], v[16:17], v[188:189] op_sel_hi:[1,0]
	v_pk_mul_f32 v[18:19], v[18:19], v[188:189] op_sel_hi:[1,0]
	v_pk_mul_f32 v[20:21], v[20:21], v[188:189] op_sel_hi:[1,0]
	v_pk_mul_f32 v[22:23], v[22:23], v[188:189] op_sel_hi:[1,0]
	global_store_dwordx2 v[200:201], v[192:193], off
	v_exp_f32_e32 v16, v16
	v_exp_f32_e32 v17, v17
	v_exp_f32_e32 v18, v18
	v_exp_f32_e32 v19, v19
	v_exp_f32_e32 v20, v20
	v_exp_f32_e32 v21, v21
	v_exp_f32_e32 v22, v22
	v_exp_f32_e32 v23, v23
	v_pk_add_f32 v[16:17], v[16:17], 1.0 op_sel_hi:[1,0]
	v_pk_add_f32 v[18:19], v[18:19], 1.0 op_sel_hi:[1,0]
	v_pk_add_f32 v[20:21], v[20:21], 1.0 op_sel_hi:[1,0]
	v_pk_add_f32 v[22:23], v[22:23], 1.0 op_sel_hi:[1,0]
	v_rcp_f32_e32 v16, v16
	v_rcp_f32_e32 v17, v17
	v_rcp_f32_e32 v18, v18
	v_rcp_f32_e32 v19, v19
	v_rcp_f32_e32 v20, v20
	v_rcp_f32_e32 v21, v21
	v_rcp_f32_e32 v22, v22
	v_rcp_f32_e32 v23, v23
	v_pk_fma_f32 v[16:17], v[16:17], s[20:21], 0.5 op_sel_hi:[1,0,0]
	v_pk_fma_f32 v[18:19], v[18:19], s[20:21], 0.5 op_sel_hi:[1,0,0]
	v_pk_fma_f32 v[20:21], v[20:21], s[20:21], 0.5 op_sel_hi:[1,0,0]
	v_pk_fma_f32 v[22:23], v[22:23], s[20:21], 0.5 op_sel_hi:[1,0,0]
	v_cvt_u32_f32_e32 v194, v20
	v_cvt_u32_f32_e32 v195, v16
	v_cvt_u32_f32_sdwa v194, v21 dst_sel:BYTE_1 dst_unused:UNUSED_PRESERVE src0_sel:DWORD
	v_cvt_u32_f32_sdwa v195, v17 dst_sel:BYTE_1 dst_unused:UNUSED_PRESERVE src0_sel:DWORD
	v_cvt_u32_f32_sdwa v194, v22 dst_sel:BYTE_2 dst_unused:UNUSED_PRESERVE src0_sel:DWORD
	v_cvt_u32_f32_sdwa v195, v18 dst_sel:BYTE_2 dst_unused:UNUSED_PRESERVE src0_sel:DWORD
	v_cvt_u32_f32_sdwa v194, v23 dst_sel:BYTE_3 dst_unused:UNUSED_PRESERVE src0_sel:DWORD
	v_cvt_u32_f32_sdwa v195, v19 dst_sel:BYTE_3 dst_unused:UNUSED_PRESERVE src0_sel:DWORD
	s_waitcnt vmcnt(13)
; __device__ __forceinline__ float sigmoidf_(float z) { return __builtin_amdgcn_rcpf(1.0f + __builtin_amdgcn_exp2f(-1.4426950408889634f * z)); }
;     __device__ __forceinline__ float compute(const Pre& p, f32x4 (&acc)[2][2][4][2], const f32x4 (&cv)[2][2], const pg8::Unit& u, int ai, int m, int wr, int wc, int fr, int fq) const {
;     ...
;             } else if (MODE == EM_GATES) {
;                 const int col = u.pn * 256 + ct; float w[8];
; #pragma unroll
;                 for (int j = 0; j < 8; ++j) w[j] = sigmoidf_(v[j] * rs) * 255.0f + 0.5f;
;                 u32x2 cd; cd.x = (unsigned)w[0] | ((unsigned)w[1] << 8) | ((unsigned)w[2] << 16) | ((unsigned)w[3] << 24); cd.y = (unsigned)w[4] | ((unsigned)w[5] << 8) | ((unsigned)w[6] << 16) | ((unsigned)w[7] << 24);
;                 *(u32x2*)(ws + WS_G8 + (size_t)row * 2048 + col) = cd;
	v_mul_f32_e32 v190, 0xbfb8aa3b, v162
	s_mov_b32 s78, 0x58000
	v_lshl_add_u64 v[202:203], v[170:171], 0, s[78:79]
	v_pk_mul_f32 v[8:9], v[8:9], v[190:191] op_sel_hi:[1,0]
	v_pk_mul_f32 v[10:11], v[10:11], v[190:191] op_sel_hi:[1,0]
	v_pk_mul_f32 v[12:13], v[12:13], v[190:191] op_sel_hi:[1,0]
	v_pk_mul_f32 v[14:15], v[14:15], v[190:191] op_sel_hi:[1,0]
	global_store_dwordx2 v[200:201], v[194:195], off offset:128
	v_exp_f32_e32 v8, v8
	v_exp_f32_e32 v9, v9
	v_exp_f32_e32 v10, v10
	v_exp_f32_e32 v11, v11
	v_exp_f32_e32 v12, v12
	v_exp_f32_e32 v13, v13
	v_exp_f32_e32 v14, v14
	v_exp_f32_e32 v15, v15
	v_pk_add_f32 v[8:9], v[8:9], 1.0 op_sel_hi:[1,0]
	v_pk_add_f32 v[10:11], v[10:11], 1.0 op_sel_hi:[1,0]
	v_pk_add_f32 v[12:13], v[12:13], 1.0 op_sel_hi:[1,0]
	v_pk_add_f32 v[14:15], v[14:15], 1.0 op_sel_hi:[1,0]
	v_rcp_f32_e32 v8, v8
	v_rcp_f32_e32 v9, v9
	v_rcp_f32_e32 v10, v10
	v_rcp_f32_e32 v11, v11
	v_rcp_f32_e32 v12, v12
	v_rcp_f32_e32 v13, v13
	v_rcp_f32_e32 v14, v14
	v_rcp_f32_e32 v15, v15
	v_pk_fma_f32 v[8:9], v[8:9], s[20:21], 0.5 op_sel_hi:[1,0,0]
	v_pk_fma_f32 v[10:11], v[10:11], s[20:21], 0.5 op_sel_hi:[1,0,0]
	v_pk_fma_f32 v[12:13], v[12:13], s[20:21], 0.5 op_sel_hi:[1,0,0]
	v_pk_fma_f32 v[14:15], v[14:15], s[20:21], 0.5 op_sel_hi:[1,0,0]
	v_cvt_u32_f32_e32 v196, v12
	v_cvt_u32_f32_e32 v197, v8
	v_cvt_u32_f32_sdwa v196, v13 dst_sel:BYTE_1 dst_unused:UNUSED_PRESERVE src0_sel:DWORD
	v_cvt_u32_f32_sdwa v197, v9 dst_sel:BYTE_1 dst_unused:UNUSED_PRESERVE src0_sel:DWORD
	v_cvt_u32_f32_sdwa v196, v14 dst_sel:BYTE_2 dst_unused:UNUSED_PRESERVE src0_sel:DWORD
	v_cvt_u32_f32_sdwa v197, v10 dst_sel:BYTE_2 dst_unused:UNUSED_PRESERVE src0_sel:DWORD
	v_cvt_u32_f32_sdwa v196, v15 dst_sel:BYTE_3 dst_unused:UNUSED_PRESERVE src0_sel:DWORD
	v_cvt_u32_f32_sdwa v197, v11 dst_sel:BYTE_3 dst_unused:UNUSED_PRESERVE src0_sel:DWORD
	v_pk_mul_f32 v[0:1], v[0:1], v[190:191] op_sel_hi:[1,0]
	v_pk_mul_f32 v[2:3], v[2:3], v[190:191] op_sel_hi:[1,0]
	v_pk_mul_f32 v[4:5], v[4:5], v[190:191] op_sel_hi:[1,0]
	v_pk_mul_f32 v[6:7], v[6:7], v[190:191] op_sel_hi:[1,0]
	global_store_dwordx2 v[202:203], v[196:197], off
	v_exp_f32_e32 v0, v0
	v_exp_f32_e32 v1, v1
	v_exp_f32_e32 v2, v2
	v_exp_f32_e32 v3, v3
	v_exp_f32_e32 v4, v4
	v_exp_f32_e32 v5, v5
	v_exp_f32_e32 v6, v6
	v_exp_f32_e32 v7, v7
	v_pk_add_f32 v[0:1], v[0:1], 1.0 op_sel_hi:[1,0]
	v_pk_add_f32 v[2:3], v[2:3], 1.0 op_sel_hi:[1,0]
	v_pk_add_f32 v[4:5], v[4:5], 1.0 op_sel_hi:[1,0]
	v_pk_add_f32 v[6:7], v[6:7], 1.0 op_sel_hi:[1,0]
	v_rcp_f32_e32 v0, v0
	v_rcp_f32_e32 v1, v1
	v_rcp_f32_e32 v2, v2
	v_rcp_f32_e32 v3, v3
	v_rcp_f32_e32 v4, v4
	v_rcp_f32_e32 v5, v5
	v_rcp_f32_e32 v6, v6
	v_rcp_f32_e32 v7, v7
	v_pk_fma_f32 v[0:1], v[0:1], s[20:21], 0.5 op_sel_hi:[1,0,0]
	v_pk_fma_f32 v[2:3], v[2:3], s[20:21], 0.5 op_sel_hi:[1,0,0]
	v_pk_fma_f32 v[4:5], v[4:5], s[20:21], 0.5 op_sel_hi:[1,0,0]
	v_pk_fma_f32 v[6:7], v[6:7], s[20:21], 0.5 op_sel_hi:[1,0,0]
	v_cvt_u32_f32_e32 v198, v4
	v_cvt_u32_f32_e32 v199, v0
	v_cvt_u32_f32_sdwa v198, v5 dst_sel:BYTE_1 dst_unused:UNUSED_PRESERVE src0_sel:DWORD
	v_cvt_u32_f32_sdwa v199, v1 dst_sel:BYTE_1 dst_unused:UNUSED_PRESERVE src0_sel:DWORD
	v_cvt_u32_f32_sdwa v198, v6 dst_sel:BYTE_2 dst_unused:UNUSED_PRESERVE src0_sel:DWORD
	v_cvt_u32_f32_sdwa v199, v2 dst_sel:BYTE_2 dst_unused:UNUSED_PRESERVE src0_sel:DWORD
	v_cvt_u32_f32_sdwa v198, v7 dst_sel:BYTE_3 dst_unused:UNUSED_PRESERVE src0_sel:DWORD
	v_cvt_u32_f32_sdwa v199, v3 dst_sel:BYTE_3 dst_unused:UNUSED_PRESERVE src0_sel:DWORD
	s_nop 0
	global_store_dwordx2 v[202:203], v[198:199], off offset:128
	s_and_b64 vcc, exec, s[4:5]
	s_mov_b64 s[4:5], -1
	s_cbranch_vccnz .LBB0_802
	s_andn2_b64 vcc, exec, s[6:7]
	s_cbranch_vccnz .LBB0_801
	s_barrier
	s_branch .LBB0_801

; __device__ __forceinline__ float sigmoidf_(float z) { return __builtin_amdgcn_rcpf(1.0f + __builtin_amdgcn_exp2f(-1.4426950408889634f * z)); }
;     __device__ __forceinline__ void load(Pre& p, const pg8::Unit& u, int ai, int m, int wr, int wc, int fr, int fq) const {
;         const int row = u.pm * 256 + ai * 128 + wr * 64 + m * 16 + fr;
;         if (MODE == EM_PROJ || MODE == EM_GATES) p.rs = ((const float*)(ws + WS_RINV0))[row];
;     __device__ __forceinline__ float compute(const Pre& p, f32x4 (&acc)[2][2][4][2], const f32x4 (&cv)[2][2], const pg8::Unit& u, int ai, int m, int wr, int wc, int fr, int fq) const {
;     ...
;             } else if (MODE == EM_GATES) {
;                 const int col = u.pn * 256 + ct; float w[8];
; #pragma unroll
;                 for (int j = 0; j < 8; ++j) w[j] = sigmoidf_(v[j] * rs) * 255.0f + 0.5f;
;                 u32x2 cd; cd.x = (unsigned)w[0] | ((unsigned)w[1] << 8) | ((unsigned)w[2] << 16) | ((unsigned)w[3] << 24); cd.y = (unsigned)w[4] | ((unsigned)w[5] << 8) | ((unsigned)w[6] << 16) | ((unsigned)w[7] << 24);
;                 *(u32x2*)(ws + WS_G8 + (size_t)row * 2048 + col) = cd;
.LBB0_866:
	v_lshl_add_u32 v162, s28, 8, v156
	v_ashrrev_i32_e32 v163, 31, v162
	v_lshl_add_u64 v[140:141], v[162:163], 2, s[12:13]
	global_load_dword v180, v[140:141], off
	v_or_b32_e32 v154, 16, v162
	v_or_b32_e32 v152, 32, v162
	v_or_b32_e32 v150, 48, v162
	v_add_u32_e32 v148, 0x80, v162
	v_add_u32_e32 v146, 0x90, v162
	v_add_u32_e32 v144, 0xa0, v162
	v_add_u32_e32 v142, 0xb0, v162
	v_ashrrev_i32_e32 v155, 31, v154
	v_ashrrev_i32_e32 v153, 31, v152
	v_ashrrev_i32_e32 v151, 31, v150
	v_ashrrev_i32_e32 v149, 31, v148
	v_ashrrev_i32_e32 v147, 31, v146
	v_ashrrev_i32_e32 v145, 31, v144
	v_ashrrev_i32_e32 v143, 31, v142
	v_lshlrev_b64 v[168:169], 11, v[162:163]
	v_lshl_add_u64 v[162:163], v[154:155], 2, s[12:13]
	v_lshl_add_u64 v[164:165], v[152:153], 2, s[12:13]
	v_lshl_add_u64 v[166:167], v[150:151], 2, s[12:13]
	v_lshl_add_u64 v[170:171], v[148:149], 2, s[12:13]
	v_lshl_add_u64 v[172:173], v[146:147], 2, s[12:13]
	v_lshl_add_u64 v[174:175], v[144:145], 2, s[12:13]
	v_lshl_add_u64 v[176:177], v[142:143], 2, s[12:13]
	global_load_dword v181, v[162:163], off
	global_load_dword v182, v[164:165], off
	s_nop 0
	global_load_dword v166, v[166:167], off
	s_nop 0
	global_load_dword v165, v[170:171], off
	global_load_dword v164, v[172:173], off
	global_load_dword v163, v[174:175], off
	global_load_dword v162, v[176:177], off
	v_lshl_or_b32 v140, s26, 8, v158
	v_ashrrev_i32_e32 v141, 31, v140
	v_lshl_add_u64 v[178:179], s[14:15], 0, v[168:169]
	v_lshl_add_u64 v[170:171], v[178:179], 0, v[140:141]
	s_mov_b32 s89, 0
	s_waitcnt vmcnt(7)
	v_mul_f32_e32 v172, 0xbfb8aa3b, v180
	v_pk_mul_f32 v[120:121], v[120:121], v[172:173] op_sel_hi:[1,0]
	v_pk_mul_f32 v[122:123], v[122:123], v[172:173] op_sel_hi:[1,0]
	v_pk_mul_f32 v[124:125], v[124:125], v[172:173] op_sel_hi:[1,0]
	v_pk_mul_f32 v[126:127], v[126:127], v[172:173] op_sel_hi:[1,0]
	v_exp_f32_e32 v120, v120
	v_exp_f32_e32 v121, v121
	v_exp_f32_e32 v122, v122
	v_exp_f32_e32 v123, v123
	v_exp_f32_e32 v124, v124
	v_exp_f32_e32 v125, v125
	v_exp_f32_e32 v126, v126
	v_exp_f32_e32 v127, v127
	v_pk_add_f32 v[120:121], v[120:121], 1.0 op_sel_hi:[1,0]
	v_pk_add_f32 v[122:123], v[122:123], 1.0 op_sel_hi:[1,0]
	v_pk_add_f32 v[124:125], v[124:125], 1.0 op_sel_hi:[1,0]
	v_pk_add_f32 v[126:127], v[126:127], 1.0 op_sel_hi:[1,0]
	v_rcp_f32_e32 v120, v120
	v_rcp_f32_e32 v121, v121
	v_rcp_f32_e32 v122, v122
	v_rcp_f32_e32 v123, v123
	v_rcp_f32_e32 v124, v124
	v_rcp_f32_e32 v125, v125
	v_rcp_f32_e32 v126, v126
	v_rcp_f32_e32 v127, v127
	v_pk_fma_f32 v[120:121], v[120:121], s[20:21], 0.5 op_sel_hi:[1,0,0]
	v_pk_fma_f32 v[122:123], v[122:123], s[20:21], 0.5 op_sel_hi:[1,0,0]
	v_pk_fma_f32 v[124:125], v[124:125], s[20:21], 0.5 op_sel_hi:[1,0,0]
	v_pk_fma_f32 v[126:127], v[126:127], s[20:21], 0.5 op_sel_hi:[1,0,0]
	v_cvt_u32_f32_e32 v192, v124
	v_cvt_u32_f32_e32 v193, v120
	v_cvt_u32_f32_sdwa v192, v125 dst_sel:BYTE_1 dst_unused:UNUSED_PRESERVE src0_sel:DWORD
	v_cvt_u32_f32_sdwa v193, v121 dst_sel:BYTE_1 dst_unused:UNUSED_PRESERVE src0_sel:DWORD
	v_cvt_u32_f32_sdwa v192, v126 dst_sel:BYTE_2 dst_unused:UNUSED_PRESERVE src0_sel:DWORD
	v_cvt_u32_f32_sdwa v193, v122 dst_sel:BYTE_2 dst_unused:UNUSED_PRESERVE src0_sel:DWORD
	v_cvt_u32_f32_sdwa v192, v127 dst_sel:BYTE_3 dst_unused:UNUSED_PRESERVE src0_sel:DWORD
	v_cvt_u32_f32_sdwa v193, v123 dst_sel:BYTE_3 dst_unused:UNUSED_PRESERVE src0_sel:DWORD
	v_pk_mul_f32 v[112:113], v[112:113], v[172:173] op_sel_hi:[1,0]
	v_pk_mul_f32 v[114:115], v[114:115], v[172:173] op_sel_hi:[1,0]
	v_pk_mul_f32 v[116:117], v[116:117], v[172:173] op_sel_hi:[1,0]
	v_pk_mul_f32 v[118:119], v[118:119], v[172:173] op_sel_hi:[1,0]
	global_store_dwordx2 v[170:171], v[192:193], off
	v_exp_f32_e32 v112, v112
	v_exp_f32_e32 v113, v113
	v_exp_f32_e32 v114, v114
	v_exp_f32_e32 v115, v115
	v_exp_f32_e32 v116, v116
	v_exp_f32_e32 v117, v117
	v_exp_f32_e32 v118, v118
	v_exp_f32_e32 v119, v119
	v_pk_add_f32 v[112:113], v[112:113], 1.0 op_sel_hi:[1,0]
	v_pk_add_f32 v[114:115], v[114:115], 1.0 op_sel_hi:[1,0]
	v_pk_add_f32 v[116:117], v[116:117], 1.0 op_sel_hi:[1,0]
	v_pk_add_f32 v[118:119], v[118:119], 1.0 op_sel_hi:[1,0]
	v_rcp_f32_e32 v112, v112
	v_rcp_f32_e32 v113, v113
	v_rcp_f32_e32 v114, v114
	v_rcp_f32_e32 v115, v115
	v_rcp_f32_e32 v116, v116
	v_rcp_f32_e32 v117, v117
	v_rcp_f32_e32 v118, v118
	v_rcp_f32_e32 v119, v119
	v_pk_fma_f32 v[112:113], v[112:113], s[20:21], 0.5 op_sel_hi:[1,0,0]
	v_pk_fma_f32 v[114:115], v[114:115], s[20:21], 0.5 op_sel_hi:[1,0,0]
	v_pk_fma_f32 v[116:117], v[116:117], s[20:21], 0.5 op_sel_hi:[1,0,0]
	v_pk_fma_f32 v[118:119], v[118:119], s[20:21], 0.5 op_sel_hi:[1,0,0]
	v_cvt_u32_f32_e32 v194, v116
	v_cvt_u32_f32_e32 v195, v112
	v_cvt_u32_f32_sdwa v194, v117 dst_sel:BYTE_1 dst_unused:UNUSED_PRESERVE src0_sel:DWORD
	v_cvt_u32_f32_sdwa v195, v113 dst_sel:BYTE_1 dst_unused:UNUSED_PRESERVE src0_sel:DWORD
	v_cvt_u32_f32_sdwa v194, v118 dst_sel:BYTE_2 dst_unused:UNUSED_PRESERVE src0_sel:DWORD
	v_cvt_u32_f32_sdwa v195, v114 dst_sel:BYTE_2 dst_unused:UNUSED_PRESERVE src0_sel:DWORD
	v_cvt_u32_f32_sdwa v194, v119 dst_sel:BYTE_3 dst_unused:UNUSED_PRESERVE src0_sel:DWORD
	v_cvt_u32_f32_sdwa v195, v115 dst_sel:BYTE_3 dst_unused:UNUSED_PRESERVE src0_sel:DWORD
	s_waitcnt vmcnt(7)
; __device__ __forceinline__ float sigmoidf_(float z) { return __builtin_amdgcn_rcpf(1.0f + __builtin_amdgcn_exp2f(-1.4426950408889634f * z)); }
;     __device__ __forceinline__ float compute(const Pre& p, f32x4 (&acc)[2][2][4][2], const f32x4 (&cv)[2][2], const pg8::Unit& u, int ai, int m, int wr, int wc, int fr, int fq) const {
;     ...
;             } else if (MODE == EM_GATES) {
;                 const int col = u.pn * 256 + ct; float w[8];
; #pragma unroll
;                 for (int j = 0; j < 8; ++j) w[j] = sigmoidf_(v[j] * rs) * 255.0f + 0.5f;
;                 u32x2 cd; cd.x = (unsigned)w[0] | ((unsigned)w[1] << 8) | ((unsigned)w[2] << 16) | ((unsigned)w[3] << 24); cd.y = (unsigned)w[4] | ((unsigned)w[5] << 8) | ((unsigned)w[6] << 16) | ((unsigned)w[7] << 24);
;                 *(u32x2*)(ws + WS_G8 + (size_t)row * 2048 + col) = cd;
	v_mul_f32_e32 v174, 0xbfb8aa3b, v181
	s_mov_b32 s88, 0x8000
	v_lshl_add_u64 v[202:203], v[170:171], 0, s[88:89]
	v_pk_mul_f32 v[104:105], v[104:105], v[174:175] op_sel_hi:[1,0]
	v_pk_mul_f32 v[106:107], v[106:107], v[174:175] op_sel_hi:[1,0]
	v_pk_mul_f32 v[108:109], v[108:109], v[174:175] op_sel_hi:[1,0]
	v_pk_mul_f32 v[110:111], v[110:111], v[174:175] op_sel_hi:[1,0]
	global_store_dwordx2 v[170:171], v[194:195], off offset:128
	v_exp_f32_e32 v104, v104
	v_exp_f32_e32 v105, v105
	v_exp_f32_e32 v106, v106
	v_exp_f32_e32 v107, v107
	v_exp_f32_e32 v108, v108
	v_exp_f32_e32 v109, v109
	v_exp_f32_e32 v110, v110
	v_exp_f32_e32 v111, v111
	v_pk_add_f32 v[104:105], v[104:105], 1.0 op_sel_hi:[1,0]
	v_pk_add_f32 v[106:107], v[106:107], 1.0 op_sel_hi:[1,0]
	v_pk_add_f32 v[108:109], v[108:109], 1.0 op_sel_hi:[1,0]
	v_pk_add_f32 v[110:111], v[110:111], 1.0 op_sel_hi:[1,0]
	v_rcp_f32_e32 v104, v104
	v_rcp_f32_e32 v105, v105
	v_rcp_f32_e32 v106, v106
	v_rcp_f32_e32 v107, v107
	v_rcp_f32_e32 v108, v108
	v_rcp_f32_e32 v109, v109
	v_rcp_f32_e32 v110, v110
	v_rcp_f32_e32 v111, v111
	v_pk_fma_f32 v[104:105], v[104:105], s[20:21], 0.5 op_sel_hi:[1,0,0]
	v_pk_fma_f32 v[106:107], v[106:107], s[20:21], 0.5 op_sel_hi:[1,0,0]
	v_pk_fma_f32 v[108:109], v[108:109], s[20:21], 0.5 op_sel_hi:[1,0,0]
	v_pk_fma_f32 v[110:111], v[110:111], s[20:21], 0.5 op_sel_hi:[1,0,0]
	v_cvt_u32_f32_e32 v196, v108
	v_cvt_u32_f32_e32 v197, v104
	v_cvt_u32_f32_sdwa v196, v109 dst_sel:BYTE_1 dst_unused:UNUSED_PRESERVE src0_sel:DWORD
	v_cvt_u32_f32_sdwa v197, v105 dst_sel:BYTE_1 dst_unused:UNUSED_PRESERVE src0_sel:DWORD
	v_cvt_u32_f32_sdwa v196, v110 dst_sel:BYTE_2 dst_unused:UNUSED_PRESERVE src0_sel:DWORD
	v_cvt_u32_f32_sdwa v197, v106 dst_sel:BYTE_2 dst_unused:UNUSED_PRESERVE src0_sel:DWORD
	v_cvt_u32_f32_sdwa v196, v111 dst_sel:BYTE_3 dst_unused:UNUSED_PRESERVE src0_sel:DWORD
	v_cvt_u32_f32_sdwa v197, v107 dst_sel:BYTE_3 dst_unused:UNUSED_PRESERVE src0_sel:DWORD
	v_pk_mul_f32 v[96:97], v[96:97], v[174:175] op_sel_hi:[1,0]
	v_pk_mul_f32 v[98:99], v[98:99], v[174:175] op_sel_hi:[1,0]
	v_pk_mul_f32 v[100:101], v[100:101], v[174:175] op_sel_hi:[1,0]
	v_pk_mul_f32 v[102:103], v[102:103], v[174:175] op_sel_hi:[1,0]
	global_store_dwordx2 v[202:203], v[196:197], off
	v_exp_f32_e32 v96, v96
	v_exp_f32_e32 v97, v97
	v_exp_f32_e32 v98, v98
	v_exp_f32_e32 v99, v99
	v_exp_f32_e32 v100, v100
	v_exp_f32_e32 v101, v101
	v_exp_f32_e32 v102, v102
	v_exp_f32_e32 v103, v103
	v_pk_add_f32 v[96:97], v[96:97], 1.0 op_sel_hi:[1,0]
	v_pk_add_f32 v[98:99], v[98:99], 1.0 op_sel_hi:[1,0]
	v_pk_add_f32 v[100:101], v[100:101], 1.0 op_sel_hi:[1,0]
	v_pk_add_f32 v[102:103], v[102:103], 1.0 op_sel_hi:[1,0]
	v_rcp_f32_e32 v96, v96
	v_rcp_f32_e32 v97, v97
	v_rcp_f32_e32 v98, v98
	v_rcp_f32_e32 v99, v99
	v_rcp_f32_e32 v100, v100
	v_rcp_f32_e32 v101, v101
	v_rcp_f32_e32 v102, v102
	v_rcp_f32_e32 v103, v103
	v_pk_fma_f32 v[96:97], v[96:97], s[20:21], 0.5 op_sel_hi:[1,0,0]
	v_pk_fma_f32 v[98:99], v[98:99], s[20:21], 0.5 op_sel_hi:[1,0,0]
	v_pk_fma_f32 v[100:101], v[100:101], s[20:21], 0.5 op_sel_hi:[1,0,0]
	v_pk_fma_f32 v[102:103], v[102:103], s[20:21], 0.5 op_sel_hi:[1,0,0]
	v_cvt_u32_f32_e32 v198, v100
	v_cvt_u32_f32_e32 v199, v96
	v_cvt_u32_f32_sdwa v198, v101 dst_sel:BYTE_1 dst_unused:UNUSED_PRESERVE src0_sel:DWORD
	v_cvt_u32_f32_sdwa v199, v97 dst_sel:BYTE_1 dst_unused:UNUSED_PRESERVE src0_sel:DWORD
	v_cvt_u32_f32_sdwa v198, v102 dst_sel:BYTE_2 dst_unused:UNUSED_PRESERVE src0_sel:DWORD
	v_cvt_u32_f32_sdwa v199, v98 dst_sel:BYTE_2 dst_unused:UNUSED_PRESERVE src0_sel:DWORD
	v_cvt_u32_f32_sdwa v198, v103 dst_sel:BYTE_3 dst_unused:UNUSED_PRESERVE src0_sel:DWORD
	v_cvt_u32_f32_sdwa v199, v99 dst_sel:BYTE_3 dst_unused:UNUSED_PRESERVE src0_sel:DWORD
	s_waitcnt vmcnt(8)
	v_mul_f32_e32 v176, 0xbfb8aa3b, v182
	s_mov_b32 s88, 0x10000
	v_lshl_add_u64 v[200:201], v[170:171], 0, s[88:89]
	v_pk_mul_f32 v[88:89], v[88:89], v[176:177] op_sel_hi:[1,0]
	v_pk_mul_f32 v[90:91], v[90:91], v[176:177] op_sel_hi:[1,0]
	v_pk_mul_f32 v[92:93], v[92:93], v[176:177] op_sel_hi:[1,0]
	v_pk_mul_f32 v[94:95], v[94:95], v[176:177] op_sel_hi:[1,0]
	global_store_dwordx2 v[202:203], v[198:199], off offset:128
	v_exp_f32_e32 v88, v88
	v_exp_f32_e32 v89, v89
	v_exp_f32_e32 v90, v90
	v_exp_f32_e32 v91, v91
	v_exp_f32_e32 v92, v92
	v_exp_f32_e32 v93, v93
	v_exp_f32_e32 v94, v94
	v_exp_f32_e32 v95, v95
	v_pk_add_f32 v[88:89], v[88:89], 1.0 op_sel_hi:[1,0]
	v_pk_add_f32 v[90:91], v[90:91], 1.0 op_sel_hi:[1,0]
	v_pk_add_f32 v[92:93], v[92:93], 1.0 op_sel_hi:[1,0]
	v_pk_add_f32 v[94:95], v[94:95], 1.0 op_sel_hi:[1,0]
	v_rcp_f32_e32 v88, v88
	v_rcp_f32_e32 v89, v89
	v_rcp_f32_e32 v90, v90
	v_rcp_f32_e32 v91, v91
	v_rcp_f32_e32 v92, v92
	v_rcp_f32_e32 v93, v93
	v_rcp_f32_e32 v94, v94
	v_rcp_f32_e32 v95, v95
	v_pk_fma_f32 v[88:89], v[88:89], s[20:21], 0.5 op_sel_hi:[1,0,0]
	v_pk_fma_f32 v[90:91], v[90:91], s[20:21], 0.5 op_sel_hi:[1,0,0]
	v_pk_fma_f32 v[92:93], v[92:93], s[20:21], 0.5 op_sel_hi:[1,0,0]
	v_pk_fma_f32 v[94:95], v[94:95], s[20:21], 0.5 op_sel_hi:[1,0,0]
	v_cvt_u32_f32_e32 v192, v92
	v_cvt_u32_f32_e32 v193, v88
	v_cvt_u32_f32_sdwa v192, v93 dst_sel:BYTE_1 dst_unused:UNUSED_PRESERVE src0_sel:DWORD
	v_cvt_u32_f32_sdwa v193, v89 dst_sel:BYTE_1 dst_unused:UNUSED_PRESERVE src0_sel:DWORD
	v_cvt_u32_f32_sdwa v192, v94 dst_sel:BYTE_2 dst_unused:UNUSED_PRESERVE src0_sel:DWORD
	v_cvt_u32_f32_sdwa v193, v90 dst_sel:BYTE_2 dst_unused:UNUSED_PRESERVE src0_sel:DWORD
	v_cvt_u32_f32_sdwa v192, v95 dst_sel:BYTE_3 dst_unused:UNUSED_PRESERVE src0_sel:DWORD
	v_cvt_u32_f32_sdwa v193, v91 dst_sel:BYTE_3 dst_unused:UNUSED_PRESERVE src0_sel:DWORD
; __device__ __forceinline__ float sigmoidf_(float z) { return __builtin_amdgcn_rcpf(1.0f + __builtin_amdgcn_exp2f(-1.4426950408889634f * z)); }
;     __device__ __forceinline__ float compute(const Pre& p, f32x4 (&acc)[2][2][4][2], const f32x4 (&cv)[2][2], const pg8::Unit& u, int ai, int m, int wr, int wc, int fr, int fq) const {
;     ...
;             } else if (MODE == EM_GATES) {
;                 const int col = u.pn * 256 + ct; float w[8];
; #pragma unroll
;                 for (int j = 0; j < 8; ++j) w[j] = sigmoidf_(v[j] * rs) * 255.0f + 0.5f;
;                 u32x2 cd; cd.x = (unsigned)w[0] | ((unsigned)w[1] << 8) | ((unsigned)w[2] << 16) | ((unsigned)w[3] << 24); cd.y = (unsigned)w[4] | ((unsigned)w[5] << 8) | ((unsigned)w[6] << 16) | ((unsigned)w[7] << 24);
;                 *(u32x2*)(ws + WS_G8 + (size_t)row * 2048 + col) = cd;
	v_pk_mul_f32 v[80:81], v[80:81], v[176:177] op_sel_hi:[1,0]
	v_pk_mul_f32 v[82:83], v[82:83], v[176:177] op_sel_hi:[1,0]
	v_pk_mul_f32 v[84:85], v[84:85], v[176:177] op_sel_hi:[1,0]
	v_pk_mul_f32 v[86:87], v[86:87], v[176:177] op_sel_hi:[1,0]
	global_store_dwordx2 v[200:201], v[192:193], off
	v_exp_f32_e32 v80, v80
	v_exp_f32_e32 v81, v81
	v_exp_f32_e32 v82, v82
	v_exp_f32_e32 v83, v83
	v_exp_f32_e32 v84, v84
	v_exp_f32_e32 v85, v85
	v_exp_f32_e32 v86, v86
	v_exp_f32_e32 v87, v87
	v_pk_add_f32 v[80:81], v[80:81], 1.0 op_sel_hi:[1,0]
	v_pk_add_f32 v[82:83], v[82:83], 1.0 op_sel_hi:[1,0]
	v_pk_add_f32 v[84:85], v[84:85], 1.0 op_sel_hi:[1,0]
	v_pk_add_f32 v[86:87], v[86:87], 1.0 op_sel_hi:[1,0]
	v_rcp_f32_e32 v80, v80
	v_rcp_f32_e32 v81, v81
	v_rcp_f32_e32 v82, v82
	v_rcp_f32_e32 v83, v83
	v_rcp_f32_e32 v84, v84
	v_rcp_f32_e32 v85, v85
	v_rcp_f32_e32 v86, v86
	v_rcp_f32_e32 v87, v87
	v_pk_fma_f32 v[80:81], v[80:81], s[20:21], 0.5 op_sel_hi:[1,0,0]
	v_pk_fma_f32 v[82:83], v[82:83], s[20:21], 0.5 op_sel_hi:[1,0,0]
	v_pk_fma_f32 v[84:85], v[84:85], s[20:21], 0.5 op_sel_hi:[1,0,0]
	v_pk_fma_f32 v[86:87], v[86:87], s[20:21], 0.5 op_sel_hi:[1,0,0]
	v_cvt_u32_f32_e32 v194, v84
	v_cvt_u32_f32_e32 v195, v80
	v_cvt_u32_f32_sdwa v194, v85 dst_sel:BYTE_1 dst_unused:UNUSED_PRESERVE src0_sel:DWORD
	v_cvt_u32_f32_sdwa v195, v81 dst_sel:BYTE_1 dst_unused:UNUSED_PRESERVE src0_sel:DWORD
	v_cvt_u32_f32_sdwa v194, v86 dst_sel:BYTE_2 dst_unused:UNUSED_PRESERVE src0_sel:DWORD
	v_cvt_u32_f32_sdwa v195, v82 dst_sel:BYTE_2 dst_unused:UNUSED_PRESERVE src0_sel:DWORD
	v_cvt_u32_f32_sdwa v194, v87 dst_sel:BYTE_3 dst_unused:UNUSED_PRESERVE src0_sel:DWORD
	v_cvt_u32_f32_sdwa v195, v83 dst_sel:BYTE_3 dst_unused:UNUSED_PRESERVE src0_sel:DWORD
	s_waitcnt vmcnt(9)
	v_mul_f32_e32 v178, 0xbfb8aa3b, v166
	s_mov_b32 s88, 0x18000
	v_lshl_add_u64 v[202:203], v[170:171], 0, s[88:89]
	v_pk_mul_f32 v[72:73], v[72:73], v[178:179] op_sel_hi:[1,0]
	v_pk_mul_f32 v[74:75], v[74:75], v[178:179] op_sel_hi:[1,0]
	v_pk_mul_f32 v[76:77], v[76:77], v[178:179] op_sel_hi:[1,0]
	v_pk_mul_f32 v[78:79], v[78:79], v[178:179] op_sel_hi:[1,0]
	global_store_dwordx2 v[200:201], v[194:195], off offset:128
	v_exp_f32_e32 v72, v72
	v_exp_f32_e32 v73, v73
	v_exp_f32_e32 v74, v74
	v_exp_f32_e32 v75, v75
	v_exp_f32_e32 v76, v76
	v_exp_f32_e32 v77, v77
	v_exp_f32_e32 v78, v78
	v_exp_f32_e32 v79, v79
	v_pk_add_f32 v[72:73], v[72:73], 1.0 op_sel_hi:[1,0]
	v_pk_add_f32 v[74:75], v[74:75], 1.0 op_sel_hi:[1,0]
	v_pk_add_f32 v[76:77], v[76:77], 1.0 op_sel_hi:[1,0]
	v_pk_add_f32 v[78:79], v[78:79], 1.0 op_sel_hi:[1,0]
	v_rcp_f32_e32 v72, v72
	v_rcp_f32_e32 v73, v73
	v_rcp_f32_e32 v74, v74
	v_rcp_f32_e32 v75, v75
	v_rcp_f32_e32 v76, v76
	v_rcp_f32_e32 v77, v77
	v_rcp_f32_e32 v78, v78
	v_rcp_f32_e32 v79, v79
	v_pk_fma_f32 v[72:73], v[72:73], s[20:21], 0.5 op_sel_hi:[1,0,0]
	v_pk_fma_f32 v[74:75], v[74:75], s[20:21], 0.5 op_sel_hi:[1,0,0]
	v_pk_fma_f32 v[76:77], v[76:77], s[20:21], 0.5 op_sel_hi:[1,0,0]
	v_pk_fma_f32 v[78:79], v[78:79], s[20:21], 0.5 op_sel_hi:[1,0,0]
	v_cvt_u32_f32_e32 v196, v76
	v_cvt_u32_f32_e32 v197, v72
	v_cvt_u32_f32_sdwa v196, v77 dst_sel:BYTE_1 dst_unused:UNUSED_PRESERVE src0_sel:DWORD
	v_cvt_u32_f32_sdwa v197, v73 dst_sel:BYTE_1 dst_unused:UNUSED_PRESERVE src0_sel:DWORD
	v_cvt_u32_f32_sdwa v196, v78 dst_sel:BYTE_2 dst_unused:UNUSED_PRESERVE src0_sel:DWORD
	v_cvt_u32_f32_sdwa v197, v74 dst_sel:BYTE_2 dst_unused:UNUSED_PRESERVE src0_sel:DWORD
	v_cvt_u32_f32_sdwa v196, v79 dst_sel:BYTE_3 dst_unused:UNUSED_PRESERVE src0_sel:DWORD
	v_cvt_u32_f32_sdwa v197, v75 dst_sel:BYTE_3 dst_unused:UNUSED_PRESERVE src0_sel:DWORD
	v_pk_mul_f32 v[64:65], v[64:65], v[178:179] op_sel_hi:[1,0]
	v_pk_mul_f32 v[66:67], v[66:67], v[178:179] op_sel_hi:[1,0]
	v_pk_mul_f32 v[68:69], v[68:69], v[178:179] op_sel_hi:[1,0]
	v_pk_mul_f32 v[70:71], v[70:71], v[178:179] op_sel_hi:[1,0]
	global_store_dwordx2 v[202:203], v[196:197], off
	v_exp_f32_e32 v64, v64
	v_exp_f32_e32 v65, v65
	v_exp_f32_e32 v66, v66
	v_exp_f32_e32 v67, v67
	v_exp_f32_e32 v68, v68
	v_exp_f32_e32 v69, v69
	v_exp_f32_e32 v70, v70
	v_exp_f32_e32 v71, v71
	v_pk_add_f32 v[64:65], v[64:65], 1.0 op_sel_hi:[1,0]
	v_pk_add_f32 v[66:67], v[66:67], 1.0 op_sel_hi:[1,0]
	v_pk_add_f32 v[68:69], v[68:69], 1.0 op_sel_hi:[1,0]
	v_pk_add_f32 v[70:71], v[70:71], 1.0 op_sel_hi:[1,0]
	v_rcp_f32_e32 v64, v64
	v_rcp_f32_e32 v65, v65
	v_rcp_f32_e32 v66, v66
	v_rcp_f32_e32 v67, v67
	v_rcp_f32_e32 v68, v68
	v_rcp_f32_e32 v69, v69
	v_rcp_f32_e32 v70, v70
	v_rcp_f32_e32 v71, v71
	v_pk_fma_f32 v[64:65], v[64:65], s[20:21], 0.5 op_sel_hi:[1,0,0]
	v_pk_fma_f32 v[66:67], v[66:67], s[20:21], 0.5 op_sel_hi:[1,0,0]
	v_pk_fma_f32 v[68:69], v[68:69], s[20:21], 0.5 op_sel_hi:[1,0,0]
	v_pk_fma_f32 v[70:71], v[70:71], s[20:21], 0.5 op_sel_hi:[1,0,0]
	v_cvt_u32_f32_e32 v198, v68
	v_cvt_u32_f32_e32 v199, v64
	v_cvt_u32_f32_sdwa v198, v69 dst_sel:BYTE_1 dst_unused:UNUSED_PRESERVE src0_sel:DWORD
	v_cvt_u32_f32_sdwa v199, v65 dst_sel:BYTE_1 dst_unused:UNUSED_PRESERVE src0_sel:DWORD
	v_cvt_u32_f32_sdwa v198, v70 dst_sel:BYTE_2 dst_unused:UNUSED_PRESERVE src0_sel:DWORD
	v_cvt_u32_f32_sdwa v199, v66 dst_sel:BYTE_2 dst_unused:UNUSED_PRESERVE src0_sel:DWORD
	v_cvt_u32_f32_sdwa v198, v71 dst_sel:BYTE_3 dst_unused:UNUSED_PRESERVE src0_sel:DWORD
	v_cvt_u32_f32_sdwa v199, v67 dst_sel:BYTE_3 dst_unused:UNUSED_PRESERVE src0_sel:DWORD
	s_waitcnt vmcnt(10)
; __device__ __forceinline__ float sigmoidf_(float z) { return __builtin_amdgcn_rcpf(1.0f + __builtin_amdgcn_exp2f(-1.4426950408889634f * z)); }
;     __device__ __forceinline__ float compute(const Pre& p, f32x4 (&acc)[2][2][4][2], const f32x4 (&cv)[2][2], const pg8::Unit& u, int ai, int m, int wr, int wc, int fr, int fq) const {
;     ...
;             } else if (MODE == EM_GATES) {
;                 const int col = u.pn * 256 + ct; float w[8];
; #pragma unroll
;                 for (int j = 0; j < 8; ++j) w[j] = sigmoidf_(v[j] * rs) * 255.0f + 0.5f;
;                 u32x2 cd; cd.x = (unsigned)w[0] | ((unsigned)w[1] << 8) | ((unsigned)w[2] << 16) | ((unsigned)w[3] << 24); cd.y = (unsigned)w[4] | ((unsigned)w[5] << 8) | ((unsigned)w[6] << 16) | ((unsigned)w[7] << 24);
;                 *(u32x2*)(ws + WS_G8 + (size_t)row * 2048 + col) = cd;
	v_mul_f32_e32 v184, 0xbfb8aa3b, v165
	s_mov_b32 s88, 0x40000
	v_lshl_add_u64 v[200:201], v[170:171], 0, s[88:89]
	v_pk_mul_f32 v[56:57], v[56:57], v[184:185] op_sel_hi:[1,0]
	v_pk_mul_f32 v[58:59], v[58:59], v[184:185] op_sel_hi:[1,0]
	v_pk_mul_f32 v[60:61], v[60:61], v[184:185] op_sel_hi:[1,0]
	v_pk_mul_f32 v[62:63], v[62:63], v[184:185] op_sel_hi:[1,0]
	global_store_dwordx2 v[202:203], v[198:199], off offset:128
	v_exp_f32_e32 v56, v56
	v_exp_f32_e32 v57, v57
	v_exp_f32_e32 v58, v58
	v_exp_f32_e32 v59, v59
	v_exp_f32_e32 v60, v60
	v_exp_f32_e32 v61, v61
	v_exp_f32_e32 v62, v62
	v_exp_f32_e32 v63, v63
	v_pk_add_f32 v[56:57], v[56:57], 1.0 op_sel_hi:[1,0]
	v_pk_add_f32 v[58:59], v[58:59], 1.0 op_sel_hi:[1,0]
	v_pk_add_f32 v[60:61], v[60:61], 1.0 op_sel_hi:[1,0]
	v_pk_add_f32 v[62:63], v[62:63], 1.0 op_sel_hi:[1,0]
	v_rcp_f32_e32 v56, v56
	v_rcp_f32_e32 v57, v57
	v_rcp_f32_e32 v58, v58
	v_rcp_f32_e32 v59, v59
	v_rcp_f32_e32 v60, v60
	v_rcp_f32_e32 v61, v61
	v_rcp_f32_e32 v62, v62
	v_rcp_f32_e32 v63, v63
	v_pk_fma_f32 v[56:57], v[56:57], s[20:21], 0.5 op_sel_hi:[1,0,0]
	v_pk_fma_f32 v[58:59], v[58:59], s[20:21], 0.5 op_sel_hi:[1,0,0]
	v_pk_fma_f32 v[60:61], v[60:61], s[20:21], 0.5 op_sel_hi:[1,0,0]
	v_pk_fma_f32 v[62:63], v[62:63], s[20:21], 0.5 op_sel_hi:[1,0,0]
	v_cvt_u32_f32_e32 v192, v60
	v_cvt_u32_f32_e32 v193, v56
	v_cvt_u32_f32_sdwa v192, v61 dst_sel:BYTE_1 dst_unused:UNUSED_PRESERVE src0_sel:DWORD
	v_cvt_u32_f32_sdwa v193, v57 dst_sel:BYTE_1 dst_unused:UNUSED_PRESERVE src0_sel:DWORD
	v_cvt_u32_f32_sdwa v192, v62 dst_sel:BYTE_2 dst_unused:UNUSED_PRESERVE src0_sel:DWORD
	v_cvt_u32_f32_sdwa v193, v58 dst_sel:BYTE_2 dst_unused:UNUSED_PRESERVE src0_sel:DWORD
	v_cvt_u32_f32_sdwa v192, v63 dst_sel:BYTE_3 dst_unused:UNUSED_PRESERVE src0_sel:DWORD
	v_cvt_u32_f32_sdwa v193, v59 dst_sel:BYTE_3 dst_unused:UNUSED_PRESERVE src0_sel:DWORD
	v_pk_mul_f32 v[48:49], v[48:49], v[184:185] op_sel_hi:[1,0]
	v_pk_mul_f32 v[50:51], v[50:51], v[184:185] op_sel_hi:[1,0]
	v_pk_mul_f32 v[52:53], v[52:53], v[184:185] op_sel_hi:[1,0]
	v_pk_mul_f32 v[54:55], v[54:55], v[184:185] op_sel_hi:[1,0]
	global_store_dwordx2 v[200:201], v[192:193], off
	v_exp_f32_e32 v48, v48
	v_exp_f32_e32 v49, v49
	v_exp_f32_e32 v50, v50
	v_exp_f32_e32 v51, v51
	v_exp_f32_e32 v52, v52
	v_exp_f32_e32 v53, v53
	v_exp_f32_e32 v54, v54
	v_exp_f32_e32 v55, v55
	v_pk_add_f32 v[48:49], v[48:49], 1.0 op_sel_hi:[1,0]
	v_pk_add_f32 v[50:51], v[50:51], 1.0 op_sel_hi:[1,0]
	v_pk_add_f32 v[52:53], v[52:53], 1.0 op_sel_hi:[1,0]
	v_pk_add_f32 v[54:55], v[54:55], 1.0 op_sel_hi:[1,0]
	v_rcp_f32_e32 v48, v48
	v_rcp_f32_e32 v49, v49
	v_rcp_f32_e32 v50, v50
	v_rcp_f32_e32 v51, v51
	v_rcp_f32_e32 v52, v52
	v_rcp_f32_e32 v53, v53
	v_rcp_f32_e32 v54, v54
	v_rcp_f32_e32 v55, v55
	v_pk_fma_f32 v[48:49], v[48:49], s[20:21], 0.5 op_sel_hi:[1,0,0]
	v_pk_fma_f32 v[50:51], v[50:51], s[20:21], 0.5 op_sel_hi:[1,0,0]
	v_pk_fma_f32 v[52:53], v[52:53], s[20:21], 0.5 op_sel_hi:[1,0,0]
	v_pk_fma_f32 v[54:55], v[54:55], s[20:21], 0.5 op_sel_hi:[1,0,0]
	v_cvt_u32_f32_e32 v194, v52
	v_cvt_u32_f32_e32 v195, v48
	v_cvt_u32_f32_sdwa v194, v53 dst_sel:BYTE_1 dst_unused:UNUSED_PRESERVE src0_sel:DWORD
	v_cvt_u32_f32_sdwa v195, v49 dst_sel:BYTE_1 dst_unused:UNUSED_PRESERVE src0_sel:DWORD
	v_cvt_u32_f32_sdwa v194, v54 dst_sel:BYTE_2 dst_unused:UNUSED_PRESERVE src0_sel:DWORD
	v_cvt_u32_f32_sdwa v195, v50 dst_sel:BYTE_2 dst_unused:UNUSED_PRESERVE src0_sel:DWORD
	v_cvt_u32_f32_sdwa v194, v55 dst_sel:BYTE_3 dst_unused:UNUSED_PRESERVE src0_sel:DWORD
	v_cvt_u32_f32_sdwa v195, v51 dst_sel:BYTE_3 dst_unused:UNUSED_PRESERVE src0_sel:DWORD
	s_waitcnt vmcnt(11)
	v_mul_f32_e32 v186, 0xbfb8aa3b, v164
	s_mov_b32 s88, 0x48000
	v_lshl_add_u64 v[202:203], v[170:171], 0, s[88:89]
	v_pk_mul_f32 v[40:41], v[40:41], v[186:187] op_sel_hi:[1,0]
	v_pk_mul_f32 v[42:43], v[42:43], v[186:187] op_sel_hi:[1,0]
	v_pk_mul_f32 v[44:45], v[44:45], v[186:187] op_sel_hi:[1,0]
	v_pk_mul_f32 v[46:47], v[46:47], v[186:187] op_sel_hi:[1,0]
	global_store_dwordx2 v[200:201], v[194:195], off offset:128
	v_exp_f32_e32 v40, v40
	v_exp_f32_e32 v41, v41
	v_exp_f32_e32 v42, v42
	v_exp_f32_e32 v43, v43
	v_exp_f32_e32 v44, v44
	v_exp_f32_e32 v45, v45
	v_exp_f32_e32 v46, v46
	v_exp_f32_e32 v47, v47
	v_pk_add_f32 v[40:41], v[40:41], 1.0 op_sel_hi:[1,0]
	v_pk_add_f32 v[42:43], v[42:43], 1.0 op_sel_hi:[1,0]
	v_pk_add_f32 v[44:45], v[44:45], 1.0 op_sel_hi:[1,0]
	v_pk_add_f32 v[46:47], v[46:47], 1.0 op_sel_hi:[1,0]
	v_rcp_f32_e32 v40, v40
	v_rcp_f32_e32 v41, v41
	v_rcp_f32_e32 v42, v42
	v_rcp_f32_e32 v43, v43
	v_rcp_f32_e32 v44, v44
	v_rcp_f32_e32 v45, v45
	v_rcp_f32_e32 v46, v46
	v_rcp_f32_e32 v47, v47
	v_pk_fma_f32 v[40:41], v[40:41], s[20:21], 0.5 op_sel_hi:[1,0,0]
	v_pk_fma_f32 v[42:43], v[42:43], s[20:21], 0.5 op_sel_hi:[1,0,0]
	v_pk_fma_f32 v[44:45], v[44:45], s[20:21], 0.5 op_sel_hi:[1,0,0]
	v_pk_fma_f32 v[46:47], v[46:47], s[20:21], 0.5 op_sel_hi:[1,0,0]
	v_cvt_u32_f32_e32 v196, v44
	v_cvt_u32_f32_e32 v197, v40
	v_cvt_u32_f32_sdwa v196, v45 dst_sel:BYTE_1 dst_unused:UNUSED_PRESERVE src0_sel:DWORD
	v_cvt_u32_f32_sdwa v197, v41 dst_sel:BYTE_1 dst_unused:UNUSED_PRESERVE src0_sel:DWORD
	v_cvt_u32_f32_sdwa v196, v46 dst_sel:BYTE_2 dst_unused:UNUSED_PRESERVE src0_sel:DWORD
	v_cvt_u32_f32_sdwa v197, v42 dst_sel:BYTE_2 dst_unused:UNUSED_PRESERVE src0_sel:DWORD
	v_cvt_u32_f32_sdwa v196, v47 dst_sel:BYTE_3 dst_unused:UNUSED_PRESERVE src0_sel:DWORD
	v_cvt_u32_f32_sdwa v197, v43 dst_sel:BYTE_3 dst_unused:UNUSED_PRESERVE src0_sel:DWORD
	v_pk_mul_f32 v[32:33], v[32:33], v[186:187] op_sel_hi:[1,0]
	v_pk_mul_f32 v[34:35], v[34:35], v[186:187] op_sel_hi:[1,0]
	v_pk_mul_f32 v[36:37], v[36:37], v[186:187] op_sel_hi:[1,0]
; __device__ __forceinline__ float sigmoidf_(float z) { return __builtin_amdgcn_rcpf(1.0f + __builtin_amdgcn_exp2f(-1.4426950408889634f * z)); }
;     __device__ __forceinline__ float compute(const Pre& p, f32x4 (&acc)[2][2][4][2], const f32x4 (&cv)[2][2], const pg8::Unit& u, int ai, int m, int wr, int wc, int fr, int fq) const {
;     ...
;             } else if (MODE == EM_GATES) {
;                 const int col = u.pn * 256 + ct; float w[8];
; #pragma unroll
;                 for (int j = 0; j < 8; ++j) w[j] = sigmoidf_(v[j] * rs) * 255.0f + 0.5f;
;                 u32x2 cd; cd.x = (unsigned)w[0] | ((unsigned)w[1] << 8) | ((unsigned)w[2] << 16) | ((unsigned)w[3] << 24); cd.y = (unsigned)w[4] | ((unsigned)w[5] << 8) | ((unsigned)w[6] << 16) | ((unsigned)w[7] << 24);
;                 *(u32x2*)(ws + WS_G8 + (size_t)row * 2048 + col) = cd;
	v_pk_mul_f32 v[38:39], v[38:39], v[186:187] op_sel_hi:[1,0]
	global_store_dwordx2 v[202:203], v[196:197], off
	v_exp_f32_e32 v32, v32
	v_exp_f32_e32 v33, v33
	v_exp_f32_e32 v34, v34
	v_exp_f32_e32 v35, v35
	v_exp_f32_e32 v36, v36
	v_exp_f32_e32 v37, v37
	v_exp_f32_e32 v38, v38
	v_exp_f32_e32 v39, v39
	v_pk_add_f32 v[32:33], v[32:33], 1.0 op_sel_hi:[1,0]
	v_pk_add_f32 v[34:35], v[34:35], 1.0 op_sel_hi:[1,0]
	v_pk_add_f32 v[36:37], v[36:37], 1.0 op_sel_hi:[1,0]
	v_pk_add_f32 v[38:39], v[38:39], 1.0 op_sel_hi:[1,0]
	v_rcp_f32_e32 v32, v32
	v_rcp_f32_e32 v33, v33
	v_rcp_f32_e32 v34, v34
	v_rcp_f32_e32 v35, v35
	v_rcp_f32_e32 v36, v36
	v_rcp_f32_e32 v37, v37
	v_rcp_f32_e32 v38, v38
	v_rcp_f32_e32 v39, v39
	v_pk_fma_f32 v[32:33], v[32:33], s[20:21], 0.5 op_sel_hi:[1,0,0]
	v_pk_fma_f32 v[34:35], v[34:35], s[20:21], 0.5 op_sel_hi:[1,0,0]
	v_pk_fma_f32 v[36:37], v[36:37], s[20:21], 0.5 op_sel_hi:[1,0,0]
	v_pk_fma_f32 v[38:39], v[38:39], s[20:21], 0.5 op_sel_hi:[1,0,0]
	v_cvt_u32_f32_e32 v198, v36
	v_cvt_u32_f32_e32 v199, v32
	v_cvt_u32_f32_sdwa v198, v37 dst_sel:BYTE_1 dst_unused:UNUSED_PRESERVE src0_sel:DWORD
	v_cvt_u32_f32_sdwa v199, v33 dst_sel:BYTE_1 dst_unused:UNUSED_PRESERVE src0_sel:DWORD
	v_cvt_u32_f32_sdwa v198, v38 dst_sel:BYTE_2 dst_unused:UNUSED_PRESERVE src0_sel:DWORD
	v_cvt_u32_f32_sdwa v199, v34 dst_sel:BYTE_2 dst_unused:UNUSED_PRESERVE src0_sel:DWORD
	v_cvt_u32_f32_sdwa v198, v39 dst_sel:BYTE_3 dst_unused:UNUSED_PRESERVE src0_sel:DWORD
	v_cvt_u32_f32_sdwa v199, v35 dst_sel:BYTE_3 dst_unused:UNUSED_PRESERVE src0_sel:DWORD
	s_waitcnt vmcnt(12)
	v_mul_f32_e32 v188, 0xbfb8aa3b, v163
	s_mov_b32 s88, 0x50000
	v_lshl_add_u64 v[200:201], v[170:171], 0, s[88:89]
	v_pk_mul_f32 v[24:25], v[24:25], v[188:189] op_sel_hi:[1,0]
	v_pk_mul_f32 v[26:27], v[26:27], v[188:189] op_sel_hi:[1,0]
	v_pk_mul_f32 v[28:29], v[28:29], v[188:189] op_sel_hi:[1,0]
	v_pk_mul_f32 v[30:31], v[30:31], v[188:189] op_sel_hi:[1,0]
	global_store_dwordx2 v[202:203], v[198:199], off offset:128
	v_exp_f32_e32 v24, v24
	v_exp_f32_e32 v25, v25
	v_exp_f32_e32 v26, v26
	v_exp_f32_e32 v27, v27
	v_exp_f32_e32 v28, v28
	v_exp_f32_e32 v29, v29
	v_exp_f32_e32 v30, v30
	v_exp_f32_e32 v31, v31
	v_pk_add_f32 v[24:25], v[24:25], 1.0 op_sel_hi:[1,0]
	v_pk_add_f32 v[26:27], v[26:27], 1.0 op_sel_hi:[1,0]
	v_pk_add_f32 v[28:29], v[28:29], 1.0 op_sel_hi:[1,0]
	v_pk_add_f32 v[30:31], v[30:31], 1.0 op_sel_hi:[1,0]
	v_rcp_f32_e32 v24, v24
	v_rcp_f32_e32 v25, v25
	v_rcp_f32_e32 v26, v26
	v_rcp_f32_e32 v27, v27
	v_rcp_f32_e32 v28, v28
	v_rcp_f32_e32 v29, v29
	v_rcp_f32_e32 v30, v30
	v_rcp_f32_e32 v31, v31
	v_pk_fma_f32 v[24:25], v[24:25], s[20:21], 0.5 op_sel_hi:[1,0,0]
	v_pk_fma_f32 v[26:27], v[26:27], s[20:21], 0.5 op_sel_hi:[1,0,0]
	v_pk_fma_f32 v[28:29], v[28:29], s[20:21], 0.5 op_sel_hi:[1,0,0]
	v_pk_fma_f32 v[30:31], v[30:31], s[20:21], 0.5 op_sel_hi:[1,0,0]
	v_cvt_u32_f32_e32 v192, v28
	v_cvt_u32_f32_e32 v193, v24
	v_cvt_u32_f32_sdwa v192, v29 dst_sel:BYTE_1 dst_unused:UNUSED_PRESERVE src0_sel:DWORD
	v_cvt_u32_f32_sdwa v193, v25 dst_sel:BYTE_1 dst_unused:UNUSED_PRESERVE src0_sel:DWORD
	v_cvt_u32_f32_sdwa v192, v30 dst_sel:BYTE_2 dst_unused:UNUSED_PRESERVE src0_sel:DWORD
	v_cvt_u32_f32_sdwa v193, v26 dst_sel:BYTE_2 dst_unused:UNUSED_PRESERVE src0_sel:DWORD
	v_cvt_u32_f32_sdwa v192, v31 dst_sel:BYTE_3 dst_unused:UNUSED_PRESERVE src0_sel:DWORD
	v_cvt_u32_f32_sdwa v193, v27 dst_sel:BYTE_3 dst_unused:UNUSED_PRESERVE src0_sel:DWORD
	v_pk_mul_f32 v[16:17], v[16:17], v[188:189] op_sel_hi:[1,0]
	v_pk_mul_f32 v[18:19], v[18:19], v[188:189] op_sel_hi:[1,0]
	v_pk_mul_f32 v[20:21], v[20:21], v[188:189] op_sel_hi:[1,0]
	v_pk_mul_f32 v[22:23], v[22:23], v[188:189] op_sel_hi:[1,0]
	global_store_dwordx2 v[200:201], v[192:193], off
	v_exp_f32_e32 v16, v16
	v_exp_f32_e32 v17, v17
	v_exp_f32_e32 v18, v18
	v_exp_f32_e32 v19, v19
	v_exp_f32_e32 v20, v20
	v_exp_f32_e32 v21, v21
	v_exp_f32_e32 v22, v22
	v_exp_f32_e32 v23, v23
	v_pk_add_f32 v[16:17], v[16:17], 1.0 op_sel_hi:[1,0]
	v_pk_add_f32 v[18:19], v[18:19], 1.0 op_sel_hi:[1,0]
	v_pk_add_f32 v[20:21], v[20:21], 1.0 op_sel_hi:[1,0]
	v_pk_add_f32 v[22:23], v[22:23], 1.0 op_sel_hi:[1,0]
	v_rcp_f32_e32 v16, v16
	v_rcp_f32_e32 v17, v17
	v_rcp_f32_e32 v18, v18
	v_rcp_f32_e32 v19, v19
	v_rcp_f32_e32 v20, v20
	v_rcp_f32_e32 v21, v21
	v_rcp_f32_e32 v22, v22
	v_rcp_f32_e32 v23, v23
	v_pk_fma_f32 v[16:17], v[16:17], s[20:21], 0.5 op_sel_hi:[1,0,0]
	v_pk_fma_f32 v[18:19], v[18:19], s[20:21], 0.5 op_sel_hi:[1,0,0]
	v_pk_fma_f32 v[20:21], v[20:21], s[20:21], 0.5 op_sel_hi:[1,0,0]
	v_pk_fma_f32 v[22:23], v[22:23], s[20:21], 0.5 op_sel_hi:[1,0,0]
	v_cvt_u32_f32_e32 v194, v20
	v_cvt_u32_f32_e32 v195, v16
	v_cvt_u32_f32_sdwa v194, v21 dst_sel:BYTE_1 dst_unused:UNUSED_PRESERVE src0_sel:DWORD
	v_cvt_u32_f32_sdwa v195, v17 dst_sel:BYTE_1 dst_unused:UNUSED_PRESERVE src0_sel:DWORD
	v_cvt_u32_f32_sdwa v194, v22 dst_sel:BYTE_2 dst_unused:UNUSED_PRESERVE src0_sel:DWORD
	v_cvt_u32_f32_sdwa v195, v18 dst_sel:BYTE_2 dst_unused:UNUSED_PRESERVE src0_sel:DWORD
	v_cvt_u32_f32_sdwa v194, v23 dst_sel:BYTE_3 dst_unused:UNUSED_PRESERVE src0_sel:DWORD
	v_cvt_u32_f32_sdwa v195, v19 dst_sel:BYTE_3 dst_unused:UNUSED_PRESERVE src0_sel:DWORD
	s_waitcnt vmcnt(13)
; __device__ __forceinline__ float sigmoidf_(float z) { return __builtin_amdgcn_rcpf(1.0f + __builtin_amdgcn_exp2f(-1.4426950408889634f * z)); }
;     __device__ __forceinline__ float compute(const Pre& p, f32x4 (&acc)[2][2][4][2], const f32x4 (&cv)[2][2], const pg8::Unit& u, int ai, int m, int wr, int wc, int fr, int fq) const {
;     ...
;             } else if (MODE == EM_GATES) {
;                 const int col = u.pn * 256 + ct; float w[8];
; #pragma unroll
;                 for (int j = 0; j < 8; ++j) w[j] = sigmoidf_(v[j] * rs) * 255.0f + 0.5f;
;                 u32x2 cd; cd.x = (unsigned)w[0] | ((unsigned)w[1] << 8) | ((unsigned)w[2] << 16) | ((unsigned)w[3] << 24); cd.y = (unsigned)w[4] | ((unsigned)w[5] << 8) | ((unsigned)w[6] << 16) | ((unsigned)w[7] << 24);
;                 *(u32x2*)(ws + WS_G8 + (size_t)row * 2048 + col) = cd;
	v_mul_f32_e32 v190, 0xbfb8aa3b, v162
	s_mov_b32 s88, 0x58000
	v_lshl_add_u64 v[202:203], v[170:171], 0, s[88:89]
	v_pk_mul_f32 v[8:9], v[8:9], v[190:191] op_sel_hi:[1,0]
	v_pk_mul_f32 v[10:11], v[10:11], v[190:191] op_sel_hi:[1,0]
	v_pk_mul_f32 v[12:13], v[12:13], v[190:191] op_sel_hi:[1,0]
	v_pk_mul_f32 v[14:15], v[14:15], v[190:191] op_sel_hi:[1,0]
	global_store_dwordx2 v[200:201], v[194:195], off offset:128
	v_exp_f32_e32 v8, v8
	v_exp_f32_e32 v9, v9
	v_exp_f32_e32 v10, v10
	v_exp_f32_e32 v11, v11
	v_exp_f32_e32 v12, v12
	v_exp_f32_e32 v13, v13
	v_exp_f32_e32 v14, v14
	v_exp_f32_e32 v15, v15
	v_pk_add_f32 v[8:9], v[8:9], 1.0 op_sel_hi:[1,0]
	v_pk_add_f32 v[10:11], v[10:11], 1.0 op_sel_hi:[1,0]
	v_pk_add_f32 v[12:13], v[12:13], 1.0 op_sel_hi:[1,0]
	v_pk_add_f32 v[14:15], v[14:15], 1.0 op_sel_hi:[1,0]
	v_rcp_f32_e32 v8, v8
	v_rcp_f32_e32 v9, v9
	v_rcp_f32_e32 v10, v10
	v_rcp_f32_e32 v11, v11
	v_rcp_f32_e32 v12, v12
	v_rcp_f32_e32 v13, v13
	v_rcp_f32_e32 v14, v14
	v_rcp_f32_e32 v15, v15
	v_pk_fma_f32 v[8:9], v[8:9], s[20:21], 0.5 op_sel_hi:[1,0,0]
	v_pk_fma_f32 v[10:11], v[10:11], s[20:21], 0.5 op_sel_hi:[1,0,0]
	v_pk_fma_f32 v[12:13], v[12:13], s[20:21], 0.5 op_sel_hi:[1,0,0]
	v_pk_fma_f32 v[14:15], v[14:15], s[20:21], 0.5 op_sel_hi:[1,0,0]
	v_cvt_u32_f32_e32 v196, v12
	v_cvt_u32_f32_e32 v197, v8
	v_cvt_u32_f32_sdwa v196, v13 dst_sel:BYTE_1 dst_unused:UNUSED_PRESERVE src0_sel:DWORD
	v_cvt_u32_f32_sdwa v197, v9 dst_sel:BYTE_1 dst_unused:UNUSED_PRESERVE src0_sel:DWORD
	v_cvt_u32_f32_sdwa v196, v14 dst_sel:BYTE_2 dst_unused:UNUSED_PRESERVE src0_sel:DWORD
	v_cvt_u32_f32_sdwa v197, v10 dst_sel:BYTE_2 dst_unused:UNUSED_PRESERVE src0_sel:DWORD
	v_cvt_u32_f32_sdwa v196, v15 dst_sel:BYTE_3 dst_unused:UNUSED_PRESERVE src0_sel:DWORD
	v_cvt_u32_f32_sdwa v197, v11 dst_sel:BYTE_3 dst_unused:UNUSED_PRESERVE src0_sel:DWORD
	v_pk_mul_f32 v[0:1], v[0:1], v[190:191] op_sel_hi:[1,0]
	v_pk_mul_f32 v[2:3], v[2:3], v[190:191] op_sel_hi:[1,0]
	v_pk_mul_f32 v[4:5], v[4:5], v[190:191] op_sel_hi:[1,0]
	v_pk_mul_f32 v[6:7], v[6:7], v[190:191] op_sel_hi:[1,0]
	global_store_dwordx2 v[202:203], v[196:197], off
	v_exp_f32_e32 v0, v0
	v_exp_f32_e32 v1, v1
	v_exp_f32_e32 v2, v2
	v_exp_f32_e32 v3, v3
	v_exp_f32_e32 v4, v4
	v_exp_f32_e32 v5, v5
	v_exp_f32_e32 v6, v6
	v_exp_f32_e32 v7, v7
	v_pk_add_f32 v[0:1], v[0:1], 1.0 op_sel_hi:[1,0]
	v_pk_add_f32 v[2:3], v[2:3], 1.0 op_sel_hi:[1,0]
	v_pk_add_f32 v[4:5], v[4:5], 1.0 op_sel_hi:[1,0]
	v_pk_add_f32 v[6:7], v[6:7], 1.0 op_sel_hi:[1,0]
	v_rcp_f32_e32 v0, v0
	v_rcp_f32_e32 v1, v1
	v_rcp_f32_e32 v2, v2
	v_rcp_f32_e32 v3, v3
	v_rcp_f32_e32 v4, v4
	v_rcp_f32_e32 v5, v5
	v_rcp_f32_e32 v6, v6
	v_rcp_f32_e32 v7, v7
	v_pk_fma_f32 v[0:1], v[0:1], s[20:21], 0.5 op_sel_hi:[1,0,0]
	v_pk_fma_f32 v[2:3], v[2:3], s[20:21], 0.5 op_sel_hi:[1,0,0]
	v_pk_fma_f32 v[4:5], v[4:5], s[20:21], 0.5 op_sel_hi:[1,0,0]
	v_pk_fma_f32 v[6:7], v[6:7], s[20:21], 0.5 op_sel_hi:[1,0,0]
	v_cvt_u32_f32_e32 v198, v4
	v_cvt_u32_f32_e32 v199, v0
	v_cvt_u32_f32_sdwa v198, v5 dst_sel:BYTE_1 dst_unused:UNUSED_PRESERVE src0_sel:DWORD
	v_cvt_u32_f32_sdwa v199, v1 dst_sel:BYTE_1 dst_unused:UNUSED_PRESERVE src0_sel:DWORD
	v_cvt_u32_f32_sdwa v198, v6 dst_sel:BYTE_2 dst_unused:UNUSED_PRESERVE src0_sel:DWORD
	v_cvt_u32_f32_sdwa v199, v2 dst_sel:BYTE_2 dst_unused:UNUSED_PRESERVE src0_sel:DWORD
	v_cvt_u32_f32_sdwa v198, v7 dst_sel:BYTE_3 dst_unused:UNUSED_PRESERVE src0_sel:DWORD
	v_cvt_u32_f32_sdwa v199, v3 dst_sel:BYTE_3 dst_unused:UNUSED_PRESERVE src0_sel:DWORD
	s_nop 0
	global_store_dwordx2 v[202:203], v[198:199], off offset:128
	s_and_b64 vcc, exec, s[4:5]
	s_mov_b64 s[4:5], -1
	s_cbranch_vccnz .LBB0_861
	s_andn2_b64 vcc, exec, s[6:7]
	s_cbranch_vccnz .LBB0_860
	s_barrier
	s_branch .LBB0_860
